# drop redundant accumulator zeroing per GEMM tile (+64-bit zero moves); remove self-max canonicalisations and keep the ones fragment resident in the attention softmax loops
# speedup vs baseline: 1.0099x; 1.0099x over previous
; #define PG8_BAR __builtin_amdgcn_s_barrier()
; template <class Epi>
; __device__ __forceinline__ void gemm_phase(LAS unsigned char* lds, const Gemm g, const Epi& E) {
;     ...
;         if (!has_next) break;
; #pragma unroll
;         for (int a = 0; a < 2; ++a)
; #pragma unroll
;             for (int b = 0; b < 2; ++b)
; #pragma unroll
;                 for (int m = 0; m < 4; ++m)
; #pragma unroll
;                     for (int n = 0; n < 2; ++n) acc[a][b][m][n] = (f32x4){0.f, 0.f, 0.f, 0.f};
;         cur = nxt; cA = nA; cB = nB; ++ui;
;         if (wr == 1) PG8_BAR;
.LBB0_157:
	s_andn2_b64 vcc, exec, s[22:23]
	s_cbranch_vccnz .LBB0_160
	s_add_u32 s16, s16, 0x80
	s_addc_u32 s17, s17, 0
	s_add_u32 s20, s44, 0x100
	s_addc_u32 s21, s45, 0
	s_mov_b32 s35, 0
	v_mov_b64_e32 v[2:3], 0
	v_mov_b64_e32 v[4:5], 0
	v_mov_b64_e32 v[6:7], 0
	v_mov_b64_e32 v[8:9], 0
	v_mov_b64_e32 v[10:11], 0
	v_mov_b64_e32 v[12:13], 0
	v_mov_b64_e32 v[14:15], 0
	v_mov_b64_e32 v[16:17], 0
	v_mov_b64_e32 v[18:19], 0
	v_mov_b64_e32 v[20:21], 0
	v_mov_b64_e32 v[22:23], 0
	v_mov_b64_e32 v[24:25], 0
	v_mov_b64_e32 v[26:27], 0
	v_mov_b64_e32 v[28:29], 0
	v_mov_b64_e32 v[30:31], 0
	v_mov_b64_e32 v[32:33], 0
	v_mov_b64_e32 v[34:35], 0
	v_mov_b64_e32 v[36:37], 0
	v_mov_b64_e32 v[38:39], 0
	v_mov_b64_e32 v[40:41], 0
	v_mov_b64_e32 v[42:43], 0
	v_mov_b64_e32 v[44:45], 0
	v_mov_b64_e32 v[46:47], 0
	v_mov_b64_e32 v[48:49], 0
	v_mov_b64_e32 v[50:51], 0
	v_mov_b64_e32 v[52:53], 0
	v_mov_b64_e32 v[54:55], 0
	v_mov_b64_e32 v[56:57], 0
	v_mov_b64_e32 v[58:59], 0
	v_mov_b64_e32 v[60:61], 0
	v_mov_b64_e32 v[62:63], 0
	v_mov_b64_e32 v[64:65], 0
	v_mov_b64_e32 v[66:67], 0
	v_mov_b64_e32 v[68:69], 0
	v_mov_b64_e32 v[70:71], 0
	v_mov_b64_e32 v[72:73], 0
	v_mov_b64_e32 v[74:75], 0
	v_mov_b64_e32 v[76:77], 0
	v_mov_b64_e32 v[78:79], 0
	v_mov_b64_e32 v[80:81], 0
	v_mov_b64_e32 v[82:83], 0
	v_mov_b64_e32 v[84:85], 0
	v_mov_b64_e32 v[86:87], 0
	v_mov_b64_e32 v[88:89], 0
	v_mov_b64_e32 v[90:91], 0
	v_mov_b64_e32 v[92:93], 0
	v_mov_b64_e32 v[94:95], 0
	v_mov_b64_e32 v[96:97], 0
	v_mov_b64_e32 v[98:99], 0
	v_mov_b64_e32 v[100:101], 0
	v_mov_b64_e32 v[102:103], 0
	v_mov_b64_e32 v[104:105], 0
	v_mov_b64_e32 v[106:107], 0
	v_mov_b64_e32 v[108:109], 0
	v_mov_b64_e32 v[110:111], 0
	v_mov_b64_e32 v[112:113], 0
	v_mov_b64_e32 v[114:115], 0
	v_mov_b64_e32 v[116:117], 0
	v_mov_b64_e32 v[118:119], 0
	v_mov_b64_e32 v[120:121], 0
	v_mov_b64_e32 v[122:123], 0
	v_mov_b64_e32 v[124:125], 0
	v_mov_b64_e32 v[126:127], 0
	v_mov_b64_e32 v[128:129], 0

; #define PG8_BAR __builtin_amdgcn_s_barrier()
; template <class Epi>
; __device__ __forceinline__ void gemm_phase(LAS unsigned char* lds, const Gemm g, const Epi& E) {
;     ...
;         if (!has_next) break;
; #pragma unroll
;         for (int a = 0; a < 2; ++a)
; #pragma unroll
;             for (int b = 0; b < 2; ++b)
; #pragma unroll
;                 for (int m = 0; m < 4; ++m)
; #pragma unroll
;                     for (int n = 0; n < 2; ++n) acc[a][b][m][n] = (f32x4){0.f, 0.f, 0.f, 0.f};
;         cur = nxt; cA = nA; cB = nB; ++ui;
;         if (wr == 1) PG8_BAR;
.LBB0_326:
	s_andn2_b64 vcc, exec, s[76:77]
	s_cbranch_vccnz .LBB0_329
	s_add_u32 s0, s0, 0x80
	s_addc_u32 s1, s1, 0
	s_add_u32 s6, s10, 0x100
	s_addc_u32 s7, s11, 0
	s_mov_b32 s8, 0
	v_mov_b64_e32 v[2:3], 0
	v_mov_b64_e32 v[4:5], 0
	v_mov_b64_e32 v[6:7], 0
	v_mov_b64_e32 v[8:9], 0
	v_mov_b64_e32 v[10:11], 0
	v_mov_b64_e32 v[12:13], 0
	v_mov_b64_e32 v[14:15], 0
	v_mov_b64_e32 v[16:17], 0
	v_mov_b64_e32 v[18:19], 0
	v_mov_b64_e32 v[20:21], 0
	v_mov_b64_e32 v[22:23], 0
	v_mov_b64_e32 v[24:25], 0
	v_mov_b64_e32 v[26:27], 0
	v_mov_b64_e32 v[28:29], 0
	v_mov_b64_e32 v[30:31], 0
	v_mov_b64_e32 v[32:33], 0
	v_mov_b64_e32 v[34:35], 0
	v_mov_b64_e32 v[36:37], 0
	v_mov_b64_e32 v[38:39], 0
	v_mov_b64_e32 v[40:41], 0
	v_mov_b64_e32 v[42:43], 0
	v_mov_b64_e32 v[44:45], 0
	v_mov_b64_e32 v[46:47], 0
	v_mov_b64_e32 v[48:49], 0
	v_mov_b64_e32 v[50:51], 0
	v_mov_b64_e32 v[52:53], 0
	v_mov_b64_e32 v[54:55], 0
	v_mov_b64_e32 v[56:57], 0
	v_mov_b64_e32 v[58:59], 0
	v_mov_b64_e32 v[60:61], 0
	v_mov_b64_e32 v[62:63], 0
	v_mov_b64_e32 v[64:65], 0
	v_mov_b64_e32 v[66:67], 0
	v_mov_b64_e32 v[68:69], 0
	v_mov_b64_e32 v[70:71], 0
	v_mov_b64_e32 v[72:73], 0
	v_mov_b64_e32 v[74:75], 0
	v_mov_b64_e32 v[76:77], 0
	v_mov_b64_e32 v[78:79], 0
	v_mov_b64_e32 v[80:81], 0
	v_mov_b64_e32 v[82:83], 0
	v_mov_b64_e32 v[84:85], 0
	v_mov_b64_e32 v[86:87], 0
	v_mov_b64_e32 v[88:89], 0
	v_mov_b64_e32 v[90:91], 0
	v_mov_b64_e32 v[92:93], 0
	v_mov_b64_e32 v[94:95], 0
	v_mov_b64_e32 v[96:97], 0
	v_mov_b64_e32 v[98:99], 0
	v_mov_b64_e32 v[100:101], 0
	v_mov_b64_e32 v[102:103], 0
	v_mov_b64_e32 v[104:105], 0
	v_mov_b64_e32 v[106:107], 0
	v_mov_b64_e32 v[108:109], 0
	v_mov_b64_e32 v[110:111], 0
	v_mov_b64_e32 v[112:113], 0
	v_mov_b64_e32 v[114:115], 0
	v_mov_b64_e32 v[116:117], 0
	v_mov_b64_e32 v[118:119], 0
	v_mov_b64_e32 v[120:121], 0
	v_mov_b64_e32 v[122:123], 0
	v_mov_b64_e32 v[124:125], 0
	v_mov_b64_e32 v[126:127], 0
	v_mov_b64_e32 v[128:129], 0

; #define PG8_BAR __builtin_amdgcn_s_barrier()
; template <class Epi>
; __device__ __forceinline__ void gemm_phase(LAS unsigned char* lds, const Gemm g, const Epi& E) {
;     ...
;         if (!has_next) break;
; #pragma unroll
;         for (int a = 0; a < 2; ++a)
; #pragma unroll
;             for (int b = 0; b < 2; ++b)
; #pragma unroll
;                 for (int m = 0; m < 4; ++m)
; #pragma unroll
;                     for (int n = 0; n < 2; ++n) acc[a][b][m][n] = (f32x4){0.f, 0.f, 0.f, 0.f};
;         cur = nxt; cA = nA; cB = nB; ++ui;
;         if (wr == 1) PG8_BAR;
.LBB0_383:
	s_andn2_b64 vcc, exec, s[38:39]
	s_cbranch_vccnz .LBB0_386
	s_add_u32 s48, s48, 0x80
	s_addc_u32 s49, s49, 0
	s_add_u32 s20, s50, 0x100
	s_addc_u32 s21, s51, 0
	s_mov_b32 s50, 0
	v_mov_b64_e32 v[2:3], 0
	v_mov_b64_e32 v[4:5], 0
	v_mov_b64_e32 v[6:7], 0
	v_mov_b64_e32 v[8:9], 0
	v_mov_b64_e32 v[10:11], 0
	v_mov_b64_e32 v[12:13], 0
	v_mov_b64_e32 v[14:15], 0
	v_mov_b64_e32 v[16:17], 0
	v_mov_b64_e32 v[18:19], 0
	v_mov_b64_e32 v[20:21], 0
	v_mov_b64_e32 v[22:23], 0
	v_mov_b64_e32 v[24:25], 0
	v_mov_b64_e32 v[26:27], 0
	v_mov_b64_e32 v[28:29], 0
	v_mov_b64_e32 v[30:31], 0
	v_mov_b64_e32 v[32:33], 0
	v_mov_b64_e32 v[34:35], 0
	v_mov_b64_e32 v[36:37], 0
	v_mov_b64_e32 v[38:39], 0
	v_mov_b64_e32 v[40:41], 0
	v_mov_b64_e32 v[42:43], 0
	v_mov_b64_e32 v[44:45], 0
	v_mov_b64_e32 v[46:47], 0
	v_mov_b64_e32 v[48:49], 0
	v_mov_b64_e32 v[50:51], 0
	v_mov_b64_e32 v[52:53], 0
	v_mov_b64_e32 v[54:55], 0
	v_mov_b64_e32 v[56:57], 0
	v_mov_b64_e32 v[58:59], 0
	v_mov_b64_e32 v[60:61], 0
	v_mov_b64_e32 v[62:63], 0
	v_mov_b64_e32 v[64:65], 0
	v_mov_b64_e32 v[66:67], 0
	v_mov_b64_e32 v[68:69], 0
	v_mov_b64_e32 v[70:71], 0
	v_mov_b64_e32 v[72:73], 0
	v_mov_b64_e32 v[74:75], 0
	v_mov_b64_e32 v[76:77], 0
	v_mov_b64_e32 v[78:79], 0
	v_mov_b64_e32 v[80:81], 0
	v_mov_b64_e32 v[82:83], 0
	v_mov_b64_e32 v[84:85], 0
	v_mov_b64_e32 v[86:87], 0
	v_mov_b64_e32 v[88:89], 0
	v_mov_b64_e32 v[90:91], 0
	v_mov_b64_e32 v[92:93], 0
	v_mov_b64_e32 v[94:95], 0
	v_mov_b64_e32 v[96:97], 0
	v_mov_b64_e32 v[98:99], 0
	v_mov_b64_e32 v[100:101], 0
	v_mov_b64_e32 v[102:103], 0
	v_mov_b64_e32 v[104:105], 0
	v_mov_b64_e32 v[106:107], 0
	v_mov_b64_e32 v[108:109], 0
	v_mov_b64_e32 v[110:111], 0
	v_mov_b64_e32 v[112:113], 0
	v_mov_b64_e32 v[114:115], 0
	v_mov_b64_e32 v[116:117], 0
	v_mov_b64_e32 v[118:119], 0
	v_mov_b64_e32 v[120:121], 0
	v_mov_b64_e32 v[122:123], 0
	v_mov_b64_e32 v[124:125], 0
	v_mov_b64_e32 v[126:127], 0
	v_mov_b64_e32 v[128:129], 0

; #define LAS __attribute__((address_space(3)))
; template <int MODE, int NQ>
; __device__ __forceinline__ void attn_unit(LAS unsigned char* lds, const Params& P, int layer, int b, int h, int qb) {
;     ...
;     const int qpos0 = q0 + wave * (32 * NQ) + r32;
;     const int tb0_ = 4 * hi - qpos0 + 2047, ts_ = tb0_ & 3;
;     const LAS unsigned char* tlane = tabb + ts_ * AT_TABC + (tb0_ - ts_) * 4;
;     bf16x8 qf[NC][ND0];
; #pragma unroll
;     for (int jq = 0; jq < NQ; ++jq) {
;         const bf16_t* qrow = Qp + (rowbase + qpos0 + 32 * jq) * qpitch + hi * 8;
; #pragma unroll
;         for (int mp = 0; mp < NMAP; ++mp)
; #pragma unroll
;             for (int d0 = 0; d0 < ND0; ++d0) qf[jq * NMAP + mp][d0] = *(const bf16x8*)(qrow + mp * 32 + d0 * 16);
;     }
;     u32x4 kreg, kreg2 = (u32x4){0u, 0u, 0u, 0u}, vreg;
;     ...
;     float mrun[NC], lrun[NC]; f32x16 o[NC][2];
; #pragma unroll
;     for (int cc = 0; cc < NC; ++cc) { mrun[cc] = -1e20f; lrun[cc] = 0.f; o[cc][0] = f32x16{}; o[cc][1] = f32x16{}; }
;     constexpr int NK = NMAP * ND0;
;     const bf16x8 ones8 = (bf16x8){0x3F80, 0x3F80, 0x3F80, 0x3F80, 0x3F80, 0x3F80, 0x3F80, 0x3F80};
;     const bf16x8 zero8 = (bf16x8){0, 0, 0, 0, 0, 0, 0, 0};
;     bf16x8 kf[NK]; s16x4 vlo[4], vhi[4];
;     ...
;     const int vlane = ((lane >> 4) & 1) * 32 + (lane & 3) * 8 + (4 * hi + ((lane & 15) >> 2)) * 64;
.LBB0_408:
	v_lshlrev_b32_e32 v185, 2, v6
	v_sub_u32_e32 v4, v185, v4
	v_lshlrev_b32_e32 v186, 3, v6
	v_lshlrev_b32_e32 v6, 1, v2
	v_lshrrev_b32_e32 v2, 2, v2
	s_lshl_b32 s4, s4, 6
	v_add_u32_e32 v4, 0x7ff, v4
	v_and_or_b32 v2, v2, 3, v185
	s_lshl_b32 s7, s6, 2
	v_and_b32_e32 v7, 3, v4
	v_lshlrev_b32_e32 v4, 2, v4
	v_lshlrev_b32_e32 v192, 6, v2
	v_mov_b32_e32 v2, s8
	s_add_u32 s8, s14, s22
	v_mul_u32_u24_e32 v7, 0x4040, v7
	v_and_b32_e32 v4, -16, v4
	s_addc_u32 s9, s15, s23
	v_mov_b32_e32 v14, v1
	v_mov_b32_e32 v15, v1
	v_add3_u32 v191, 0, v7, v4
	v_and_b32_e32 v193, 32, v6
	v_or3_b32 v178, s0, v2, v5
	v_lshl_add_u64 v[180:181], s[8:9], 0, v[0:1]
	v_or_b32_e32 v182, s0, v3
	s_add_u32 s0, s10, s16
	v_mov_b32_e32 v0, v1
	v_mov_b32_e32 v2, v1
	v_mov_b32_e32 v3, v1
	v_mov_b32_e32 v4, v1
	v_mov_b32_e32 v5, v1
	v_mov_b32_e32 v6, v1
	v_mov_b32_e32 v7, v1
	v_mov_b32_e32 v8, v1
	v_mov_b32_e32 v9, v1
	v_mov_b32_e32 v10, v1
	v_mov_b32_e32 v11, v1
	v_mov_b32_e32 v12, v1
	v_mov_b32_e32 v13, v1
	v_mov_b64_e32 v[46:47], v[14:15]
	v_mov_b64_e32 v[62:63], v[14:15]
	v_mov_b64_e32 v[30:31], v[14:15]
	v_mov_b64_e32 v[78:79], v[14:15]
	v_or3_b32 v179, s1, 0, 0
	v_mov_b32_e32 v183, s1
	s_addc_u32 s1, s11, s17
	s_lshl_b32 s5, s6, 10
	s_mov_b32 s8, 0
	v_mov_b32_e32 v187, 0
	v_mov_b32_e32 v197, 0xe0ad78ec
	v_mov_b32_e32 v198, 0xe0ad78ec
	v_mov_b32_e32 v188, 0
	v_mov_b64_e32 v[44:45], v[12:13]
	v_mov_b64_e32 v[42:43], v[10:11]
	v_mov_b64_e32 v[40:41], v[8:9]
	v_mov_b64_e32 v[38:39], v[6:7]
	v_mov_b64_e32 v[36:37], v[4:5]
	v_mov_b64_e32 v[34:35], v[2:3]
	v_mov_b64_e32 v[32:33], v[0:1]
	v_mov_b64_e32 v[60:61], v[12:13]
	v_mov_b64_e32 v[58:59], v[10:11]
	v_mov_b64_e32 v[56:57], v[8:9]
	v_mov_b64_e32 v[54:55], v[6:7]
	v_mov_b64_e32 v[52:53], v[4:5]
	v_mov_b64_e32 v[50:51], v[2:3]
	v_mov_b64_e32 v[48:49], v[0:1]
	v_mov_b64_e32 v[28:29], v[12:13]
	v_mov_b64_e32 v[26:27], v[10:11]
	v_mov_b64_e32 v[24:25], v[8:9]
	v_mov_b64_e32 v[22:23], v[6:7]
	v_mov_b64_e32 v[20:21], v[4:5]
	v_mov_b64_e32 v[18:19], v[2:3]
	v_mov_b64_e32 v[16:17], v[0:1]
	v_mov_b64_e32 v[76:77], v[12:13]
	v_mov_b64_e32 v[74:75], v[10:11]
	v_mov_b64_e32 v[72:73], v[8:9]
	v_mov_b64_e32 v[70:71], v[6:7]
	v_mov_b64_e32 v[68:69], v[4:5]
	v_mov_b64_e32 v[66:67], v[2:3]
	v_mov_b64_e32 v[64:65], v[0:1]
	s_mov_b32 s9, 0
	v_mov_b32_e32 v220, s60
	v_mov_b32_e32 v221, s60
	v_mov_b32_e32 v222, s60
	v_mov_b32_e32 v223, s60
	s_branch .LBB0_410

; template <int MODE, int NQ>
; __device__ __forceinline__ void attn_unit(LAS unsigned char* lds, const Params& P, int layer, int b, int h, int qb) {
;     ...
;         const int kt = AT_TILE(it);
;         const int bnx = (bcur == 2) ? 0 : bcur + 1, bn2 = (bnx == 2) ? 0 : bnx + 1;
;         const LAS unsigned char* cur = lds + bcur * AT_BUF;
;         const LAS unsigned char* nxt = lds + bnx * AT_BUF;
; #pragma unroll
;         for (int hf = 0; hf < 2; ++hf) {
;             if (it + 2 < NT) { if (hf == 0) AT_GLOADK(AT_TILE(it + 2)); else AT_GLOADV(AT_TILE(it + 2)); }
;             f32x16 sc[NC];
; #pragma unroll
;             for (int cc = 0; cc < NC; ++cc) {
;                 sc[cc] = f32x16{};
; #pragma unroll
;                 for (int d0 = 0; d0 < ND0; ++d0) sc[cc] = __builtin_amdgcn_mfma_f32_32x32x16_bf16(kf[(cc % NMAP) * ND0 + d0], qf[cc][d0], sc[cc], 0, 0, 0);
;             }
;             __builtin_amdgcn_sched_barrier(0);
;             AT_VLOAD(cur, hf);
;             if (hf == 0) AT_KLOAD(cur, 1); else if (it + 1 < NT) AT_KLOAD(nxt, 0);
;             __builtin_amdgcn_sched_barrier(0);
;             bf16x8 pw[NC][2]; float rmrel[NC]; bool alive = false;
; #pragma unroll
;             for (int cc = 0; cc < NC; ++cc) {
;                 f32x16& s0 = sc[cc];
;                 float mn;
;                 if (MODE != 0) {
;                     const LAS f32x4* tp4 = (const LAS f32x4*)(tlane + (kt * 64 + hf * 32) * 4);
;                     float rm = -3e38f;
; #pragma unroll
;                     for (int g = 0; g < 4; ++g) { const f32x4 t4 = tp4[2 * g];
; #pragma unroll
;                         for (int i = 0; i < 4; ++i) { s0[4 * g + i] = s0[4 * g + i] * c + t4[i]; rm = fmaxf(rm, s0[4 * g + i]); } }
;                     rm = xmax(rm);
;                     mn = fmaxf(mrun[cc], rm);
;                     rmrel[cc] = rm;
;                 } else {
;                     float rm = -3e38f;
; #pragma unroll
;                     for (int r = 0; r < 16; ++r) rm = fmaxf(rm, s0[r]);
;                     rm = xmax(rm);
;                     mn = fmaxf(mrun[cc], rm * c);
;                 }
;                 if (__any(mn > mrun[cc] + AT_THR)) {
;                     const float al = fast_exp2(mrun[cc] - mn); lrun[cc] *= al;
; #pragma unroll
;                     for (int r = 0; r < 16; ++r) { o[cc][0][r] *= al; o[cc][1][r] *= al; }
.LBB0_410:
	s_mul_i32 s10, s9, 0x5000
	s_add_i32 s16, s10, 0
	s_add_i32 s10, s5, s8
	s_add_i32 s11, s10, 0xffffe000
	s_cmp_gt_u32 s7, 31
	v_add3_u32 v0, s16, v193, v192
	s_cselect_b32 s10, s11, s10
	v_add_u32_e32 v199, v0, v189
	v_add_u32_e32 v0, s10, v191
	s_add_i32 s10, s7, 2
	s_sub_i32 s11, s7, 30
	s_cmp_gt_u32 s10, 31
	s_cselect_b32 s10, s11, s10
	s_ashr_i32 s11, s10, 31
	s_lshl_b64 s[10:11], s[10:11], 6
	v_lshl_add_u64 v[2:3], v[182:183], 0, s[10:11]
	v_mov_b64_e32 v[4:5], s[0:1]
	v_mad_u64_u32 v[4:5], s[14:15], v2, s27, v[4:5]
	v_mad_i32_i24 v5, v3, s27, v5
	global_load_dwordx4 v[2:5], v[4:5], off
	s_waitcnt lgkmcnt(3)
	v_mfma_f32_32x32x16_bf16 v[96:111], v[140:143], v[124:127], 0
	s_waitcnt lgkmcnt(1)
	v_mfma_f32_32x32x16_bf16 v[80:95], v[132:135], v[120:123], 0
	v_mfma_f32_32x32x16_bf16 v[96:111], v[136:139], v[116:119], v[96:111]
	s_waitcnt lgkmcnt(0)
	v_mfma_f32_32x32x16_bf16 v[80:95], v[128:131], v[112:115], v[80:95]
	ds_read_b64_tr_b16 v[148:149], v199 offset:12288
	ds_read_b64_tr_b16 v[150:151], v199 offset:12800
	ds_read_b64_tr_b16 v[144:145], v199 offset:13312
	ds_read_b64_tr_b16 v[146:147], v199 offset:13824
	ds_read_b64_tr_b16 v[140:141], v199 offset:16384
	ds_read_b64_tr_b16 v[142:143], v199 offset:16896
	ds_read_b64_tr_b16 v[136:137], v199 offset:17408
	ds_read_b64_tr_b16 v[138:139], v199 offset:17920
	v_add3_u32 v6, s16, v195, v196
	ds_read_b128 v[132:135], v6 offset:512
	ds_read_b128 v[128:131], v6 offset:2560
	ds_read_b128 v[10:13], v6 offset:4608
	ds_read_b128 v[6:9], v6 offset:6656
	ds_read_b128 v[156:159], v0 offset:61440
	ds_read_b128 v[152:155], v0 offset:61472
	ds_read_b128 v[164:167], v0 offset:61504
	ds_read_b128 v[172:175], v0 offset:61536
	s_waitcnt lgkmcnt(3)
	v_pk_fma_f32 v[160:161], v[96:97], s[34:35], v[156:157] op_sel_hi:[1,0,1]
	v_pk_fma_f32 v[98:99], v[98:99], s[34:35], v[158:159] op_sel_hi:[1,0,1]
	v_max3_f32 v96, v160, s68, v161
	s_waitcnt lgkmcnt(2)
	v_pk_fma_f32 v[14:15], v[100:101], s[34:35], v[152:153] op_sel_hi:[1,0,1]
	v_max3_f32 v96, v96, v98, v99
	v_max3_f32 v100, v96, v14, v15
	v_pk_fma_f32 v[96:97], v[102:103], s[34:35], v[154:155] op_sel_hi:[1,0,1]
	s_waitcnt lgkmcnt(1)
	v_pk_fma_f32 v[104:105], v[104:105], s[34:35], v[164:165] op_sel_hi:[1,0,1]
	v_max3_f32 v100, v100, v96, v97
	v_max3_f32 v102, v100, v104, v105
	v_pk_fma_f32 v[100:101], v[106:107], s[34:35], v[166:167] op_sel_hi:[1,0,1]
	s_nop 0
	v_max3_f32 v106, v102, v100, v101
	s_waitcnt lgkmcnt(0)
	v_pk_fma_f32 v[102:103], v[108:109], s[34:35], v[172:173] op_sel_hi:[1,0,1]
	s_nop 0
	v_max3_f32 v108, v106, v102, v103
	v_pk_fma_f32 v[106:107], v[110:111], s[34:35], v[174:175] op_sel_hi:[1,0,1]
	s_nop 0
	v_max3_f32 v108, v108, v106, v107
	v_mov_b32_e32 v109, v108
	s_nop 1
	v_permlane32_swap_b32_e32 v108, v109
	v_max_f32_e32 v108, v108, v109
	v_max_f32_e32 v200, v198, v108
	v_add_f32_e32 v109, 0x41000000, v198
	v_cmp_gt_f32_e32 vcc, v200, v109
	s_cbranch_vccz .LBB0_412
	v_sub_f32_e32 v109, v198, v200
	v_exp_f32_e32 v110, v109
	s_nop 0
	v_mul_f32_e32 v188, v188, v110
	v_pk_mul_f32 v[78:79], v[78:79], v[110:111] op_sel_hi:[1,0]
	v_pk_mul_f32 v[76:77], v[76:77], v[110:111] op_sel_hi:[1,0]
	v_pk_mul_f32 v[74:75], v[74:75], v[110:111] op_sel_hi:[1,0]
	v_pk_mul_f32 v[72:73], v[72:73], v[110:111] op_sel_hi:[1,0]
	v_pk_mul_f32 v[70:71], v[70:71], v[110:111] op_sel_hi:[1,0]
	v_pk_mul_f32 v[68:69], v[68:69], v[110:111] op_sel_hi:[1,0]
	v_pk_mul_f32 v[66:67], v[66:67], v[110:111] op_sel_hi:[1,0]
	v_pk_mul_f32 v[64:65], v[64:65], v[110:111] op_sel_hi:[1,0]
	v_pk_mul_f32 v[30:31], v[30:31], v[110:111] op_sel_hi:[1,0]
	v_pk_mul_f32 v[28:29], v[28:29], v[110:111] op_sel_hi:[1,0]
	v_pk_mul_f32 v[26:27], v[26:27], v[110:111] op_sel_hi:[1,0]
	v_pk_mul_f32 v[24:25], v[24:25], v[110:111] op_sel_hi:[1,0]
	v_pk_mul_f32 v[22:23], v[22:23], v[110:111] op_sel_hi:[1,0]
	v_pk_mul_f32 v[20:21], v[20:21], v[110:111] op_sel_hi:[1,0]
	v_pk_mul_f32 v[18:19], v[18:19], v[110:111] op_sel_hi:[1,0]
	v_pk_mul_f32 v[16:17], v[16:17], v[110:111] op_sel_hi:[1,0]
	s_branch .LBB0_413

; __device__ __forceinline__ unsigned cvtpk(float lo, float hi) { f32x2 v = {lo, hi}; bf16x2_t b = __builtin_convertvector(v, bf16x2_t); return __builtin_bit_cast(unsigned, b); }
; __device__ __forceinline__ float fast_exp2(float x) { return __builtin_amdgcn_exp2f(x); }
; template <int MODE, int NQ>
; __device__ __forceinline__ void attn_unit(LAS unsigned char* lds, const Params& P, int layer, int b, int h, int qb) {
;     ...
;                 mn = mrun[cc];
;                 if (MODE != 0) rmrel[cc] -= mn;
;                 const bool dead = (MODE != 0) && __all(rmrel[cc] < -136.f);
;                 if (dead) { pw[cc][0] = zero8; pw[cc][1] = zero8; }
;                 else {
;                     alive = true;
;                     if (MODE != 0) {
; #pragma unroll
;                         for (int r = 0; r < 16; ++r) s0[r] = fast_exp2(s0[r] - mn);
;                     } else {
;                         const float nm = -mn;
; #pragma unroll
;                         for (int r = 0; r < 16; ++r) s0[r] = fast_exp2(__builtin_fmaf(s0[r], c, nm));
;                     }
;                     u32x4 w;
;                     w.x = cvtpk(s0[0], s0[1]); w.y = cvtpk(s0[2], s0[3]); w.z = cvtpk(s0[4], s0[5]); w.w = cvtpk(s0[6], s0[7]); pw[cc][0] = __builtin_bit_cast(bf16x8, w);
;                     w.x = cvtpk(s0[8], s0[9]); w.y = cvtpk(s0[10], s0[11]); w.z = cvtpk(s0[12], s0[13]); w.w = cvtpk(s0[14], s0[15]); pw[cc][1] = __builtin_bit_cast(bf16x8, w);
;                     f32x16 t = __builtin_amdgcn_mfma_f32_32x32x16_bf16(ones8, pw[cc][0], f32x16{}, 0, 0, 0);
;                     t = __builtin_amdgcn_mfma_f32_32x32x16_bf16(ones8, pw[cc][1], t, 0, 0, 0);
;                     lrun[cc] += t[0];
;                 }
.LBB0_413:
	v_sub_f32_e32 v108, v108, v200
	v_cmp_gt_f32_e32 vcc, s30, v108
	s_cmp_lg_u64 vcc, exec
	s_cselect_b64 s[14:15], -1, 0
	s_cmp_eq_u64 vcc, exec
	s_cbranch_scc1 .LBB0_415
	s_mov_b32 s62, s60
	s_mov_b32 s63, s60
	v_sub_f32_e32 v108, v160, v200
	v_sub_f32_e32 v109, v161, v200
	v_sub_f32_e32 v98, v98, v200
	v_sub_f32_e32 v99, v99, v200
	v_sub_f32_e32 v14, v14, v200
	v_sub_f32_e32 v15, v15, v200
	v_sub_f32_e32 v96, v96, v200
	v_sub_f32_e32 v97, v97, v200
	s_mov_b32 s61, s60
	v_exp_f32_e32 v108, v108
	v_exp_f32_e32 v109, v109
	v_exp_f32_e32 v98, v98
	v_exp_f32_e32 v99, v99
	v_exp_f32_e32 v14, v14
	v_exp_f32_e32 v15, v15
	v_exp_f32_e32 v96, v96
	v_exp_f32_e32 v97, v97
	v_sub_f32_e32 v104, v104, v200
	v_sub_f32_e32 v105, v105, v200
	v_sub_f32_e32 v100, v100, v200
	v_sub_f32_e32 v101, v101, v200
	v_sub_f32_e32 v102, v102, v200
	v_sub_f32_e32 v103, v103, v200
	v_sub_f32_e32 v106, v106, v200
	v_sub_f32_e32 v107, v107, v200
	v_exp_f32_e32 v104, v104
	v_exp_f32_e32 v105, v105
	v_exp_f32_e32 v100, v100
	v_exp_f32_e32 v101, v101
	v_exp_f32_e32 v102, v102
	v_exp_f32_e32 v103, v103
	v_exp_f32_e32 v106, v106
	v_exp_f32_e32 v107, v107
	v_cvt_pk_bf16_f32 v168, v108, v109
	v_cvt_pk_bf16_f32 v169, v98, v99
	v_cvt_pk_bf16_f32 v170, v14, v15
	v_cvt_pk_bf16_f32 v171, v96, v97
	v_cvt_pk_bf16_f32 v160, v104, v105
	v_cvt_pk_bf16_f32 v161, v100, v101
	v_cvt_pk_bf16_f32 v162, v102, v103
	v_cvt_pk_bf16_f32 v163, v106, v107
	v_mfma_f32_32x32x16_bf16 v[96:111], v[220:223], v[168:171], 0
	s_nop 0
	v_mfma_f32_32x32x16_bf16 v[96:111], v[220:223], v[160:163], v[96:111]
	s_nop 11
	v_add_f32_e32 v188, v188, v96
	s_branch .LBB0_416

; #define LAS __attribute__((address_space(3)))
; __device__ __forceinline__ float fast_exp2(float x) { return __builtin_amdgcn_exp2f(x); }
; template <int MODE, int NQ>
; __device__ __forceinline__ void attn_unit(LAS unsigned char* lds, const Params& P, int layer, int b, int h, int qb) {
;     ...
;             for (int cc = 0; cc < NC; ++cc) {
;                 f32x16& s0 = sc[cc];
;                 float mn;
;                 if (MODE != 0) {
;                     const LAS f32x4* tp4 = (const LAS f32x4*)(tlane + (kt * 64 + hf * 32) * 4);
;                     float rm = -3e38f;
; #pragma unroll
;                     for (int g = 0; g < 4; ++g) { const f32x4 t4 = tp4[2 * g];
; #pragma unroll
;                         for (int i = 0; i < 4; ++i) { s0[4 * g + i] = s0[4 * g + i] * c + t4[i]; rm = fmaxf(rm, s0[4 * g + i]); } }
;                     rm = xmax(rm);
;                     mn = fmaxf(mrun[cc], rm);
;                     rmrel[cc] = rm;
;                 } else {
;                     float rm = -3e38f;
; #pragma unroll
;                     for (int r = 0; r < 16; ++r) rm = fmaxf(rm, s0[r]);
;                     rm = xmax(rm);
;                     mn = fmaxf(mrun[cc], rm * c);
;                 }
;                 if (__any(mn > mrun[cc] + AT_THR)) {
;                     const float al = fast_exp2(mrun[cc] - mn); lrun[cc] *= al;
; #pragma unroll
;                     for (int r = 0; r < 16; ++r) { o[cc][0][r] *= al; o[cc][1][r] *= al; }
;                     mrun[cc] = mn;
;                 }
;                 mn = mrun[cc];
;                 if (MODE != 0) rmrel[cc] -= mn;
;                 const bool dead = (MODE != 0) && __all(rmrel[cc] < -136.f);
;                 if (dead) { pw[cc][0] = zero8; pw[cc][1] = zero8; }
;                 else {
;                     alive = true;
;                     if (MODE != 0) {
; #pragma unroll
;                         for (int r = 0; r < 16; ++r) s0[r] = fast_exp2(s0[r] - mn);
;                     } else {
;                         const float nm = -mn;
; #pragma unroll
;                         for (int r = 0; r < 16; ++r) s0[r] = fast_exp2(__builtin_fmaf(s0[r], c, nm));
;                     }
;                     u32x4 w;
;                     w.x = cvtpk(s0[0], s0[1]); w.y = cvtpk(s0[2], s0[3]); w.z = cvtpk(s0[4], s0[5]); w.w = cvtpk(s0[6], s0[7]); pw[cc][0] = __builtin_bit_cast(bf16x8, w);
.LBB0_416:
	v_fmamk_f32 v99, v80, 0x3e8293ee, v156
	v_fmamk_f32 v96, v81, 0x3e8293ee, v157
	v_max3_f32 v14, v99, s68, v96
	v_fmamk_f32 v97, v82, 0x3e8293ee, v158
	v_fmac_f32_e32 v159, 0x3e8293ee, v83
	v_max3_f32 v14, v14, v97, v159
	v_fmamk_f32 v98, v84, 0x3e8293ee, v152
	v_fmamk_f32 v83, v85, 0x3e8293ee, v153
	v_max3_f32 v14, v14, v98, v83
	v_fmamk_f32 v84, v86, 0x3e8293ee, v154
	v_fmac_f32_e32 v155, 0x3e8293ee, v87
	v_max3_f32 v14, v14, v84, v155
	v_fmamk_f32 v85, v88, 0x3e8293ee, v164
	v_fmamk_f32 v80, v89, 0x3e8293ee, v165
	v_max3_f32 v14, v14, v85, v80
	v_fmamk_f32 v81, v90, 0x3e8293ee, v166
	v_fmac_f32_e32 v167, 0x3e8293ee, v91
	v_max3_f32 v15, v14, v81, v167
	v_fmamk_f32 v82, v92, 0x3e8293ee, v172
	v_fmamk_f32 v14, v93, 0x3e8293ee, v173
	v_max3_f32 v86, v15, v82, v14
	v_fmamk_f32 v15, v94, 0x3e8293ee, v174
	v_fmac_f32_e32 v175, 0x3e8293ee, v95
	v_max3_f32 v86, v86, v15, v175
	v_mov_b32_e32 v87, v86
	s_nop 1
	v_permlane32_swap_b32_e32 v86, v87
	v_max_f32_e32 v86, v86, v87
	v_max_f32_e32 v201, v197, v86
	v_add_f32_e32 v87, 0x41000000, v197
	v_cmp_gt_f32_e32 vcc, v201, v87
	s_cbranch_vccz .LBB0_419
	v_sub_f32_e32 v87, v197, v201
	v_exp_f32_e32 v88, v87
	s_nop 0
	v_mul_f32_e32 v187, v187, v88
	v_pk_mul_f32 v[62:63], v[62:63], v[88:89] op_sel_hi:[1,0]
	v_pk_mul_f32 v[60:61], v[60:61], v[88:89] op_sel_hi:[1,0]
	v_pk_mul_f32 v[58:59], v[58:59], v[88:89] op_sel_hi:[1,0]
	v_pk_mul_f32 v[56:57], v[56:57], v[88:89] op_sel_hi:[1,0]
	v_pk_mul_f32 v[54:55], v[54:55], v[88:89] op_sel_hi:[1,0]
	v_pk_mul_f32 v[52:53], v[52:53], v[88:89] op_sel_hi:[1,0]
	v_pk_mul_f32 v[50:51], v[50:51], v[88:89] op_sel_hi:[1,0]
	v_pk_mul_f32 v[48:49], v[48:49], v[88:89] op_sel_hi:[1,0]
	v_pk_mul_f32 v[46:47], v[46:47], v[88:89] op_sel_hi:[1,0]
	v_pk_mul_f32 v[44:45], v[44:45], v[88:89] op_sel_hi:[1,0]
	v_pk_mul_f32 v[42:43], v[42:43], v[88:89] op_sel_hi:[1,0]
	v_pk_mul_f32 v[40:41], v[40:41], v[88:89] op_sel_hi:[1,0]
	v_pk_mul_f32 v[38:39], v[38:39], v[88:89] op_sel_hi:[1,0]
	v_pk_mul_f32 v[36:37], v[36:37], v[88:89] op_sel_hi:[1,0]
	v_pk_mul_f32 v[34:35], v[34:35], v[88:89] op_sel_hi:[1,0]
	v_pk_mul_f32 v[32:33], v[32:33], v[88:89] op_sel_hi:[1,0]
	v_sub_f32_e32 v86, v86, v201
	v_cmp_gt_f32_e32 vcc, s30, v86
	s_cmp_eq_u64 vcc, exec
	s_cbranch_scc1 .LBB0_420
.LBB0_418:
	s_mov_b32 s62, s60
	s_mov_b32 s63, s60
	v_sub_f32_e32 v86, v99, v201
	v_sub_f32_e32 v87, v96, v201
	v_sub_f32_e32 v88, v97, v201
	v_sub_f32_e32 v89, v159, v201
	v_sub_f32_e32 v90, v98, v201
	v_sub_f32_e32 v83, v83, v201
	v_sub_f32_e32 v84, v84, v201
	v_sub_f32_e32 v91, v155, v201
	s_mov_b32 s61, s60
	v_exp_f32_e32 v86, v86
	v_exp_f32_e32 v87, v87
	v_exp_f32_e32 v88, v88
	v_exp_f32_e32 v89, v89
	v_exp_f32_e32 v90, v90
	v_exp_f32_e32 v83, v83
	v_exp_f32_e32 v84, v84
	v_exp_f32_e32 v91, v91
	v_sub_f32_e32 v85, v85, v201
	v_sub_f32_e32 v80, v80, v201
	v_sub_f32_e32 v81, v81, v201
	v_sub_f32_e32 v92, v167, v201
	v_sub_f32_e32 v82, v82, v201
	v_sub_f32_e32 v14, v14, v201
	v_sub_f32_e32 v15, v15, v201
	v_sub_f32_e32 v93, v175, v201
	v_exp_f32_e32 v85, v85
	v_exp_f32_e32 v80, v80
	v_exp_f32_e32 v81, v81
	v_exp_f32_e32 v92, v92
	v_exp_f32_e32 v82, v82
	v_exp_f32_e32 v14, v14
	v_exp_f32_e32 v15, v15
	v_exp_f32_e32 v93, v93
	v_cvt_pk_bf16_f32 v100, v86, v87
	v_cvt_pk_bf16_f32 v101, v88, v89
	v_cvt_pk_bf16_f32 v102, v90, v83
	v_cvt_pk_bf16_f32 v103, v84, v91
	v_cvt_pk_bf16_f32 v96, v85, v80
	v_cvt_pk_bf16_f32 v97, v81, v92
	v_cvt_pk_bf16_f32 v98, v82, v14
	v_cvt_pk_bf16_f32 v99, v15, v93
	v_mfma_f32_32x32x16_bf16 v[80:95], v[220:223], v[100:103], 0
	s_nop 0
	v_mfma_f32_32x32x16_bf16 v[80:95], v[220:223], v[96:99], v[80:95]
	s_nop 11
	v_add_f32_e32 v187, v187, v80
	s_cbranch_execnz .LBB0_421
	s_branch .LBB0_422

; #define LAS __attribute__((address_space(3)))
; template <int MODE, int NQ>
; __device__ __forceinline__ void attn_unit(LAS unsigned char* lds, const Params& P, int layer, int b, int h, int qb) {
;     ...
;     for (int it = 0; it < NT; ++it) {
;         const int kt = AT_TILE(it);
;         const int bnx = (bcur == 2) ? 0 : bcur + 1, bn2 = (bnx == 2) ? 0 : bnx + 1;
;         const LAS unsigned char* cur = lds + bcur * AT_BUF;
;         const LAS unsigned char* nxt = lds + bnx * AT_BUF;
; #pragma unroll
;         for (int hf = 0; hf < 2; ++hf) {
;             if (it + 2 < NT) { if (hf == 0) AT_GLOADK(AT_TILE(it + 2)); else AT_GLOADV(AT_TILE(it + 2)); }
;             f32x16 sc[NC];
; #pragma unroll
;             for (int cc = 0; cc < NC; ++cc) {
;                 sc[cc] = f32x16{};
; #pragma unroll
;                 for (int d0 = 0; d0 < ND0; ++d0) sc[cc] = __builtin_amdgcn_mfma_f32_32x32x16_bf16(kf[(cc % NMAP) * ND0 + d0], qf[cc][d0], sc[cc], 0, 0, 0);
;             }
;             __builtin_amdgcn_sched_barrier(0);
;             AT_VLOAD(cur, hf);
;             if (hf == 0) AT_KLOAD(cur, 1); else if (it + 1 < NT) AT_KLOAD(nxt, 0);
;             __builtin_amdgcn_sched_barrier(0);
;             bf16x8 pw[NC][2]; float rmrel[NC]; bool alive = false;
; #pragma unroll
;             for (int cc = 0; cc < NC; ++cc) {
;                 f32x16& s0 = sc[cc];
;                 float mn;
;                 if (MODE != 0) {
;                     const LAS f32x4* tp4 = (const LAS f32x4*)(tlane + (kt * 64 + hf * 32) * 4);
;                     float rm = -3e38f;
; #pragma unroll
;                     for (int g = 0; g < 4; ++g) { const f32x4 t4 = tp4[2 * g];
; #pragma unroll
;                         for (int i = 0; i < 4; ++i) { s0[4 * g + i] = s0[4 * g + i] * c + t4[i]; rm = fmaxf(rm, s0[4 * g + i]); } }
;                     rm = xmax(rm);
;                     mn = fmaxf(mrun[cc], rm);
;                     rmrel[cc] = rm;
;                 } else {
;                     float rm = -3e38f;
; #pragma unroll
;                     for (int r = 0; r < 16; ++r) rm = fmaxf(rm, s0[r]);
;                     rm = xmax(rm);
;                     mn = fmaxf(mrun[cc], rm * c);
;                 }
;                 if (__any(mn > mrun[cc] + AT_THR)) {
;                     const float al = fast_exp2(mrun[cc] - mn); lrun[cc] *= al;
; #pragma unroll
.LBB0_422:
	s_add_i32 s14, s9, 1
	s_cmp_lg_u32 s9, 2
	s_cselect_b32 s9, s14, 0
	v_lshl_add_u64 v[14:15], v[178:179], 0, s[10:11]
	s_mul_i32 s15, s9, 0x5000
	v_mad_u64_u32 v[80:81], s[10:11], v14, s27, v[180:181]
	s_add_i32 s10, s15, 0x5000
	s_cmp_lg_u32 s9, 2
	s_cselect_b32 s14, s10, 0
	v_mad_i32_i24 v81, v15, s27, v81
	v_add_u32_e32 v202, s14, v194
	s_waitcnt vmcnt(0)
	ds_write_b128 v202, v[2:5]
	global_load_dwordx4 v[2:5], v[80:81], off
	v_mfma_f32_32x32x16_bf16 v[96:111], v[132:135], v[124:127], 0
	v_mfma_f32_32x32x16_bf16 v[80:95], v[10:13], v[120:123], 0
	v_mfma_f32_32x32x16_bf16 v[96:111], v[128:131], v[116:119], v[96:111]
	v_mfma_f32_32x32x16_bf16 v[80:95], v[6:9], v[112:115], v[80:95]
	ds_read_b64_tr_b16 v[148:149], v199 offset:14336
	ds_read_b64_tr_b16 v[150:151], v199 offset:14848
	ds_read_b64_tr_b16 v[144:145], v199 offset:15360
	ds_read_b64_tr_b16 v[146:147], v199 offset:15872
	ds_read_b64_tr_b16 v[10:11], v199 offset:18432
	ds_read_b64_tr_b16 v[12:13], v199 offset:18944
	ds_read_b64_tr_b16 v[6:7], v199 offset:19456
	ds_read_b64_tr_b16 v[8:9], v199 offset:19968
	v_add_u32_e32 v14, s15, v190
	ds_read_b128 v[140:143], v14
	ds_read_b128 v[136:139], v14 offset:2048
	ds_read_b128 v[132:135], v14 offset:4096
	ds_read_b128 v[128:131], v14 offset:6144
	ds_read_b128 v[156:159], v0 offset:61568
	ds_read_b128 v[152:155], v0 offset:61600
	ds_read_b128 v[164:167], v0 offset:61632
	ds_read_b128 v[172:175], v0 offset:61664
	s_waitcnt lgkmcnt(3)
	v_pk_fma_f32 v[160:161], v[96:97], s[34:35], v[156:157] op_sel_hi:[1,0,1]
	v_pk_fma_f32 v[98:99], v[98:99], s[34:35], v[158:159] op_sel_hi:[1,0,1]
	v_max3_f32 v96, v160, s68, v161
	s_waitcnt lgkmcnt(2)
	v_pk_fma_f32 v[14:15], v[100:101], s[34:35], v[152:153] op_sel_hi:[1,0,1]
	v_max3_f32 v96, v96, v98, v99
	v_max3_f32 v100, v96, v14, v15
	v_pk_fma_f32 v[96:97], v[102:103], s[34:35], v[154:155] op_sel_hi:[1,0,1]
	s_waitcnt lgkmcnt(1)
	v_pk_fma_f32 v[104:105], v[104:105], s[34:35], v[164:165] op_sel_hi:[1,0,1]
	v_max3_f32 v100, v100, v96, v97
	v_max3_f32 v0, v100, v104, v105
	v_pk_fma_f32 v[100:101], v[106:107], s[34:35], v[166:167] op_sel_hi:[1,0,1]
	s_waitcnt lgkmcnt(0)
	v_pk_fma_f32 v[102:103], v[108:109], s[34:35], v[172:173] op_sel_hi:[1,0,1]
	v_max3_f32 v0, v0, v100, v101
	v_max3_f32 v0, v0, v102, v103
	v_pk_fma_f32 v[106:107], v[110:111], s[34:35], v[174:175] op_sel_hi:[1,0,1]
	s_nop 0
	v_max3_f32 v0, v0, v106, v107
	v_mov_b32_e32 v108, v0
	s_nop 1
	v_permlane32_swap_b32_e32 v0, v108
	v_max_f32_e32 v0, v0, v108
	v_max_f32_e32 v198, v200, v0
	v_add_f32_e32 v108, 0x41000000, v200
	v_cmp_gt_f32_e32 vcc, v198, v108
	s_cbranch_vccz .LBB0_424
	v_sub_f32_e32 v108, v200, v198
	v_exp_f32_e32 v108, v108
	s_nop 0
	v_mul_f32_e32 v188, v188, v108
	v_pk_mul_f32 v[78:79], v[78:79], v[108:109] op_sel_hi:[1,0]
	v_pk_mul_f32 v[76:77], v[76:77], v[108:109] op_sel_hi:[1,0]
	v_pk_mul_f32 v[74:75], v[74:75], v[108:109] op_sel_hi:[1,0]
	v_pk_mul_f32 v[72:73], v[72:73], v[108:109] op_sel_hi:[1,0]
	v_pk_mul_f32 v[70:71], v[70:71], v[108:109] op_sel_hi:[1,0]
	v_pk_mul_f32 v[68:69], v[68:69], v[108:109] op_sel_hi:[1,0]
	v_pk_mul_f32 v[66:67], v[66:67], v[108:109] op_sel_hi:[1,0]
	v_pk_mul_f32 v[64:65], v[64:65], v[108:109] op_sel_hi:[1,0]
	v_pk_mul_f32 v[30:31], v[30:31], v[108:109] op_sel_hi:[1,0]
	v_pk_mul_f32 v[28:29], v[28:29], v[108:109] op_sel_hi:[1,0]
	v_pk_mul_f32 v[26:27], v[26:27], v[108:109] op_sel_hi:[1,0]
	v_pk_mul_f32 v[24:25], v[24:25], v[108:109] op_sel_hi:[1,0]
	v_pk_mul_f32 v[22:23], v[22:23], v[108:109] op_sel_hi:[1,0]
	v_pk_mul_f32 v[20:21], v[20:21], v[108:109] op_sel_hi:[1,0]
	v_pk_mul_f32 v[18:19], v[18:19], v[108:109] op_sel_hi:[1,0]
	v_pk_mul_f32 v[16:17], v[16:17], v[108:109] op_sel_hi:[1,0]
	s_branch .LBB0_425

; __device__ __forceinline__ unsigned cvtpk(float lo, float hi) { f32x2 v = {lo, hi}; bf16x2_t b = __builtin_convertvector(v, bf16x2_t); return __builtin_bit_cast(unsigned, b); }
; __device__ __forceinline__ float fast_exp2(float x) { return __builtin_amdgcn_exp2f(x); }
; template <int MODE, int NQ>
; __device__ __forceinline__ void attn_unit(LAS unsigned char* lds, const Params& P, int layer, int b, int h, int qb) {
;     ...
;                 mn = mrun[cc];
;                 if (MODE != 0) rmrel[cc] -= mn;
;                 const bool dead = (MODE != 0) && __all(rmrel[cc] < -136.f);
;                 if (dead) { pw[cc][0] = zero8; pw[cc][1] = zero8; }
;                 else {
;                     alive = true;
;                     if (MODE != 0) {
; #pragma unroll
;                         for (int r = 0; r < 16; ++r) s0[r] = fast_exp2(s0[r] - mn);
;                     } else {
;                         const float nm = -mn;
; #pragma unroll
;                         for (int r = 0; r < 16; ++r) s0[r] = fast_exp2(__builtin_fmaf(s0[r], c, nm));
;                     }
;                     u32x4 w;
;                     w.x = cvtpk(s0[0], s0[1]); w.y = cvtpk(s0[2], s0[3]); w.z = cvtpk(s0[4], s0[5]); w.w = cvtpk(s0[6], s0[7]); pw[cc][0] = __builtin_bit_cast(bf16x8, w);
;                     w.x = cvtpk(s0[8], s0[9]); w.y = cvtpk(s0[10], s0[11]); w.z = cvtpk(s0[12], s0[13]); w.w = cvtpk(s0[14], s0[15]); pw[cc][1] = __builtin_bit_cast(bf16x8, w);
;                     f32x16 t = __builtin_amdgcn_mfma_f32_32x32x16_bf16(ones8, pw[cc][0], f32x16{}, 0, 0, 0);
;                     t = __builtin_amdgcn_mfma_f32_32x32x16_bf16(ones8, pw[cc][1], t, 0, 0, 0);
;                     lrun[cc] += t[0];
;                 }
.LBB0_425:
	v_sub_f32_e32 v0, v0, v198
	v_cmp_gt_f32_e32 vcc, s30, v0
	s_cmp_lg_u64 vcc, exec
	s_cselect_b64 s[10:11], -1, 0
	s_cmp_eq_u64 vcc, exec
	s_cbranch_scc1 .LBB0_427
	s_mov_b32 s62, s60
	s_mov_b32 s63, s60
	v_sub_f32_e32 v0, v160, v198
	v_sub_f32_e32 v108, v161, v198
	v_sub_f32_e32 v98, v98, v198
	v_sub_f32_e32 v99, v99, v198
	v_sub_f32_e32 v14, v14, v198
	v_sub_f32_e32 v15, v15, v198
	v_sub_f32_e32 v96, v96, v198
	v_sub_f32_e32 v97, v97, v198
	s_mov_b32 s61, s60
	v_exp_f32_e32 v0, v0
	v_exp_f32_e32 v108, v108
	v_exp_f32_e32 v98, v98
	v_exp_f32_e32 v99, v99
	v_exp_f32_e32 v14, v14
	v_exp_f32_e32 v15, v15
	v_exp_f32_e32 v96, v96
	v_exp_f32_e32 v97, v97
	v_sub_f32_e32 v104, v104, v198
	v_sub_f32_e32 v105, v105, v198
	v_sub_f32_e32 v100, v100, v198
	v_sub_f32_e32 v101, v101, v198
	v_sub_f32_e32 v102, v102, v198
	v_sub_f32_e32 v103, v103, v198
	v_sub_f32_e32 v106, v106, v198
	v_sub_f32_e32 v107, v107, v198
	v_exp_f32_e32 v104, v104
	v_exp_f32_e32 v105, v105
	v_exp_f32_e32 v100, v100
	v_exp_f32_e32 v101, v101
	v_exp_f32_e32 v102, v102
	v_exp_f32_e32 v103, v103
	v_exp_f32_e32 v106, v106
	v_exp_f32_e32 v107, v107
	v_cvt_pk_bf16_f32 v168, v0, v108
	v_cvt_pk_bf16_f32 v169, v98, v99
	v_cvt_pk_bf16_f32 v170, v14, v15
	v_cvt_pk_bf16_f32 v171, v96, v97
	v_cvt_pk_bf16_f32 v160, v104, v105
	v_cvt_pk_bf16_f32 v161, v100, v101
	v_cvt_pk_bf16_f32 v162, v102, v103
	v_cvt_pk_bf16_f32 v163, v106, v107
	v_mfma_f32_32x32x16_bf16 v[96:111], v[220:223], v[168:171], 0
	s_nop 0
	v_mfma_f32_32x32x16_bf16 v[96:111], v[220:223], v[160:163], v[96:111]
	s_nop 11
	v_add_f32_e32 v188, v188, v96
	s_branch .LBB0_428

; #define LAS __attribute__((address_space(3)))
; __device__ __forceinline__ float fast_exp2(float x) { return __builtin_amdgcn_exp2f(x); }
; template <int MODE, int NQ>
; __device__ __forceinline__ void attn_unit(LAS unsigned char* lds, const Params& P, int layer, int b, int h, int qb) {
;     ...
;             for (int cc = 0; cc < NC; ++cc) {
;                 f32x16& s0 = sc[cc];
;                 float mn;
;                 if (MODE != 0) {
;                     const LAS f32x4* tp4 = (const LAS f32x4*)(tlane + (kt * 64 + hf * 32) * 4);
;                     float rm = -3e38f;
; #pragma unroll
;                     for (int g = 0; g < 4; ++g) { const f32x4 t4 = tp4[2 * g];
; #pragma unroll
;                         for (int i = 0; i < 4; ++i) { s0[4 * g + i] = s0[4 * g + i] * c + t4[i]; rm = fmaxf(rm, s0[4 * g + i]); } }
;                     rm = xmax(rm);
;                     mn = fmaxf(mrun[cc], rm);
;                     rmrel[cc] = rm;
;                 } else {
;                     float rm = -3e38f;
; #pragma unroll
;                     for (int r = 0; r < 16; ++r) rm = fmaxf(rm, s0[r]);
;                     rm = xmax(rm);
;                     mn = fmaxf(mrun[cc], rm * c);
;                 }
;                 if (__any(mn > mrun[cc] + AT_THR)) {
;                     const float al = fast_exp2(mrun[cc] - mn); lrun[cc] *= al;
; #pragma unroll
;                     for (int r = 0; r < 16; ++r) { o[cc][0][r] *= al; o[cc][1][r] *= al; }
;                     mrun[cc] = mn;
;                 }
;                 mn = mrun[cc];
;                 if (MODE != 0) rmrel[cc] -= mn;
;                 const bool dead = (MODE != 0) && __all(rmrel[cc] < -136.f);
;                 if (dead) { pw[cc][0] = zero8; pw[cc][1] = zero8; }
;                 else {
;                     alive = true;
;                     if (MODE != 0) {
; #pragma unroll
;                         for (int r = 0; r < 16; ++r) s0[r] = fast_exp2(s0[r] - mn);
;                     } else {
;                         const float nm = -mn;
; #pragma unroll
;                         for (int r = 0; r < 16; ++r) s0[r] = fast_exp2(__builtin_fmaf(s0[r], c, nm));
;                     }
;                     u32x4 w;
;                     w.x = cvtpk(s0[0], s0[1]); w.y = cvtpk(s0[2], s0[3]); w.z = cvtpk(s0[4], s0[5]); w.w = cvtpk(s0[6], s0[7]); pw[cc][0] = __builtin_bit_cast(bf16x8, w);
.LBB0_428:
	v_fmamk_f32 v99, v80, 0x3e8293ee, v156
	v_fmamk_f32 v96, v81, 0x3e8293ee, v157
	v_max3_f32 v0, v99, s68, v96
	v_fmamk_f32 v97, v82, 0x3e8293ee, v158
	v_fmac_f32_e32 v159, 0x3e8293ee, v83
	v_max3_f32 v0, v0, v97, v159
	v_fmamk_f32 v98, v84, 0x3e8293ee, v152
	v_fmamk_f32 v82, v85, 0x3e8293ee, v153
	v_max3_f32 v0, v0, v98, v82
	v_fmamk_f32 v83, v86, 0x3e8293ee, v154
	v_fmac_f32_e32 v155, 0x3e8293ee, v87
	v_max3_f32 v0, v0, v83, v155
	v_fmamk_f32 v84, v88, 0x3e8293ee, v164
	v_fmamk_f32 v15, v89, 0x3e8293ee, v165
	v_max3_f32 v0, v0, v84, v15
	v_fmamk_f32 v80, v90, 0x3e8293ee, v166
	v_fmac_f32_e32 v167, 0x3e8293ee, v91
	v_max3_f32 v14, v0, v80, v167
	v_fmamk_f32 v81, v92, 0x3e8293ee, v172
	v_fmamk_f32 v0, v93, 0x3e8293ee, v173
	v_max3_f32 v85, v14, v81, v0
	v_fmamk_f32 v14, v94, 0x3e8293ee, v174
	v_fmac_f32_e32 v175, 0x3e8293ee, v95
	v_max3_f32 v85, v85, v14, v175
	v_mov_b32_e32 v86, v85
	s_nop 1
	v_permlane32_swap_b32_e32 v85, v86
	v_max_f32_e32 v85, v85, v86
	v_max_f32_e32 v197, v201, v85
	v_add_f32_e32 v86, 0x41000000, v201
	v_cmp_gt_f32_e32 vcc, v197, v86
	s_cbranch_vccz .LBB0_431
	v_sub_f32_e32 v86, v201, v197
	v_exp_f32_e32 v86, v86
	s_nop 0
	v_mul_f32_e32 v187, v187, v86
	v_pk_mul_f32 v[62:63], v[62:63], v[86:87] op_sel_hi:[1,0]
	v_pk_mul_f32 v[60:61], v[60:61], v[86:87] op_sel_hi:[1,0]
	v_pk_mul_f32 v[58:59], v[58:59], v[86:87] op_sel_hi:[1,0]
	v_pk_mul_f32 v[56:57], v[56:57], v[86:87] op_sel_hi:[1,0]
	v_pk_mul_f32 v[54:55], v[54:55], v[86:87] op_sel_hi:[1,0]
	v_pk_mul_f32 v[52:53], v[52:53], v[86:87] op_sel_hi:[1,0]
	v_pk_mul_f32 v[50:51], v[50:51], v[86:87] op_sel_hi:[1,0]
	v_pk_mul_f32 v[48:49], v[48:49], v[86:87] op_sel_hi:[1,0]
	v_pk_mul_f32 v[46:47], v[46:47], v[86:87] op_sel_hi:[1,0]
	v_pk_mul_f32 v[44:45], v[44:45], v[86:87] op_sel_hi:[1,0]
	v_pk_mul_f32 v[42:43], v[42:43], v[86:87] op_sel_hi:[1,0]
	v_pk_mul_f32 v[40:41], v[40:41], v[86:87] op_sel_hi:[1,0]
	v_pk_mul_f32 v[38:39], v[38:39], v[86:87] op_sel_hi:[1,0]
	v_pk_mul_f32 v[36:37], v[36:37], v[86:87] op_sel_hi:[1,0]
	v_pk_mul_f32 v[34:35], v[34:35], v[86:87] op_sel_hi:[1,0]
	v_pk_mul_f32 v[32:33], v[32:33], v[86:87] op_sel_hi:[1,0]
	v_sub_f32_e32 v85, v85, v197
	v_cmp_gt_f32_e32 vcc, s30, v85
	s_cmp_eq_u64 vcc, exec
	s_cbranch_scc1 .LBB0_432
.LBB0_430:
	s_mov_b32 s62, s60
	s_mov_b32 s63, s60
	v_sub_f32_e32 v85, v99, v197
	v_sub_f32_e32 v86, v96, v197
	v_sub_f32_e32 v87, v97, v197
	v_sub_f32_e32 v88, v159, v197
	v_sub_f32_e32 v89, v98, v197
	v_sub_f32_e32 v82, v82, v197
	v_sub_f32_e32 v83, v83, v197
	v_sub_f32_e32 v90, v155, v197
	s_mov_b32 s61, s60
	v_exp_f32_e32 v85, v85
	v_exp_f32_e32 v86, v86
	v_exp_f32_e32 v87, v87
	v_exp_f32_e32 v88, v88
	v_exp_f32_e32 v89, v89
	v_exp_f32_e32 v82, v82
	v_exp_f32_e32 v83, v83
	v_exp_f32_e32 v90, v90
	v_sub_f32_e32 v84, v84, v197
	v_sub_f32_e32 v15, v15, v197
	v_sub_f32_e32 v80, v80, v197
	v_sub_f32_e32 v91, v167, v197
	v_sub_f32_e32 v81, v81, v197
	v_sub_f32_e32 v0, v0, v197
	v_sub_f32_e32 v14, v14, v197
	v_sub_f32_e32 v92, v175, v197
	v_exp_f32_e32 v84, v84
	v_exp_f32_e32 v15, v15
	v_exp_f32_e32 v80, v80
	v_exp_f32_e32 v91, v91
	v_exp_f32_e32 v81, v81
	v_exp_f32_e32 v0, v0
	v_exp_f32_e32 v14, v14
	v_exp_f32_e32 v92, v92
	v_cvt_pk_bf16_f32 v100, v85, v86
	v_cvt_pk_bf16_f32 v101, v87, v88
	v_cvt_pk_bf16_f32 v102, v89, v82
	v_cvt_pk_bf16_f32 v103, v83, v90
	v_cvt_pk_bf16_f32 v96, v84, v15
	v_cvt_pk_bf16_f32 v97, v80, v91
	v_cvt_pk_bf16_f32 v98, v81, v0
	v_cvt_pk_bf16_f32 v99, v14, v92
	v_mfma_f32_32x32x16_bf16 v[80:95], v[220:223], v[100:103], 0
	s_nop 0
	v_mfma_f32_32x32x16_bf16 v[80:95], v[220:223], v[96:99], v[80:95]
	s_nop 11
	v_add_f32_e32 v187, v187, v80
	s_branch .LBB0_433

; #define LAS __attribute__((address_space(3)))
; template <int MODE, int NQ>
; __device__ __forceinline__ void attn_unit(LAS unsigned char* lds, const Params& P, int layer, int b, int h, int qb) {
;     ...
;     for (int it = 0; it < NT; ++it) {
;         const int kt = AT_TILE(it);
;         const int bnx = (bcur == 2) ? 0 : bcur + 1, bn2 = (bnx == 2) ? 0 : bnx + 1;
;         const LAS unsigned char* cur = lds + bcur * AT_BUF;
;         const LAS unsigned char* nxt = lds + bnx * AT_BUF;
; #pragma unroll
;         for (int hf = 0; hf < 2; ++hf) {
;             if (it + 2 < NT) { if (hf == 0) AT_GLOADK(AT_TILE(it + 2)); else AT_GLOADV(AT_TILE(it + 2)); }
;             f32x16 sc[NC];
; #pragma unroll
;             for (int cc = 0; cc < NC; ++cc) {
;                 sc[cc] = f32x16{};
; #pragma unroll
;                 for (int d0 = 0; d0 < ND0; ++d0) sc[cc] = __builtin_amdgcn_mfma_f32_32x32x16_bf16(kf[(cc % NMAP) * ND0 + d0], qf[cc][d0], sc[cc], 0, 0, 0);
;             }
;             __builtin_amdgcn_sched_barrier(0);
;             AT_VLOAD(cur, hf);
;             if (hf == 0) AT_KLOAD(cur, 1); else if (it + 1 < NT) AT_KLOAD(nxt, 0);
;             __builtin_amdgcn_sched_barrier(0);
;             bf16x8 pw[NC][2]; float rmrel[NC]; bool alive = false;
; #pragma unroll
;             for (int cc = 0; cc < NC; ++cc) {
;                 f32x16& s0 = sc[cc];
;                 float mn;
;                 if (MODE != 0) {
;                     const LAS f32x4* tp4 = (const LAS f32x4*)(tlane + (kt * 64 + hf * 32) * 4);
;                     float rm = -3e38f;
; #pragma unroll
;                     for (int g = 0; g < 4; ++g) { const f32x4 t4 = tp4[2 * g];
; #pragma unroll
;                         for (int i = 0; i < 4; ++i) { s0[4 * g + i] = s0[4 * g + i] * c + t4[i]; rm = fmaxf(rm, s0[4 * g + i]); } }
;                     rm = xmax(rm);
;                     mn = fmaxf(mrun[cc], rm);
;                     rmrel[cc] = rm;
;                 } else {
;                     float rm = -3e38f;
; #pragma unroll
;                     for (int r = 0; r < 16; ++r) rm = fmaxf(rm, s0[r]);
;                     rm = xmax(rm);
;                     mn = fmaxf(mrun[cc], rm * c);
;                 }
;                 if (__any(mn > mrun[cc] + AT_THR)) {
;                     const float al = fast_exp2(mrun[cc] - mn); lrun[cc] *= al;
; #pragma unroll
.LBB0_434:
	v_mfma_f32_32x32x16_bf16 v[96:111], v[140:143], v[124:127], 0
	s_add_i32 s8, s15, 0
	s_add_i32 s9, s5, 0xfffffe00
	s_cmp_eq_u32 s6, 0
	s_cselect_b64 s[0:1], -1, 0
	s_and_b64 s[6:7], s[0:1], exec
	v_add3_u32 v0, s8, v193, v192
	s_cselect_b32 s6, 0x1e00, s9
	v_mfma_f32_32x32x16_bf16 v[80:95], v[132:135], v[120:123], 0
	v_add_u32_e32 v172, v0, v189
	v_add_u32_e32 v0, s6, v191
	v_mfma_f32_32x32x16_bf16 v[96:111], v[136:139], v[116:119], v[96:111]
	v_mfma_f32_32x32x16_bf16 v[80:95], v[128:131], v[112:115], v[80:95]
	ds_read_b64_tr_b16 v[144:145], v172 offset:12288
	ds_read_b64_tr_b16 v[146:147], v172 offset:12800
	ds_read_b64_tr_b16 v[140:141], v172 offset:13312
	ds_read_b64_tr_b16 v[142:143], v172 offset:13824
	ds_read_b64_tr_b16 v[136:137], v172 offset:16384
	ds_read_b64_tr_b16 v[138:139], v172 offset:16896
	ds_read_b64_tr_b16 v[132:133], v172 offset:17408
	ds_read_b64_tr_b16 v[134:135], v172 offset:17920
	v_add3_u32 v2, s8, v195, v196
	ds_read_b128 v[128:131], v2 offset:512
	ds_read_b128 v[6:9], v2 offset:2560
	ds_read_b128 v[10:13], v2 offset:4608
	ds_read_b128 v[2:5], v2 offset:6656
	ds_read_b128 v[152:155], v0 offset:61440
	ds_read_b128 v[148:151], v0 offset:61472
	ds_read_b128 v[160:163], v0 offset:61504
	ds_read_b128 v[168:171], v0 offset:61536
	s_waitcnt lgkmcnt(3)
	v_pk_fma_f32 v[156:157], v[96:97], s[34:35], v[152:153] op_sel_hi:[1,0,1]
	v_pk_fma_f32 v[98:99], v[98:99], s[34:35], v[154:155] op_sel_hi:[1,0,1]
	v_max3_f32 v96, v156, s68, v157
	s_waitcnt lgkmcnt(2)
	v_pk_fma_f32 v[14:15], v[100:101], s[34:35], v[148:149] op_sel_hi:[1,0,1]
	v_max3_f32 v96, v96, v98, v99
	v_max3_f32 v100, v96, v14, v15
	v_pk_fma_f32 v[96:97], v[102:103], s[34:35], v[150:151] op_sel_hi:[1,0,1]
	s_waitcnt lgkmcnt(1)
	v_pk_fma_f32 v[104:105], v[104:105], s[34:35], v[160:161] op_sel_hi:[1,0,1]
	v_max3_f32 v100, v100, v96, v97
	v_max3_f32 v102, v100, v104, v105
	v_pk_fma_f32 v[100:101], v[106:107], s[34:35], v[162:163] op_sel_hi:[1,0,1]
	s_nop 0
	v_max3_f32 v106, v102, v100, v101
	s_waitcnt lgkmcnt(0)
	v_pk_fma_f32 v[102:103], v[108:109], s[34:35], v[168:169] op_sel_hi:[1,0,1]
	s_nop 0
	v_max3_f32 v108, v106, v102, v103
	v_pk_fma_f32 v[106:107], v[110:111], s[34:35], v[170:171] op_sel_hi:[1,0,1]
	s_nop 0
	v_max3_f32 v108, v108, v106, v107
	v_mov_b32_e32 v109, v108
	s_nop 1
	v_permlane32_swap_b32_e32 v108, v109
	v_max_f32_e32 v108, v108, v109
	v_max_f32_e32 v174, v198, v108
	v_add_f32_e32 v109, 0x41000000, v198
	v_cmp_gt_f32_e32 vcc, v174, v109
	s_cbranch_vccz .LBB0_436
	v_sub_f32_e32 v109, v198, v174
	v_exp_f32_e32 v110, v109
	s_nop 0
	v_mul_f32_e32 v188, v188, v110
	v_pk_mul_f32 v[78:79], v[78:79], v[110:111] op_sel_hi:[1,0]
	v_pk_mul_f32 v[76:77], v[76:77], v[110:111] op_sel_hi:[1,0]
	v_pk_mul_f32 v[74:75], v[74:75], v[110:111] op_sel_hi:[1,0]
	v_pk_mul_f32 v[72:73], v[72:73], v[110:111] op_sel_hi:[1,0]
	v_pk_mul_f32 v[70:71], v[70:71], v[110:111] op_sel_hi:[1,0]
	v_pk_mul_f32 v[68:69], v[68:69], v[110:111] op_sel_hi:[1,0]
	v_pk_mul_f32 v[66:67], v[66:67], v[110:111] op_sel_hi:[1,0]
	v_pk_mul_f32 v[64:65], v[64:65], v[110:111] op_sel_hi:[1,0]
	v_pk_mul_f32 v[30:31], v[30:31], v[110:111] op_sel_hi:[1,0]
	v_pk_mul_f32 v[28:29], v[28:29], v[110:111] op_sel_hi:[1,0]
	v_pk_mul_f32 v[26:27], v[26:27], v[110:111] op_sel_hi:[1,0]
	v_pk_mul_f32 v[24:25], v[24:25], v[110:111] op_sel_hi:[1,0]
	v_pk_mul_f32 v[22:23], v[22:23], v[110:111] op_sel_hi:[1,0]
	v_pk_mul_f32 v[20:21], v[20:21], v[110:111] op_sel_hi:[1,0]
	v_pk_mul_f32 v[18:19], v[18:19], v[110:111] op_sel_hi:[1,0]
	v_pk_mul_f32 v[16:17], v[16:17], v[110:111] op_sel_hi:[1,0]
	s_branch .LBB0_437

; #define LAS __attribute__((address_space(3)))
; __device__ __forceinline__ float fast_exp2(float x) { return __builtin_amdgcn_exp2f(x); }
; __device__ __forceinline__ float xmax(float a) { auto rr = __builtin_amdgcn_permlane32_swap(__float_as_uint(a), __float_as_uint(a), false, false); return fmaxf(__uint_as_float(rr[0]), __uint_as_float(rr[1])); }
; template <int MODE, int NQ>
; __device__ __forceinline__ void attn_unit(LAS unsigned char* lds, const Params& P, int layer, int b, int h, int qb) {
;     ...
;             for (int cc = 0; cc < NC; ++cc) {
;                 f32x16& s0 = sc[cc];
;                 float mn;
;                 if (MODE != 0) {
;                     const LAS f32x4* tp4 = (const LAS f32x4*)(tlane + (kt * 64 + hf * 32) * 4);
;                     float rm = -3e38f;
; #pragma unroll
;                     for (int g = 0; g < 4; ++g) { const f32x4 t4 = tp4[2 * g];
; #pragma unroll
;                         for (int i = 0; i < 4; ++i) { s0[4 * g + i] = s0[4 * g + i] * c + t4[i]; rm = fmaxf(rm, s0[4 * g + i]); } }
;                     rm = xmax(rm);
;                     mn = fmaxf(mrun[cc], rm);
;                     rmrel[cc] = rm;
;                 } else {
;                     float rm = -3e38f;
; #pragma unroll
;                     for (int r = 0; r < 16; ++r) rm = fmaxf(rm, s0[r]);
;                     rm = xmax(rm);
;                     mn = fmaxf(mrun[cc], rm * c);
;                 }
;                 if (__any(mn > mrun[cc] + AT_THR)) {
;                     const float al = fast_exp2(mrun[cc] - mn); lrun[cc] *= al;
; #pragma unroll
;                     for (int r = 0; r < 16; ++r) { o[cc][0][r] *= al; o[cc][1][r] *= al; }
;                     mrun[cc] = mn;
;                 }
;                 mn = mrun[cc];
;                 if (MODE != 0) rmrel[cc] -= mn;
;                 const bool dead = (MODE != 0) && __all(rmrel[cc] < -136.f);
.LBB0_440:
	v_fmamk_f32 v99, v80, 0x3e8293ee, v152
	v_fmamk_f32 v96, v81, 0x3e8293ee, v153
	v_max3_f32 v14, v99, s68, v96
	v_fmamk_f32 v97, v82, 0x3e8293ee, v154
	v_fmac_f32_e32 v155, 0x3e8293ee, v83
	v_max3_f32 v14, v14, v97, v155
	v_fmamk_f32 v98, v84, 0x3e8293ee, v148
	v_fmamk_f32 v83, v85, 0x3e8293ee, v149
	v_max3_f32 v14, v14, v98, v83
	v_fmamk_f32 v84, v86, 0x3e8293ee, v150
	v_fmac_f32_e32 v151, 0x3e8293ee, v87
	v_max3_f32 v14, v14, v84, v151
	v_fmamk_f32 v85, v88, 0x3e8293ee, v160
	v_fmamk_f32 v80, v89, 0x3e8293ee, v161
	v_max3_f32 v14, v14, v85, v80
	v_fmamk_f32 v81, v90, 0x3e8293ee, v162
	v_fmac_f32_e32 v163, 0x3e8293ee, v91
	v_max3_f32 v15, v14, v81, v163
	v_fmamk_f32 v82, v92, 0x3e8293ee, v168
	v_fmamk_f32 v14, v93, 0x3e8293ee, v169
	v_max3_f32 v86, v15, v82, v14
	v_fmamk_f32 v15, v94, 0x3e8293ee, v170
	v_fmac_f32_e32 v171, 0x3e8293ee, v95
	v_max3_f32 v86, v86, v15, v171
	v_mov_b32_e32 v87, v86
	s_nop 1
	v_permlane32_swap_b32_e32 v86, v87
	v_max_f32_e32 v86, v86, v87
	v_max_f32_e32 v175, v197, v86
	v_add_f32_e32 v87, 0x41000000, v197
	v_cmp_gt_f32_e32 vcc, v175, v87
	s_cbranch_vccz .LBB0_443
	v_sub_f32_e32 v87, v197, v175
	v_exp_f32_e32 v88, v87
	s_nop 0
	v_mul_f32_e32 v187, v187, v88
	v_pk_mul_f32 v[62:63], v[62:63], v[88:89] op_sel_hi:[1,0]
	v_pk_mul_f32 v[60:61], v[60:61], v[88:89] op_sel_hi:[1,0]
	v_pk_mul_f32 v[58:59], v[58:59], v[88:89] op_sel_hi:[1,0]
	v_pk_mul_f32 v[56:57], v[56:57], v[88:89] op_sel_hi:[1,0]
	v_pk_mul_f32 v[54:55], v[54:55], v[88:89] op_sel_hi:[1,0]
	v_pk_mul_f32 v[52:53], v[52:53], v[88:89] op_sel_hi:[1,0]
	v_pk_mul_f32 v[50:51], v[50:51], v[88:89] op_sel_hi:[1,0]
	v_pk_mul_f32 v[48:49], v[48:49], v[88:89] op_sel_hi:[1,0]
	v_pk_mul_f32 v[46:47], v[46:47], v[88:89] op_sel_hi:[1,0]
	v_pk_mul_f32 v[44:45], v[44:45], v[88:89] op_sel_hi:[1,0]
	v_pk_mul_f32 v[42:43], v[42:43], v[88:89] op_sel_hi:[1,0]
	v_pk_mul_f32 v[40:41], v[40:41], v[88:89] op_sel_hi:[1,0]
	v_pk_mul_f32 v[38:39], v[38:39], v[88:89] op_sel_hi:[1,0]
	v_pk_mul_f32 v[36:37], v[36:37], v[88:89] op_sel_hi:[1,0]
	v_pk_mul_f32 v[34:35], v[34:35], v[88:89] op_sel_hi:[1,0]
	v_pk_mul_f32 v[32:33], v[32:33], v[88:89] op_sel_hi:[1,0]
	v_sub_f32_e32 v86, v86, v175
	v_cmp_gt_f32_e32 vcc, s30, v86
	s_cmp_eq_u64 vcc, exec
	s_cbranch_scc1 .LBB0_444

; #define LAS __attribute__((address_space(3)))
; __device__ __forceinline__ float fast_exp2(float x) { return __builtin_amdgcn_exp2f(x); }
; template <int MODE, int NQ>
; __device__ __forceinline__ void attn_unit(LAS unsigned char* lds, const Params& P, int layer, int b, int h, int qb) {
;     ...
;         for (int hf = 0; hf < 2; ++hf) {
;             if (it + 2 < NT) { if (hf == 0) AT_GLOADK(AT_TILE(it + 2)); else AT_GLOADV(AT_TILE(it + 2)); }
;             f32x16 sc[NC];
; #pragma unroll
;             for (int cc = 0; cc < NC; ++cc) {
;                 sc[cc] = f32x16{};
; #pragma unroll
;                 for (int d0 = 0; d0 < ND0; ++d0) sc[cc] = __builtin_amdgcn_mfma_f32_32x32x16_bf16(kf[(cc % NMAP) * ND0 + d0], qf[cc][d0], sc[cc], 0, 0, 0);
;             }
;             __builtin_amdgcn_sched_barrier(0);
;             AT_VLOAD(cur, hf);
;             if (hf == 0) AT_KLOAD(cur, 1); else if (it + 1 < NT) AT_KLOAD(nxt, 0);
;             __builtin_amdgcn_sched_barrier(0);
;             bf16x8 pw[NC][2]; float rmrel[NC]; bool alive = false;
; #pragma unroll
;             for (int cc = 0; cc < NC; ++cc) {
;                 f32x16& s0 = sc[cc];
;                 float mn;
;                 if (MODE != 0) {
;                     const LAS f32x4* tp4 = (const LAS f32x4*)(tlane + (kt * 64 + hf * 32) * 4);
;                     float rm = -3e38f;
; #pragma unroll
;                     for (int g = 0; g < 4; ++g) { const f32x4 t4 = tp4[2 * g];
; #pragma unroll
;                         for (int i = 0; i < 4; ++i) { s0[4 * g + i] = s0[4 * g + i] * c + t4[i]; rm = fmaxf(rm, s0[4 * g + i]); } }
;                     rm = xmax(rm);
;                     mn = fmaxf(mrun[cc], rm);
;                     rmrel[cc] = rm;
;                 } else {
;                     float rm = -3e38f;
; #pragma unroll
;                     for (int r = 0; r < 16; ++r) rm = fmaxf(rm, s0[r]);
;                     rm = xmax(rm);
;                     mn = fmaxf(mrun[cc], rm * c);
;                 }
;                 if (__any(mn > mrun[cc] + AT_THR)) {
;                     const float al = fast_exp2(mrun[cc] - mn); lrun[cc] *= al;
; #pragma unroll
;                     for (int r = 0; r < 16; ++r) { o[cc][0][r] *= al; o[cc][1][r] *= al; }
;                     mrun[cc] = mn;
;                 }
.LBB0_446:
	v_mfma_f32_32x32x16_bf16 v[96:111], v[128:131], v[124:127], 0
	v_mfma_f32_32x32x16_bf16 v[80:95], v[10:13], v[120:123], 0
	v_mfma_f32_32x32x16_bf16 v[96:111], v[6:9], v[116:119], v[96:111]
	v_mfma_f32_32x32x16_bf16 v[80:95], v[2:5], v[112:115], v[80:95]
	ds_read_b64_tr_b16 v[144:145], v172 offset:14336
	ds_read_b64_tr_b16 v[146:147], v172 offset:14848
	ds_read_b64_tr_b16 v[140:141], v172 offset:15360
	ds_read_b64_tr_b16 v[142:143], v172 offset:15872
	ds_read_b64_tr_b16 v[136:137], v172 offset:18432
	ds_read_b64_tr_b16 v[138:139], v172 offset:18944
	ds_read_b64_tr_b16 v[132:133], v172 offset:19456
	ds_read_b64_tr_b16 v[134:135], v172 offset:19968
	v_add_u32_e32 v2, s14, v190
	ds_read_b128 v[128:131], v2
	ds_read_b128 v[10:13], v2 offset:2048
	ds_read_b128 v[6:9], v2 offset:4096
	ds_read_b128 v[2:5], v2 offset:6144
	ds_read_b128 v[152:155], v0 offset:61568
	ds_read_b128 v[148:151], v0 offset:61600
	ds_read_b128 v[160:163], v0 offset:61632
	ds_read_b128 v[168:171], v0 offset:61664
	s_waitcnt lgkmcnt(3)
	v_pk_fma_f32 v[156:157], v[96:97], s[34:35], v[152:153] op_sel_hi:[1,0,1]
	v_pk_fma_f32 v[98:99], v[98:99], s[34:35], v[154:155] op_sel_hi:[1,0,1]
	v_max3_f32 v96, v156, s68, v157
	s_waitcnt lgkmcnt(2)
	v_pk_fma_f32 v[14:15], v[100:101], s[34:35], v[148:149] op_sel_hi:[1,0,1]
	v_max3_f32 v96, v96, v98, v99
	v_max3_f32 v100, v96, v14, v15
	v_pk_fma_f32 v[96:97], v[102:103], s[34:35], v[150:151] op_sel_hi:[1,0,1]
	s_waitcnt lgkmcnt(1)
	v_pk_fma_f32 v[104:105], v[104:105], s[34:35], v[160:161] op_sel_hi:[1,0,1]
	v_max3_f32 v100, v100, v96, v97
	v_max3_f32 v0, v100, v104, v105
	v_pk_fma_f32 v[100:101], v[106:107], s[34:35], v[162:163] op_sel_hi:[1,0,1]
	s_waitcnt lgkmcnt(0)
	v_pk_fma_f32 v[102:103], v[108:109], s[34:35], v[168:169] op_sel_hi:[1,0,1]
	v_max3_f32 v0, v0, v100, v101
	v_max3_f32 v0, v0, v102, v103
	v_pk_fma_f32 v[106:107], v[110:111], s[34:35], v[170:171] op_sel_hi:[1,0,1]
	s_nop 0
	v_max3_f32 v0, v0, v106, v107
	v_mov_b32_e32 v108, v0
	s_nop 1
	v_permlane32_swap_b32_e32 v0, v108
	v_max_f32_e32 v0, v0, v108
	v_max_f32_e32 v173, v174, v0
	v_add_f32_e32 v108, 0x41000000, v174
	v_cmp_gt_f32_e32 vcc, v173, v108
	s_cbranch_vccz .LBB0_448
	v_sub_f32_e32 v108, v174, v173
	v_exp_f32_e32 v108, v108
	s_nop 0
	v_mul_f32_e32 v188, v188, v108
	v_pk_mul_f32 v[78:79], v[78:79], v[108:109] op_sel_hi:[1,0]
	v_pk_mul_f32 v[76:77], v[76:77], v[108:109] op_sel_hi:[1,0]
	v_pk_mul_f32 v[74:75], v[74:75], v[108:109] op_sel_hi:[1,0]
	v_pk_mul_f32 v[72:73], v[72:73], v[108:109] op_sel_hi:[1,0]
	v_pk_mul_f32 v[70:71], v[70:71], v[108:109] op_sel_hi:[1,0]
	v_pk_mul_f32 v[68:69], v[68:69], v[108:109] op_sel_hi:[1,0]
	v_pk_mul_f32 v[66:67], v[66:67], v[108:109] op_sel_hi:[1,0]
	v_pk_mul_f32 v[64:65], v[64:65], v[108:109] op_sel_hi:[1,0]
	v_pk_mul_f32 v[30:31], v[30:31], v[108:109] op_sel_hi:[1,0]
	v_pk_mul_f32 v[28:29], v[28:29], v[108:109] op_sel_hi:[1,0]
	v_pk_mul_f32 v[26:27], v[26:27], v[108:109] op_sel_hi:[1,0]
	v_pk_mul_f32 v[24:25], v[24:25], v[108:109] op_sel_hi:[1,0]
	v_pk_mul_f32 v[22:23], v[22:23], v[108:109] op_sel_hi:[1,0]
	v_pk_mul_f32 v[20:21], v[20:21], v[108:109] op_sel_hi:[1,0]
	v_pk_mul_f32 v[18:19], v[18:19], v[108:109] op_sel_hi:[1,0]
	v_pk_mul_f32 v[16:17], v[16:17], v[108:109] op_sel_hi:[1,0]
	s_branch .LBB0_449

; #define LAS __attribute__((address_space(3)))
; __device__ __forceinline__ float fast_exp2(float x) { return __builtin_amdgcn_exp2f(x); }
; __device__ __forceinline__ float xmax(float a) { auto rr = __builtin_amdgcn_permlane32_swap(__float_as_uint(a), __float_as_uint(a), false, false); return fmaxf(__uint_as_float(rr[0]), __uint_as_float(rr[1])); }
; template <int MODE, int NQ>
; __device__ __forceinline__ void attn_unit(LAS unsigned char* lds, const Params& P, int layer, int b, int h, int qb) {
;     ...
;             for (int cc = 0; cc < NC; ++cc) {
;                 f32x16& s0 = sc[cc];
;                 float mn;
;                 if (MODE != 0) {
;                     const LAS f32x4* tp4 = (const LAS f32x4*)(tlane + (kt * 64 + hf * 32) * 4);
;                     float rm = -3e38f;
; #pragma unroll
;                     for (int g = 0; g < 4; ++g) { const f32x4 t4 = tp4[2 * g];
; #pragma unroll
;                         for (int i = 0; i < 4; ++i) { s0[4 * g + i] = s0[4 * g + i] * c + t4[i]; rm = fmaxf(rm, s0[4 * g + i]); } }
;                     rm = xmax(rm);
;                     mn = fmaxf(mrun[cc], rm);
;                     rmrel[cc] = rm;
;                 } else {
;                     float rm = -3e38f;
; #pragma unroll
;                     for (int r = 0; r < 16; ++r) rm = fmaxf(rm, s0[r]);
;                     rm = xmax(rm);
;                     mn = fmaxf(mrun[cc], rm * c);
;                 }
;                 if (__any(mn > mrun[cc] + AT_THR)) {
;                     const float al = fast_exp2(mrun[cc] - mn); lrun[cc] *= al;
; #pragma unroll
;                     for (int r = 0; r < 16; ++r) { o[cc][0][r] *= al; o[cc][1][r] *= al; }
;                     mrun[cc] = mn;
;                 }
;                 mn = mrun[cc];
;                 if (MODE != 0) rmrel[cc] -= mn;
;                 const bool dead = (MODE != 0) && __all(rmrel[cc] < -136.f);
.LBB0_452:
	v_fmamk_f32 v99, v80, 0x3e8293ee, v152
	v_fmamk_f32 v96, v81, 0x3e8293ee, v153
	v_max3_f32 v0, v99, s68, v96
	v_fmamk_f32 v97, v82, 0x3e8293ee, v154
	v_fmac_f32_e32 v155, 0x3e8293ee, v83
	v_max3_f32 v0, v0, v97, v155
	v_fmamk_f32 v98, v84, 0x3e8293ee, v148
	v_fmamk_f32 v82, v85, 0x3e8293ee, v149
	v_max3_f32 v0, v0, v98, v82
	v_fmamk_f32 v83, v86, 0x3e8293ee, v150
	v_fmac_f32_e32 v151, 0x3e8293ee, v87
	v_max3_f32 v0, v0, v83, v151
	v_fmamk_f32 v84, v88, 0x3e8293ee, v160
	v_fmamk_f32 v15, v89, 0x3e8293ee, v161
	v_max3_f32 v0, v0, v84, v15
	v_fmamk_f32 v80, v90, 0x3e8293ee, v162
	v_fmac_f32_e32 v163, 0x3e8293ee, v91
	v_max3_f32 v14, v0, v80, v163
	v_fmamk_f32 v81, v92, 0x3e8293ee, v168
	v_fmamk_f32 v0, v93, 0x3e8293ee, v169
	v_max3_f32 v85, v14, v81, v0
	v_fmamk_f32 v14, v94, 0x3e8293ee, v170
	v_fmac_f32_e32 v171, 0x3e8293ee, v95
	v_max3_f32 v85, v85, v14, v171
	v_mov_b32_e32 v86, v85
	s_nop 1
	v_permlane32_swap_b32_e32 v85, v86
	v_max_f32_e32 v85, v85, v86
	v_max_f32_e32 v174, v175, v85
	v_add_f32_e32 v86, 0x41000000, v175
	v_cmp_gt_f32_e32 vcc, v174, v86
	s_cbranch_vccz .LBB0_455
	v_sub_f32_e32 v86, v175, v174
	v_exp_f32_e32 v86, v86
	s_nop 0
	v_mul_f32_e32 v187, v187, v86
	v_pk_mul_f32 v[62:63], v[62:63], v[86:87] op_sel_hi:[1,0]
	v_pk_mul_f32 v[60:61], v[60:61], v[86:87] op_sel_hi:[1,0]
	v_pk_mul_f32 v[58:59], v[58:59], v[86:87] op_sel_hi:[1,0]
	v_pk_mul_f32 v[56:57], v[56:57], v[86:87] op_sel_hi:[1,0]
	v_pk_mul_f32 v[54:55], v[54:55], v[86:87] op_sel_hi:[1,0]
	v_pk_mul_f32 v[52:53], v[52:53], v[86:87] op_sel_hi:[1,0]
	v_pk_mul_f32 v[50:51], v[50:51], v[86:87] op_sel_hi:[1,0]
	v_pk_mul_f32 v[48:49], v[48:49], v[86:87] op_sel_hi:[1,0]
	v_pk_mul_f32 v[46:47], v[46:47], v[86:87] op_sel_hi:[1,0]
	v_pk_mul_f32 v[44:45], v[44:45], v[86:87] op_sel_hi:[1,0]
	v_pk_mul_f32 v[42:43], v[42:43], v[86:87] op_sel_hi:[1,0]
	v_pk_mul_f32 v[40:41], v[40:41], v[86:87] op_sel_hi:[1,0]
	v_pk_mul_f32 v[38:39], v[38:39], v[86:87] op_sel_hi:[1,0]
	v_pk_mul_f32 v[36:37], v[36:37], v[86:87] op_sel_hi:[1,0]
	v_pk_mul_f32 v[34:35], v[34:35], v[86:87] op_sel_hi:[1,0]
	v_pk_mul_f32 v[32:33], v[32:33], v[86:87] op_sel_hi:[1,0]
	v_sub_f32_e32 v85, v85, v174
	v_cmp_gt_f32_e32 vcc, s30, v85
	s_cmp_eq_u64 vcc, exec
	s_cbranch_scc1 .LBB0_456

; #define LAS __attribute__((address_space(3)))
; template <int MODE, int NQ>
; __device__ __forceinline__ void attn_unit(LAS unsigned char* lds, const Params& P, int layer, int b, int h, int qb) {
;     ...
;     for (int it = 0; it < NT; ++it) {
;         const int kt = AT_TILE(it);
;         const int bnx = (bcur == 2) ? 0 : bcur + 1, bn2 = (bnx == 2) ? 0 : bnx + 1;
;         const LAS unsigned char* cur = lds + bcur * AT_BUF;
;         const LAS unsigned char* nxt = lds + bnx * AT_BUF;
; #pragma unroll
;         for (int hf = 0; hf < 2; ++hf) {
;             if (it + 2 < NT) { if (hf == 0) AT_GLOADK(AT_TILE(it + 2)); else AT_GLOADV(AT_TILE(it + 2)); }
;             f32x16 sc[NC];
; #pragma unroll
;             for (int cc = 0; cc < NC; ++cc) {
;                 sc[cc] = f32x16{};
; #pragma unroll
;                 for (int d0 = 0; d0 < ND0; ++d0) sc[cc] = __builtin_amdgcn_mfma_f32_32x32x16_bf16(kf[(cc % NMAP) * ND0 + d0], qf[cc][d0], sc[cc], 0, 0, 0);
;             }
;             __builtin_amdgcn_sched_barrier(0);
;             AT_VLOAD(cur, hf);
;             if (hf == 0) AT_KLOAD(cur, 1); else if (it + 1 < NT) AT_KLOAD(nxt, 0);
;             __builtin_amdgcn_sched_barrier(0);
;             bf16x8 pw[NC][2]; float rmrel[NC]; bool alive = false;
; #pragma unroll
;             for (int cc = 0; cc < NC; ++cc) {
;                 f32x16& s0 = sc[cc];
;                 float mn;
;                 if (MODE != 0) {
;                     const LAS f32x4* tp4 = (const LAS f32x4*)(tlane + (kt * 64 + hf * 32) * 4);
;                     float rm = -3e38f;
; #pragma unroll
;                     for (int g = 0; g < 4; ++g) { const f32x4 t4 = tp4[2 * g];
; #pragma unroll
;                         for (int i = 0; i < 4; ++i) { s0[4 * g + i] = s0[4 * g + i] * c + t4[i]; rm = fmaxf(rm, s0[4 * g + i]); } }
;                     rm = xmax(rm);
;                     mn = fmaxf(mrun[cc], rm);
;                     rmrel[cc] = rm;
;                 } else {
;                     float rm = -3e38f;
; #pragma unroll
;                     for (int r = 0; r < 16; ++r) rm = fmaxf(rm, s0[r]);
;                     rm = xmax(rm);
;                     mn = fmaxf(mrun[cc], rm * c);
;                 }
;                 if (__any(mn > mrun[cc] + AT_THR)) {
;                     const float al = fast_exp2(mrun[cc] - mn); lrun[cc] *= al;
; #pragma unroll
.LBB0_458:
	v_mfma_f32_32x32x16_bf16 v[96:111], v[128:131], v[124:127], 0
	s_addk_i32 s5, 0xff00
	s_and_b64 s[0:1], s[0:1], exec
	v_add3_u32 v0, 0, v193, v192
	s_cselect_b32 s0, 0x1f00, s5
	v_add_u32_e32 v172, v0, v189
	v_add_u32_e32 v0, s0, v191
	v_mfma_f32_32x32x16_bf16 v[80:95], v[6:9], v[120:123], 0
	s_barrier
	v_mfma_f32_32x32x16_bf16 v[96:111], v[10:13], v[116:119], v[96:111]
	v_mfma_f32_32x32x16_bf16 v[80:95], v[2:5], v[112:115], v[80:95]
	ds_read_b64_tr_b16 v[144:145], v172 offset:32768
	ds_read_b64_tr_b16 v[146:147], v172 offset:33280
	ds_read_b64_tr_b16 v[140:141], v172 offset:33792
	ds_read_b64_tr_b16 v[142:143], v172 offset:34304
	ds_read_b64_tr_b16 v[136:137], v172 offset:36864
	ds_read_b64_tr_b16 v[138:139], v172 offset:37376
	ds_read_b64_tr_b16 v[132:133], v172 offset:37888
	ds_read_b64_tr_b16 v[134:135], v172 offset:38400
	ds_read_b128 v[128:131], v190 offset:20992
	ds_read_b128 v[6:9], v190 offset:23040
	ds_read_b128 v[10:13], v190 offset:25088
	ds_read_b128 v[2:5], v190 offset:27136
	ds_read_b128 v[152:155], v0 offset:61440
	ds_read_b128 v[148:151], v0 offset:61472
	ds_read_b128 v[160:163], v0 offset:61504
	ds_read_b128 v[168:171], v0 offset:61536
	s_waitcnt lgkmcnt(3)
	v_pk_fma_f32 v[156:157], v[96:97], s[34:35], v[152:153] op_sel_hi:[1,0,1]
	v_pk_fma_f32 v[98:99], v[98:99], s[34:35], v[154:155] op_sel_hi:[1,0,1]
	v_max3_f32 v96, v156, s68, v157
	s_waitcnt lgkmcnt(2)
	v_pk_fma_f32 v[14:15], v[100:101], s[34:35], v[148:149] op_sel_hi:[1,0,1]
	v_max3_f32 v96, v96, v98, v99
	v_max3_f32 v100, v96, v14, v15
	v_pk_fma_f32 v[96:97], v[102:103], s[34:35], v[150:151] op_sel_hi:[1,0,1]
	s_waitcnt lgkmcnt(1)
	v_pk_fma_f32 v[104:105], v[104:105], s[34:35], v[160:161] op_sel_hi:[1,0,1]
	v_max3_f32 v100, v100, v96, v97
	v_max3_f32 v102, v100, v104, v105
	v_pk_fma_f32 v[100:101], v[106:107], s[34:35], v[162:163] op_sel_hi:[1,0,1]
	s_nop 0
	v_max3_f32 v106, v102, v100, v101
	s_waitcnt lgkmcnt(0)
	v_pk_fma_f32 v[102:103], v[108:109], s[34:35], v[168:169] op_sel_hi:[1,0,1]
	s_nop 0
	v_max3_f32 v108, v106, v102, v103
	v_pk_fma_f32 v[106:107], v[110:111], s[34:35], v[170:171] op_sel_hi:[1,0,1]
	s_nop 0
	v_max3_f32 v108, v108, v106, v107
	v_mov_b32_e32 v109, v108
	s_nop 1
	v_permlane32_swap_b32_e32 v108, v109
	v_max_f32_e32 v108, v108, v109
	v_max_f32_e32 v175, v173, v108
	v_add_f32_e32 v109, 0x41000000, v173
	v_cmp_gt_f32_e32 vcc, v175, v109
	s_cbranch_vccz .LBB0_460
	v_sub_f32_e32 v109, v173, v175
	v_exp_f32_e32 v110, v109
	s_nop 0
	v_mul_f32_e32 v188, v188, v110
	v_pk_mul_f32 v[78:79], v[78:79], v[110:111] op_sel_hi:[1,0]
	v_pk_mul_f32 v[76:77], v[76:77], v[110:111] op_sel_hi:[1,0]
	v_pk_mul_f32 v[74:75], v[74:75], v[110:111] op_sel_hi:[1,0]
	v_pk_mul_f32 v[72:73], v[72:73], v[110:111] op_sel_hi:[1,0]
	v_pk_mul_f32 v[70:71], v[70:71], v[110:111] op_sel_hi:[1,0]
	v_pk_mul_f32 v[68:69], v[68:69], v[110:111] op_sel_hi:[1,0]
	v_pk_mul_f32 v[66:67], v[66:67], v[110:111] op_sel_hi:[1,0]
	v_pk_mul_f32 v[64:65], v[64:65], v[110:111] op_sel_hi:[1,0]
	v_pk_mul_f32 v[30:31], v[30:31], v[110:111] op_sel_hi:[1,0]
	v_pk_mul_f32 v[28:29], v[28:29], v[110:111] op_sel_hi:[1,0]
	v_pk_mul_f32 v[26:27], v[26:27], v[110:111] op_sel_hi:[1,0]
	v_pk_mul_f32 v[24:25], v[24:25], v[110:111] op_sel_hi:[1,0]
	v_pk_mul_f32 v[22:23], v[22:23], v[110:111] op_sel_hi:[1,0]
	v_pk_mul_f32 v[20:21], v[20:21], v[110:111] op_sel_hi:[1,0]
	v_pk_mul_f32 v[18:19], v[18:19], v[110:111] op_sel_hi:[1,0]
	v_pk_mul_f32 v[16:17], v[16:17], v[110:111] op_sel_hi:[1,0]
	s_branch .LBB0_461

; #define LAS __attribute__((address_space(3)))
; __device__ __forceinline__ float fast_exp2(float x) { return __builtin_amdgcn_exp2f(x); }
; __device__ __forceinline__ float xmax(float a) { auto rr = __builtin_amdgcn_permlane32_swap(__float_as_uint(a), __float_as_uint(a), false, false); return fmaxf(__uint_as_float(rr[0]), __uint_as_float(rr[1])); }
; template <int MODE, int NQ>
; __device__ __forceinline__ void attn_unit(LAS unsigned char* lds, const Params& P, int layer, int b, int h, int qb) {
;     ...
;             for (int cc = 0; cc < NC; ++cc) {
;                 f32x16& s0 = sc[cc];
;                 float mn;
;                 if (MODE != 0) {
;                     const LAS f32x4* tp4 = (const LAS f32x4*)(tlane + (kt * 64 + hf * 32) * 4);
;                     float rm = -3e38f;
; #pragma unroll
;                     for (int g = 0; g < 4; ++g) { const f32x4 t4 = tp4[2 * g];
; #pragma unroll
;                         for (int i = 0; i < 4; ++i) { s0[4 * g + i] = s0[4 * g + i] * c + t4[i]; rm = fmaxf(rm, s0[4 * g + i]); } }
;                     rm = xmax(rm);
;                     mn = fmaxf(mrun[cc], rm);
;                     rmrel[cc] = rm;
;                 } else {
;                     float rm = -3e38f;
; #pragma unroll
;                     for (int r = 0; r < 16; ++r) rm = fmaxf(rm, s0[r]);
;                     rm = xmax(rm);
;                     mn = fmaxf(mrun[cc], rm * c);
;                 }
;                 if (__any(mn > mrun[cc] + AT_THR)) {
;                     const float al = fast_exp2(mrun[cc] - mn); lrun[cc] *= al;
; #pragma unroll
;                     for (int r = 0; r < 16; ++r) { o[cc][0][r] *= al; o[cc][1][r] *= al; }
;                     mrun[cc] = mn;
;                 }
;                 mn = mrun[cc];
;                 if (MODE != 0) rmrel[cc] -= mn;
;                 const bool dead = (MODE != 0) && __all(rmrel[cc] < -136.f);
.LBB0_464:
	v_fmamk_f32 v99, v80, 0x3e8293ee, v152
	v_fmamk_f32 v96, v81, 0x3e8293ee, v153
	v_max3_f32 v14, v99, s68, v96
	v_fmamk_f32 v97, v82, 0x3e8293ee, v154
	v_fmac_f32_e32 v155, 0x3e8293ee, v83
	v_max3_f32 v14, v14, v97, v155
	v_fmamk_f32 v98, v84, 0x3e8293ee, v148
	v_fmamk_f32 v83, v85, 0x3e8293ee, v149
	v_max3_f32 v14, v14, v98, v83
	v_fmamk_f32 v84, v86, 0x3e8293ee, v150
	v_fmac_f32_e32 v151, 0x3e8293ee, v87
	v_max3_f32 v14, v14, v84, v151
	v_fmamk_f32 v85, v88, 0x3e8293ee, v160
	v_fmamk_f32 v80, v89, 0x3e8293ee, v161
	v_max3_f32 v14, v14, v85, v80
	v_fmamk_f32 v81, v90, 0x3e8293ee, v162
	v_fmac_f32_e32 v163, 0x3e8293ee, v91
	v_max3_f32 v15, v14, v81, v163
	v_fmamk_f32 v82, v92, 0x3e8293ee, v168
	v_fmamk_f32 v14, v93, 0x3e8293ee, v169
	v_max3_f32 v86, v15, v82, v14
	v_fmamk_f32 v15, v94, 0x3e8293ee, v170
	v_fmac_f32_e32 v171, 0x3e8293ee, v95
	v_max3_f32 v86, v86, v15, v171
	v_mov_b32_e32 v87, v86
	s_nop 1
	v_permlane32_swap_b32_e32 v86, v87
	v_max_f32_e32 v86, v86, v87
	v_max_f32_e32 v148, v174, v86
	v_add_f32_e32 v87, 0x41000000, v174
	v_cmp_gt_f32_e32 vcc, v148, v87
	s_cbranch_vccz .LBB0_467
	v_sub_f32_e32 v87, v174, v148
	v_exp_f32_e32 v88, v87
	s_nop 0
	v_mul_f32_e32 v187, v187, v88
	v_pk_mul_f32 v[62:63], v[62:63], v[88:89] op_sel_hi:[1,0]
	v_pk_mul_f32 v[60:61], v[60:61], v[88:89] op_sel_hi:[1,0]
	v_pk_mul_f32 v[58:59], v[58:59], v[88:89] op_sel_hi:[1,0]
	v_pk_mul_f32 v[56:57], v[56:57], v[88:89] op_sel_hi:[1,0]
	v_pk_mul_f32 v[54:55], v[54:55], v[88:89] op_sel_hi:[1,0]
	v_pk_mul_f32 v[52:53], v[52:53], v[88:89] op_sel_hi:[1,0]
	v_pk_mul_f32 v[50:51], v[50:51], v[88:89] op_sel_hi:[1,0]
	v_pk_mul_f32 v[48:49], v[48:49], v[88:89] op_sel_hi:[1,0]
	v_pk_mul_f32 v[46:47], v[46:47], v[88:89] op_sel_hi:[1,0]
	v_pk_mul_f32 v[44:45], v[44:45], v[88:89] op_sel_hi:[1,0]
	v_pk_mul_f32 v[42:43], v[42:43], v[88:89] op_sel_hi:[1,0]
	v_pk_mul_f32 v[40:41], v[40:41], v[88:89] op_sel_hi:[1,0]
	v_pk_mul_f32 v[38:39], v[38:39], v[88:89] op_sel_hi:[1,0]
	v_pk_mul_f32 v[36:37], v[36:37], v[88:89] op_sel_hi:[1,0]
	v_pk_mul_f32 v[34:35], v[34:35], v[88:89] op_sel_hi:[1,0]
	v_pk_mul_f32 v[32:33], v[32:33], v[88:89] op_sel_hi:[1,0]
	v_sub_f32_e32 v86, v86, v148
	v_cmp_gt_f32_e32 vcc, s30, v86
	s_cmp_eq_u64 vcc, exec
	s_cbranch_scc1 .LBB0_468

; #define LAS __attribute__((address_space(3)))
; __device__ __forceinline__ float fast_exp2(float x) { return __builtin_amdgcn_exp2f(x); }
; template <int MODE, int NQ>
; __device__ __forceinline__ void attn_unit(LAS unsigned char* lds, const Params& P, int layer, int b, int h, int qb) {
;     ...
;         for (int hf = 0; hf < 2; ++hf) {
;             if (it + 2 < NT) { if (hf == 0) AT_GLOADK(AT_TILE(it + 2)); else AT_GLOADV(AT_TILE(it + 2)); }
;             f32x16 sc[NC];
; #pragma unroll
;             for (int cc = 0; cc < NC; ++cc) {
;                 sc[cc] = f32x16{};
; #pragma unroll
;                 for (int d0 = 0; d0 < ND0; ++d0) sc[cc] = __builtin_amdgcn_mfma_f32_32x32x16_bf16(kf[(cc % NMAP) * ND0 + d0], qf[cc][d0], sc[cc], 0, 0, 0);
;             }
;             __builtin_amdgcn_sched_barrier(0);
;             AT_VLOAD(cur, hf);
;             if (hf == 0) AT_KLOAD(cur, 1); else if (it + 1 < NT) AT_KLOAD(nxt, 0);
;             __builtin_amdgcn_sched_barrier(0);
;             bf16x8 pw[NC][2]; float rmrel[NC]; bool alive = false;
; #pragma unroll
;             for (int cc = 0; cc < NC; ++cc) {
;                 f32x16& s0 = sc[cc];
;                 float mn;
;                 if (MODE != 0) {
;                     const LAS f32x4* tp4 = (const LAS f32x4*)(tlane + (kt * 64 + hf * 32) * 4);
;                     float rm = -3e38f;
; #pragma unroll
;                     for (int g = 0; g < 4; ++g) { const f32x4 t4 = tp4[2 * g];
; #pragma unroll
;                         for (int i = 0; i < 4; ++i) { s0[4 * g + i] = s0[4 * g + i] * c + t4[i]; rm = fmaxf(rm, s0[4 * g + i]); } }
;                     rm = xmax(rm);
;                     mn = fmaxf(mrun[cc], rm);
;                     rmrel[cc] = rm;
;                 } else {
;                     float rm = -3e38f;
; #pragma unroll
;                     for (int r = 0; r < 16; ++r) rm = fmaxf(rm, s0[r]);
;                     rm = xmax(rm);
;                     mn = fmaxf(mrun[cc], rm * c);
;                 }
;                 if (__any(mn > mrun[cc] + AT_THR)) {
;                     const float al = fast_exp2(mrun[cc] - mn); lrun[cc] *= al;
; #pragma unroll
;                     for (int r = 0; r < 16; ++r) { o[cc][0][r] *= al; o[cc][1][r] *= al; }
;                     mrun[cc] = mn;
;                 }
.LBB0_470:
	v_mfma_f32_32x32x16_bf16 v[96:111], v[128:131], v[124:127], 0
	v_mfma_f32_32x32x16_bf16 v[80:95], v[10:13], v[120:123], 0
	v_mfma_f32_32x32x16_bf16 v[96:111], v[6:9], v[116:119], v[96:111]
	v_mfma_f32_32x32x16_bf16 v[80:95], v[2:5], v[112:115], v[80:95]
	ds_read_b64_tr_b16 v[112:113], v172 offset:34816
	ds_read_b64_tr_b16 v[114:115], v172 offset:35328
	ds_read_b64_tr_b16 v[10:11], v172 offset:35840
	ds_read_b64_tr_b16 v[12:13], v172 offset:36352
	ds_read_b64_tr_b16 v[6:7], v172 offset:38912
	ds_read_b64_tr_b16 v[8:9], v172 offset:39424
	ds_read_b64_tr_b16 v[2:3], v172 offset:39936
	ds_read_b64_tr_b16 v[4:5], v172 offset:40448
	ds_read_b128 v[120:123], v0 offset:61568
	ds_read_b128 v[116:119], v0 offset:61600
	ds_read_b128 v[128:131], v0 offset:61632
	ds_read_b128 v[136:139], v0 offset:61664
	s_waitcnt lgkmcnt(3)
	v_pk_fma_f32 v[124:125], v[96:97], s[34:35], v[120:121] op_sel_hi:[1,0,1]
	v_pk_fma_f32 v[98:99], v[98:99], s[34:35], v[122:123] op_sel_hi:[1,0,1]
	v_max3_f32 v96, v124, s68, v125
	s_waitcnt lgkmcnt(2)
	v_pk_fma_f32 v[14:15], v[100:101], s[34:35], v[116:117] op_sel_hi:[1,0,1]
	v_max3_f32 v96, v96, v98, v99
	v_max3_f32 v100, v96, v14, v15
	v_pk_fma_f32 v[96:97], v[102:103], s[34:35], v[118:119] op_sel_hi:[1,0,1]
	s_waitcnt lgkmcnt(1)
	v_pk_fma_f32 v[104:105], v[104:105], s[34:35], v[128:129] op_sel_hi:[1,0,1]
	v_max3_f32 v100, v100, v96, v97
	v_max3_f32 v0, v100, v104, v105
	v_pk_fma_f32 v[100:101], v[106:107], s[34:35], v[130:131] op_sel_hi:[1,0,1]
	s_waitcnt lgkmcnt(0)
	v_pk_fma_f32 v[102:103], v[108:109], s[34:35], v[136:137] op_sel_hi:[1,0,1]
	v_max3_f32 v0, v0, v100, v101
	v_max3_f32 v0, v0, v102, v103
	v_pk_fma_f32 v[106:107], v[110:111], s[34:35], v[138:139] op_sel_hi:[1,0,1]
	v_add_f32_e32 v109, 0x41000000, v175
	v_max3_f32 v0, v0, v106, v107
	v_mov_b32_e32 v108, v0
	s_nop 1
	v_permlane32_swap_b32_e32 v0, v108
	v_max_f32_e32 v108, v0, v108
	v_max_f32_e32 v0, v175, v175
	v_max_f32_e32 v0, v0, v108
	v_cmp_gt_f32_e32 vcc, v0, v109
	s_cbranch_vccz .LBB0_472
	v_sub_f32_e32 v109, v175, v0
	v_exp_f32_e32 v110, v109
	s_nop 0
	v_mul_f32_e32 v188, v188, v110
	v_pk_mul_f32 v[78:79], v[78:79], v[110:111] op_sel_hi:[1,0]
	v_pk_mul_f32 v[76:77], v[76:77], v[110:111] op_sel_hi:[1,0]
	v_pk_mul_f32 v[74:75], v[74:75], v[110:111] op_sel_hi:[1,0]
	v_pk_mul_f32 v[72:73], v[72:73], v[110:111] op_sel_hi:[1,0]
	v_pk_mul_f32 v[70:71], v[70:71], v[110:111] op_sel_hi:[1,0]
	v_pk_mul_f32 v[68:69], v[68:69], v[110:111] op_sel_hi:[1,0]
	v_pk_mul_f32 v[66:67], v[66:67], v[110:111] op_sel_hi:[1,0]
	v_pk_mul_f32 v[64:65], v[64:65], v[110:111] op_sel_hi:[1,0]
	v_pk_mul_f32 v[30:31], v[30:31], v[110:111] op_sel_hi:[1,0]
	v_pk_mul_f32 v[28:29], v[28:29], v[110:111] op_sel_hi:[1,0]
	v_pk_mul_f32 v[26:27], v[26:27], v[110:111] op_sel_hi:[1,0]
	v_pk_mul_f32 v[24:25], v[24:25], v[110:111] op_sel_hi:[1,0]
	v_pk_mul_f32 v[22:23], v[22:23], v[110:111] op_sel_hi:[1,0]
	v_pk_mul_f32 v[20:21], v[20:21], v[110:111] op_sel_hi:[1,0]
	v_pk_mul_f32 v[18:19], v[18:19], v[110:111] op_sel_hi:[1,0]
	v_pk_mul_f32 v[16:17], v[16:17], v[110:111] op_sel_hi:[1,0]
	s_branch .LBB0_473

; #define LAS __attribute__((address_space(3)))
; __device__ __forceinline__ float fast_exp2(float x) { return __builtin_amdgcn_exp2f(x); }
; __device__ __forceinline__ float xmax(float a) { auto rr = __builtin_amdgcn_permlane32_swap(__float_as_uint(a), __float_as_uint(a), false, false); return fmaxf(__uint_as_float(rr[0]), __uint_as_float(rr[1])); }
; template <int MODE, int NQ>
; __device__ __forceinline__ void attn_unit(LAS unsigned char* lds, const Params& P, int layer, int b, int h, int qb) {
;     ...
;             for (int cc = 0; cc < NC; ++cc) {
;                 f32x16& s0 = sc[cc];
;                 float mn;
;                 if (MODE != 0) {
;                     const LAS f32x4* tp4 = (const LAS f32x4*)(tlane + (kt * 64 + hf * 32) * 4);
;                     float rm = -3e38f;
; #pragma unroll
;                     for (int g = 0; g < 4; ++g) { const f32x4 t4 = tp4[2 * g];
; #pragma unroll
;                         for (int i = 0; i < 4; ++i) { s0[4 * g + i] = s0[4 * g + i] * c + t4[i]; rm = fmaxf(rm, s0[4 * g + i]); } }
;                     rm = xmax(rm);
;                     mn = fmaxf(mrun[cc], rm);
;                     rmrel[cc] = rm;
;                 } else {
;                     float rm = -3e38f;
; #pragma unroll
;                     for (int r = 0; r < 16; ++r) rm = fmaxf(rm, s0[r]);
;                     rm = xmax(rm);
;                     mn = fmaxf(mrun[cc], rm * c);
;                 }
;                 if (__any(mn > mrun[cc] + AT_THR)) {
;                     const float al = fast_exp2(mrun[cc] - mn); lrun[cc] *= al;
; #pragma unroll
;                     for (int r = 0; r < 16; ++r) { o[cc][0][r] *= al; o[cc][1][r] *= al; }
;                     mrun[cc] = mn;
;                 }
;                 mn = mrun[cc];
;                 if (MODE != 0) rmrel[cc] -= mn;
;                 const bool dead = (MODE != 0) && __all(rmrel[cc] < -136.f);
.LBB0_476:
	v_fmamk_f32 v99, v80, 0x3e8293ee, v120
	v_fmamk_f32 v96, v81, 0x3e8293ee, v121
	v_max3_f32 v0, v99, s68, v96
	v_fmamk_f32 v97, v82, 0x3e8293ee, v122
	v_fmac_f32_e32 v123, 0x3e8293ee, v83
	v_max3_f32 v0, v0, v97, v123
	v_fmamk_f32 v98, v84, 0x3e8293ee, v116
	v_fmamk_f32 v82, v85, 0x3e8293ee, v117
	v_max3_f32 v0, v0, v98, v82
	v_fmamk_f32 v83, v86, 0x3e8293ee, v118
	v_fmac_f32_e32 v119, 0x3e8293ee, v87
	v_max3_f32 v0, v0, v83, v119
	v_fmamk_f32 v84, v88, 0x3e8293ee, v128
	v_fmamk_f32 v15, v89, 0x3e8293ee, v129
	v_max3_f32 v0, v0, v84, v15
	v_fmamk_f32 v80, v90, 0x3e8293ee, v130
	v_fmac_f32_e32 v131, 0x3e8293ee, v91
	v_max3_f32 v14, v0, v80, v131
	v_fmamk_f32 v81, v92, 0x3e8293ee, v136
	v_fmamk_f32 v0, v93, 0x3e8293ee, v137
	v_max3_f32 v85, v14, v81, v0
	v_fmamk_f32 v14, v94, 0x3e8293ee, v138
	v_fmac_f32_e32 v139, 0x3e8293ee, v95
	v_max3_f32 v85, v85, v14, v139
	v_mov_b32_e32 v86, v85
	s_nop 1
	v_permlane32_swap_b32_e32 v85, v86
	v_max_f32_e32 v86, v85, v86
	v_max_f32_e32 v85, v148, v86
	v_add_f32_e32 v87, 0x41000000, v148
	v_cmp_gt_f32_e32 vcc, v85, v87
	s_cbranch_vccz .LBB0_479
	v_sub_f32_e32 v87, v148, v85
	v_exp_f32_e32 v88, v87
	s_nop 0
	v_mul_f32_e32 v187, v187, v88
	v_pk_mul_f32 v[62:63], v[62:63], v[88:89] op_sel_hi:[1,0]
	v_pk_mul_f32 v[60:61], v[60:61], v[88:89] op_sel_hi:[1,0]
	v_pk_mul_f32 v[58:59], v[58:59], v[88:89] op_sel_hi:[1,0]
	v_pk_mul_f32 v[56:57], v[56:57], v[88:89] op_sel_hi:[1,0]
	v_pk_mul_f32 v[54:55], v[54:55], v[88:89] op_sel_hi:[1,0]
	v_pk_mul_f32 v[52:53], v[52:53], v[88:89] op_sel_hi:[1,0]
	v_pk_mul_f32 v[50:51], v[50:51], v[88:89] op_sel_hi:[1,0]
	v_pk_mul_f32 v[48:49], v[48:49], v[88:89] op_sel_hi:[1,0]
	v_pk_mul_f32 v[46:47], v[46:47], v[88:89] op_sel_hi:[1,0]
	v_pk_mul_f32 v[44:45], v[44:45], v[88:89] op_sel_hi:[1,0]
	v_pk_mul_f32 v[42:43], v[42:43], v[88:89] op_sel_hi:[1,0]
	v_pk_mul_f32 v[40:41], v[40:41], v[88:89] op_sel_hi:[1,0]
	v_pk_mul_f32 v[38:39], v[38:39], v[88:89] op_sel_hi:[1,0]
	v_pk_mul_f32 v[36:37], v[36:37], v[88:89] op_sel_hi:[1,0]
	v_pk_mul_f32 v[34:35], v[34:35], v[88:89] op_sel_hi:[1,0]
	v_pk_mul_f32 v[32:33], v[32:33], v[88:89] op_sel_hi:[1,0]
	v_sub_f32_e32 v86, v86, v85
	v_cmp_gt_f32_e32 vcc, s30, v86
	s_cmp_eq_u64 vcc, exec
	s_cbranch_scc1 .LBB0_480

; #define LAS __attribute__((address_space(3)))
; template <int MODE, int NQ>
; __device__ __forceinline__ void attn_unit(LAS unsigned char* lds, const Params& P, int layer, int b, int h, int qb) {
;     ...
;     const int qpos0 = q0 + wave * (32 * NQ) + r32;
;     const int tb0_ = 4 * hi - qpos0 + 2047, ts_ = tb0_ & 3;
;     const LAS unsigned char* tlane = tabb + ts_ * AT_TABC + (tb0_ - ts_) * 4;
;     bf16x8 qf[NC][ND0];
; #pragma unroll
;     for (int jq = 0; jq < NQ; ++jq) {
;         const bf16_t* qrow = Qp + (rowbase + qpos0 + 32 * jq) * qpitch + hi * 8;
; #pragma unroll
;         for (int mp = 0; mp < NMAP; ++mp)
; #pragma unroll
;             for (int d0 = 0; d0 < ND0; ++d0) qf[jq * NMAP + mp][d0] = *(const bf16x8*)(qrow + mp * 32 + d0 * 16);
;     }
;     u32x4 kreg, kreg2 = (u32x4){0u, 0u, 0u, 0u}, vreg;
;     ...
;     float mrun[NC], lrun[NC]; f32x16 o[NC][2];
; #pragma unroll
;     for (int cc = 0; cc < NC; ++cc) { mrun[cc] = -1e20f; lrun[cc] = 0.f; o[cc][0] = f32x16{}; o[cc][1] = f32x16{}; }
;     constexpr int NK = NMAP * ND0;
;     const bf16x8 ones8 = (bf16x8){0x3F80, 0x3F80, 0x3F80, 0x3F80, 0x3F80, 0x3F80, 0x3F80, 0x3F80};
;     const bf16x8 zero8 = (bf16x8){0, 0, 0, 0, 0, 0, 0, 0};
;     bf16x8 kf[NK]; s16x4 vlo[4], vhi[4];
;     ...
;     const int vlane = ((lane >> 4) & 1) * 32 + (lane & 3) * 8 + (4 * hi + ((lane & 15) >> 2)) * 64;
.LBB0_501:
	v_lshlrev_b32_e32 v7, 2, v6
	v_sub_u32_e32 v4, v7, v4
	s_lshl_b32 s9, s9, 6
	v_add_u32_e32 v4, 0x7ff, v4
	v_lshlrev_b32_e32 v129, 3, v6
	v_lshlrev_b32_e32 v6, 1, v2
	v_lshrrev_b32_e32 v2, 2, v2
	v_and_b32_e32 v8, 3, v4
	v_and_or_b32 v2, v2, 3, v7
	s_add_u32 s14, s14, s22
	v_mul_u32_u24_e32 v8, 0x4040, v8
	v_lshlrev_b32_e32 v4, 2, v4
	v_lshlrev_b32_e32 v131, 6, v2
	v_mov_b32_e32 v2, s21
	s_addc_u32 s15, s15, s23
	v_and_b32_e32 v4, -16, v4
	v_or3_b32 v118, s0, v2, v5
	v_lshl_add_u64 v[120:121], s[14:15], 0, v[0:1]
	v_or_b32_e32 v122, s0, v3
	s_add_u32 s0, s10, s16
	v_lshl_add_u32 v0, s19, 10, v8
	v_readlane_b32 s10, v252, 25
	v_mov_b32_e32 v14, v1
	v_mov_b32_e32 v15, v1
	v_and_b32_e32 v130, 32, v6
	v_add3_u32 v133, v0, v4, s10
	v_mov_b32_e32 v0, v1
	v_mov_b32_e32 v2, v1
	v_mov_b32_e32 v3, v1
	v_mov_b32_e32 v4, v1
	v_mov_b32_e32 v5, v1
	v_mov_b32_e32 v6, v1
	v_mov_b32_e32 v7, v1
	v_mov_b32_e32 v8, v1
	v_mov_b32_e32 v9, v1
	v_mov_b32_e32 v10, v1
	v_mov_b32_e32 v11, v1
	v_mov_b32_e32 v12, v1
	v_mov_b32_e32 v13, v1
	v_mov_b64_e32 v[30:31], v[14:15]
	v_mov_b64_e32 v[46:47], v[14:15]
	s_mov_b32 s18, 2
	v_or3_b32 v119, s1, 0, 0
	v_mov_b32_e32 v123, s1
	s_addc_u32 s1, s11, s17
	s_mov_b32 s19, 0
	v_mov_b32_e32 v134, 0xe0ad78ec
	v_mov_b32_e32 v132, 0
	v_mov_b64_e32 v[28:29], v[12:13]
	v_mov_b64_e32 v[26:27], v[10:11]
	v_mov_b64_e32 v[24:25], v[8:9]
	v_mov_b64_e32 v[22:23], v[6:7]
	v_mov_b64_e32 v[20:21], v[4:5]
	v_mov_b64_e32 v[18:19], v[2:3]
	v_mov_b64_e32 v[16:17], v[0:1]
	v_mov_b64_e32 v[44:45], v[12:13]
	v_mov_b64_e32 v[42:43], v[10:11]
	v_mov_b64_e32 v[40:41], v[8:9]
	v_mov_b64_e32 v[38:39], v[6:7]
	v_mov_b64_e32 v[36:37], v[4:5]
	v_mov_b64_e32 v[34:35], v[2:3]
	v_mov_b64_e32 v[32:33], v[0:1]
	v_mov_b32_e32 v220, s60
	v_mov_b32_e32 v221, s60
	v_mov_b32_e32 v222, s60
	v_mov_b32_e32 v223, s60
	s_branch .LBB0_503

; #define LAS __attribute__((address_space(3)))
; __device__ __forceinline__ float fast_exp2(float x) { return __builtin_amdgcn_exp2f(x); }
; template <int MODE, int NQ>
; __device__ __forceinline__ void attn_unit(LAS unsigned char* lds, const Params& P, int layer, int b, int h, int qb) {
;     ...
;         for (int hf = 0; hf < 2; ++hf) {
;             if (it + 2 < NT) { if (hf == 0) AT_GLOADK(AT_TILE(it + 2)); else AT_GLOADV(AT_TILE(it + 2)); }
;             f32x16 sc[NC];
; #pragma unroll
;             for (int cc = 0; cc < NC; ++cc) {
;                 sc[cc] = f32x16{};
; #pragma unroll
;                 for (int d0 = 0; d0 < ND0; ++d0) sc[cc] = __builtin_amdgcn_mfma_f32_32x32x16_bf16(kf[(cc % NMAP) * ND0 + d0], qf[cc][d0], sc[cc], 0, 0, 0);
;             }
;             __builtin_amdgcn_sched_barrier(0);
;             AT_VLOAD(cur, hf);
;             if (hf == 0) AT_KLOAD(cur, 1); else if (it + 1 < NT) AT_KLOAD(nxt, 0);
;             __builtin_amdgcn_sched_barrier(0);
;             bf16x8 pw[NC][2]; float rmrel[NC]; bool alive = false;
; #pragma unroll
;             for (int cc = 0; cc < NC; ++cc) {
;                 f32x16& s0 = sc[cc];
;                 float mn;
;                 if (MODE != 0) {
;                     const LAS f32x4* tp4 = (const LAS f32x4*)(tlane + (kt * 64 + hf * 32) * 4);
;                     float rm = -3e38f;
; #pragma unroll
;                     for (int g = 0; g < 4; ++g) { const f32x4 t4 = tp4[2 * g];
; #pragma unroll
;                         for (int i = 0; i < 4; ++i) { s0[4 * g + i] = s0[4 * g + i] * c + t4[i]; rm = fmaxf(rm, s0[4 * g + i]); } }
;                     rm = xmax(rm);
;                     mn = fmaxf(mrun[cc], rm);
;                     rmrel[cc] = rm;
;                 } else {
;                     float rm = -3e38f;
; #pragma unroll
;                     for (int r = 0; r < 16; ++r) rm = fmaxf(rm, s0[r]);
;                     rm = xmax(rm);
;                     mn = fmaxf(mrun[cc], rm * c);
;                 }
;                 if (__any(mn > mrun[cc] + AT_THR)) {
;                     const float al = fast_exp2(mrun[cc] - mn); lrun[cc] *= al;
; #pragma unroll
;                     for (int r = 0; r < 16; ++r) { o[cc][0][r] *= al; o[cc][1][r] *= al; }
;                     mrun[cc] = mn;
;                 }
.LBB0_505:
	s_add_i32 s16, s16, -2
	s_cmp_ge_i32 s16, s6
	s_mul_i32 s17, s19, 0x5000
	s_cselect_b32 s16, s6, 0
	s_add_i32 s17, s17, 0
	v_add3_u32 v0, s17, v130, v131
	s_lshl_b32 s20, s16, 8
	s_waitcnt lgkmcnt(3)
	v_mfma_f32_32x32x16_bf16 v[48:63], v[96:99], v[64:67], 0
	v_add_u32_e32 v15, v0, v124
	ds_read_b64_tr_b16 v[2:3], v15 offset:12288
	ds_read_b64_tr_b16 v[4:5], v15 offset:12800
	ds_read_b64_tr_b16 v[6:7], v15 offset:13312
	ds_read_b64_tr_b16 v[8:9], v15 offset:13824
	ds_read_b64_tr_b16 v[10:11], v15 offset:16384
	ds_read_b64_tr_b16 v[12:13], v15 offset:16896
	ds_read_b64_tr_b16 v[104:105], v15 offset:17408
	ds_read_b64_tr_b16 v[106:107], v15 offset:17920
	v_add3_u32 v0, s17, v126, v127
	s_waitcnt lgkmcnt(10)
	v_mfma_f32_32x32x16_bf16 v[48:63], v[100:103], v[68:71], v[48:63]
	ds_read_b128 v[96:99], v0 offset:512
	ds_read_b128 v[100:103], v0 offset:2560
	s_waitcnt lgkmcnt(11)
	v_mfma_f32_32x32x16_bf16 v[48:63], v[92:95], v[72:75], v[48:63]
	s_waitcnt lgkmcnt(10)
	v_mfma_f32_32x32x16_bf16 v[48:63], v[88:91], v[76:79], v[48:63]
	ds_read_b128 v[92:95], v0 offset:4608
	ds_read_b128 v[88:91], v0 offset:6656
	v_subrev_u32_e32 v0, s20, v133
	ds_read_b128 v[112:115], v0
	ds_read_b128 v[108:111], v0 offset:32
	s_waitcnt lgkmcnt(1)
	s_nop 5
	v_fmamk_f32 v135, v48, 0x3e38aa3b, v112
	v_fmamk_f32 v14, v49, 0x3e38aa3b, v113
	v_fmamk_f32 v112, v50, 0x3e38aa3b, v114
	v_fmac_f32_e32 v115, 0x3e38aa3b, v51
	v_max3_f32 v48, v135, s68, v14
	v_max3_f32 v48, v48, v112, v115
	s_waitcnt lgkmcnt(0)
	v_fmamk_f32 v113, v52, 0x3e38aa3b, v108
	v_fmamk_f32 v108, v53, 0x3e38aa3b, v109
	v_max3_f32 v52, v48, v113, v108
	ds_read_b128 v[48:51], v0 offset:64
	v_fmamk_f32 v109, v54, 0x3e38aa3b, v110
	v_fmac_f32_e32 v111, 0x3e38aa3b, v55
	v_max3_f32 v114, v52, v109, v111
	ds_read_b128 v[52:55], v0 offset:96
	s_waitcnt lgkmcnt(1)
	v_fmamk_f32 v110, v56, 0x3e38aa3b, v48
	v_fmamk_f32 v56, v57, 0x3e38aa3b, v49
	v_max3_f32 v0, v114, v110, v56
	v_fmamk_f32 v57, v58, 0x3e38aa3b, v50
	v_fmac_f32_e32 v51, 0x3e38aa3b, v59
	v_max3_f32 v0, v0, v57, v51
	s_waitcnt lgkmcnt(0)
	v_fmamk_f32 v50, v60, 0x3e38aa3b, v52
	v_fmamk_f32 v48, v61, 0x3e38aa3b, v53
	v_max3_f32 v0, v0, v50, v48
	v_fmamk_f32 v49, v62, 0x3e38aa3b, v54
	v_fmac_f32_e32 v55, 0x3e38aa3b, v63
	v_max3_f32 v0, v0, v49, v55
	v_mov_b32_e32 v52, v0
	s_nop 1
	v_permlane32_swap_b32_e32 v0, v52
	v_max_f32_e32 v52, v0, v52
	v_max_f32_e32 v0, v134, v52
	v_add_f32_e32 v53, 0x41000000, v134
	v_cmp_gt_f32_e32 vcc, v0, v53
	s_cbranch_vccz .LBB0_507
	v_sub_f32_e32 v53, v134, v0
	v_exp_f32_e32 v54, v53
	s_nop 0
	v_pk_mul_f32 v[46:47], v[46:47], v[54:55] op_sel_hi:[1,0]
	v_pk_mul_f32 v[44:45], v[44:45], v[54:55] op_sel_hi:[1,0]
	v_pk_mul_f32 v[42:43], v[42:43], v[54:55] op_sel_hi:[1,0]
	v_pk_mul_f32 v[40:41], v[40:41], v[54:55] op_sel_hi:[1,0]
	v_pk_mul_f32 v[38:39], v[38:39], v[54:55] op_sel_hi:[1,0]
	v_pk_mul_f32 v[36:37], v[36:37], v[54:55] op_sel_hi:[1,0]
	v_pk_mul_f32 v[34:35], v[34:35], v[54:55] op_sel_hi:[1,0]
	v_pk_mul_f32 v[32:33], v[32:33], v[54:55] op_sel_hi:[1,0]
	v_pk_mul_f32 v[30:31], v[30:31], v[54:55] op_sel_hi:[1,0]
	v_pk_mul_f32 v[28:29], v[28:29], v[54:55] op_sel_hi:[1,0]
	v_pk_mul_f32 v[26:27], v[26:27], v[54:55] op_sel_hi:[1,0]
	v_pk_mul_f32 v[24:25], v[24:25], v[54:55] op_sel_hi:[1,0]
	v_pk_mul_f32 v[22:23], v[22:23], v[54:55] op_sel_hi:[1,0]
	v_pk_mul_f32 v[20:21], v[20:21], v[54:55] op_sel_hi:[1,0]
	v_pk_mul_f32 v[18:19], v[18:19], v[54:55] op_sel_hi:[1,0]
	v_pk_mul_f32 v[16:17], v[16:17], v[54:55] op_sel_hi:[1,0]
	v_mul_f32_e32 v132, v132, v54
	s_branch .LBB0_508

; __device__ __forceinline__ unsigned cvtpk(float lo, float hi) { f32x2 v = {lo, hi}; bf16x2_t b = __builtin_convertvector(v, bf16x2_t); return __builtin_bit_cast(unsigned, b); }
; __device__ __forceinline__ float fast_exp2(float x) { return __builtin_amdgcn_exp2f(x); }
; template <int MODE, int NQ>
; __device__ __forceinline__ void attn_unit(LAS unsigned char* lds, const Params& P, int layer, int b, int h, int qb) {
;     ...
;                 mn = mrun[cc];
;                 if (MODE != 0) rmrel[cc] -= mn;
;                 const bool dead = (MODE != 0) && __all(rmrel[cc] < -136.f);
;                 if (dead) { pw[cc][0] = zero8; pw[cc][1] = zero8; }
;                 else {
;                     alive = true;
;                     if (MODE != 0) {
; #pragma unroll
;                         for (int r = 0; r < 16; ++r) s0[r] = fast_exp2(s0[r] - mn);
;                     } else {
;                         const float nm = -mn;
; #pragma unroll
;                         for (int r = 0; r < 16; ++r) s0[r] = fast_exp2(__builtin_fmaf(s0[r], c, nm));
;                     }
;                     u32x4 w;
;                     w.x = cvtpk(s0[0], s0[1]); w.y = cvtpk(s0[2], s0[3]); w.z = cvtpk(s0[4], s0[5]); w.w = cvtpk(s0[6], s0[7]); pw[cc][0] = __builtin_bit_cast(bf16x8, w);
;                     w.x = cvtpk(s0[8], s0[9]); w.y = cvtpk(s0[10], s0[11]); w.z = cvtpk(s0[12], s0[13]); w.w = cvtpk(s0[14], s0[15]); pw[cc][1] = __builtin_bit_cast(bf16x8, w);
;                     f32x16 t = __builtin_amdgcn_mfma_f32_32x32x16_bf16(ones8, pw[cc][0], f32x16{}, 0, 0, 0);
;                     t = __builtin_amdgcn_mfma_f32_32x32x16_bf16(ones8, pw[cc][1], t, 0, 0, 0);
;                     lrun[cc] += t[0];
;                 }
.LBB0_508:
	v_sub_f32_e32 v52, v52, v0
	v_cmp_gt_f32_e32 vcc, s30, v52
	s_cmp_lg_u64 vcc, exec
	s_cselect_b64 s[16:17], -1, 0
	s_cmp_eq_u64 vcc, exec
	s_cbranch_scc1 .LBB0_510
	s_mov_b32 s62, s60
	s_mov_b32 s63, s60
	v_sub_f32_e32 v52, v135, v0
	v_sub_f32_e32 v14, v14, v0
	v_sub_f32_e32 v53, v112, v0
	v_sub_f32_e32 v54, v115, v0
	v_sub_f32_e32 v58, v113, v0
	v_sub_f32_e32 v59, v108, v0
	v_sub_f32_e32 v60, v109, v0
	v_sub_f32_e32 v61, v111, v0
	s_mov_b32 s61, s60
	v_exp_f32_e32 v52, v52
	v_exp_f32_e32 v14, v14
	v_exp_f32_e32 v53, v53
	v_exp_f32_e32 v54, v54
	v_exp_f32_e32 v58, v58
	v_exp_f32_e32 v59, v59
	v_exp_f32_e32 v60, v60
	v_exp_f32_e32 v61, v61
	v_sub_f32_e32 v62, v110, v0
	v_sub_f32_e32 v56, v56, v0
	v_sub_f32_e32 v57, v57, v0
	v_sub_f32_e32 v51, v51, v0
	v_sub_f32_e32 v50, v50, v0
	v_sub_f32_e32 v48, v48, v0
	v_sub_f32_e32 v49, v49, v0
	v_sub_f32_e32 v55, v55, v0
	v_exp_f32_e32 v62, v62
	v_exp_f32_e32 v56, v56
	v_exp_f32_e32 v57, v57
	v_exp_f32_e32 v51, v51
	v_exp_f32_e32 v50, v50
	v_exp_f32_e32 v48, v48
	v_exp_f32_e32 v49, v49
	v_exp_f32_e32 v55, v55
	v_cvt_pk_bf16_f32 v112, v52, v14
	v_cvt_pk_bf16_f32 v113, v53, v54
	v_cvt_pk_bf16_f32 v114, v58, v59
	v_cvt_pk_bf16_f32 v115, v60, v61
	v_cvt_pk_bf16_f32 v108, v62, v56
	v_cvt_pk_bf16_f32 v109, v57, v51
	v_cvt_pk_bf16_f32 v110, v50, v48
	v_cvt_pk_bf16_f32 v111, v49, v55
	v_mfma_f32_32x32x16_bf16 v[48:63], v[220:223], v[112:115], 0
	s_nop 0
	v_mfma_f32_32x32x16_bf16 v[48:63], v[220:223], v[108:111], v[48:63]
	s_nop 11
	v_add_f32_e32 v132, v132, v48
	s_andn2_b64 vcc, exec, s[16:17]
	s_cbranch_vccz .LBB0_511
	s_branch .LBB0_512

; #define LAS __attribute__((address_space(3)))
; __device__ __forceinline__ float fast_exp2(float x) { return __builtin_amdgcn_exp2f(x); }
; __device__ __forceinline__ float xmax(float a) { auto rr = __builtin_amdgcn_permlane32_swap(__float_as_uint(a), __float_as_uint(a), false, false); return fmaxf(__uint_as_float(rr[0]), __uint_as_float(rr[1])); }
; template <int MODE, int NQ>
; __device__ __forceinline__ void attn_unit(LAS unsigned char* lds, const Params& P, int layer, int b, int h, int qb) {
;     ...
;             for (int cc = 0; cc < NC; ++cc) {
;                 f32x16& s0 = sc[cc];
;                 float mn;
;                 if (MODE != 0) {
;                     const LAS f32x4* tp4 = (const LAS f32x4*)(tlane + (kt * 64 + hf * 32) * 4);
;                     float rm = -3e38f;
; #pragma unroll
;                     for (int g = 0; g < 4; ++g) { const f32x4 t4 = tp4[2 * g];
; #pragma unroll
;                         for (int i = 0; i < 4; ++i) { s0[4 * g + i] = s0[4 * g + i] * c + t4[i]; rm = fmaxf(rm, s0[4 * g + i]); } }
;                     rm = xmax(rm);
;                     mn = fmaxf(mrun[cc], rm);
;                     rmrel[cc] = rm;
;                 } else {
;                     float rm = -3e38f;
; #pragma unroll
;                     for (int r = 0; r < 16; ++r) rm = fmaxf(rm, s0[r]);
;                     rm = xmax(rm);
;                     mn = fmaxf(mrun[cc], rm * c);
;                 }
;                 if (__any(mn > mrun[cc] + AT_THR)) {
;                     const float al = fast_exp2(mrun[cc] - mn); lrun[cc] *= al;
; #pragma unroll
;                     for (int r = 0; r < 16; ++r) { o[cc][0][r] *= al; o[cc][1][r] *= al; }
;                     mrun[cc] = mn;
;                 }
;                 mn = mrun[cc];
;                 if (MODE != 0) rmrel[cc] -= mn;
;                 const bool dead = (MODE != 0) && __all(rmrel[cc] < -136.f);
.LBB0_516:
	s_sub_i32 s10, 0, s20
	v_add_u32_e32 v134, s10, v133
	ds_read_b128 v[112:115], v134 offset:128
	ds_read_b128 v[108:111], v134 offset:160
	s_waitcnt lgkmcnt(1)
	s_nop 5
	v_fmamk_f32 v135, v48, 0x3e38aa3b, v112
	v_fmamk_f32 v15, v49, 0x3e38aa3b, v113
	v_fmamk_f32 v112, v50, 0x3e38aa3b, v114
	v_fmac_f32_e32 v115, 0x3e38aa3b, v51
	v_max3_f32 v48, v135, s68, v15
	v_max3_f32 v48, v48, v112, v115
	s_waitcnt lgkmcnt(0)
	v_fmamk_f32 v113, v52, 0x3e38aa3b, v108
	v_fmamk_f32 v108, v53, 0x3e38aa3b, v109
	v_max3_f32 v52, v48, v113, v108
	ds_read_b128 v[48:51], v134 offset:192
	v_fmamk_f32 v109, v54, 0x3e38aa3b, v110
	v_fmac_f32_e32 v111, 0x3e38aa3b, v55
	v_max3_f32 v114, v52, v109, v111
	ds_read_b128 v[52:55], v134 offset:224
	s_waitcnt lgkmcnt(1)
	v_fmamk_f32 v110, v56, 0x3e38aa3b, v48
	v_fmamk_f32 v56, v57, 0x3e38aa3b, v49
	v_max3_f32 v48, v114, v110, v56
	v_fmamk_f32 v57, v58, 0x3e38aa3b, v50
	v_fmac_f32_e32 v51, 0x3e38aa3b, v59
	v_max3_f32 v49, v48, v57, v51
	s_waitcnt lgkmcnt(0)
	v_fmamk_f32 v50, v60, 0x3e38aa3b, v52
	v_fmamk_f32 v48, v61, 0x3e38aa3b, v53
	v_max3_f32 v52, v49, v50, v48
	v_fmamk_f32 v49, v62, 0x3e38aa3b, v54
	v_fmac_f32_e32 v55, 0x3e38aa3b, v63
	v_max3_f32 v52, v52, v49, v55
	v_mov_b32_e32 v53, v52
	s_nop 1
	v_permlane32_swap_b32_e32 v52, v53
	v_max_f32_e32 v52, v52, v53
	v_max_f32_e32 v134, v0, v52
	v_add_f32_e32 v53, 0x41000000, v0
	v_cmp_gt_f32_e32 vcc, v134, v53
	s_cbranch_vccz .LBB0_518
	v_sub_f32_e32 v0, v0, v134
	v_exp_f32_e32 v0, v0
	s_nop 0
	v_pk_mul_f32 v[46:47], v[46:47], v[0:1] op_sel_hi:[1,0]
	v_pk_mul_f32 v[44:45], v[44:45], v[0:1] op_sel_hi:[1,0]
	v_pk_mul_f32 v[42:43], v[42:43], v[0:1] op_sel_hi:[1,0]
	v_pk_mul_f32 v[40:41], v[40:41], v[0:1] op_sel_hi:[1,0]
	v_pk_mul_f32 v[38:39], v[38:39], v[0:1] op_sel_hi:[1,0]
	v_pk_mul_f32 v[36:37], v[36:37], v[0:1] op_sel_hi:[1,0]
	v_pk_mul_f32 v[34:35], v[34:35], v[0:1] op_sel_hi:[1,0]
	v_pk_mul_f32 v[32:33], v[32:33], v[0:1] op_sel_hi:[1,0]
	v_pk_mul_f32 v[30:31], v[30:31], v[0:1] op_sel_hi:[1,0]
	v_pk_mul_f32 v[28:29], v[28:29], v[0:1] op_sel_hi:[1,0]
	v_pk_mul_f32 v[26:27], v[26:27], v[0:1] op_sel_hi:[1,0]
	v_pk_mul_f32 v[24:25], v[24:25], v[0:1] op_sel_hi:[1,0]
	v_pk_mul_f32 v[22:23], v[22:23], v[0:1] op_sel_hi:[1,0]
	v_pk_mul_f32 v[20:21], v[20:21], v[0:1] op_sel_hi:[1,0]
	v_pk_mul_f32 v[18:19], v[18:19], v[0:1] op_sel_hi:[1,0]
	v_pk_mul_f32 v[16:17], v[16:17], v[0:1] op_sel_hi:[1,0]
	v_mul_f32_e32 v132, v132, v0
	s_branch .LBB0_519

; __device__ __forceinline__ unsigned cvtpk(float lo, float hi) { f32x2 v = {lo, hi}; bf16x2_t b = __builtin_convertvector(v, bf16x2_t); return __builtin_bit_cast(unsigned, b); }
; __device__ __forceinline__ float fast_exp2(float x) { return __builtin_amdgcn_exp2f(x); }
; template <int MODE, int NQ>
; __device__ __forceinline__ void attn_unit(LAS unsigned char* lds, const Params& P, int layer, int b, int h, int qb) {
;     ...
;                 mn = mrun[cc];
;                 if (MODE != 0) rmrel[cc] -= mn;
;                 const bool dead = (MODE != 0) && __all(rmrel[cc] < -136.f);
;                 if (dead) { pw[cc][0] = zero8; pw[cc][1] = zero8; }
;                 else {
;                     alive = true;
;                     if (MODE != 0) {
; #pragma unroll
;                         for (int r = 0; r < 16; ++r) s0[r] = fast_exp2(s0[r] - mn);
;                     } else {
;                         const float nm = -mn;
; #pragma unroll
;                         for (int r = 0; r < 16; ++r) s0[r] = fast_exp2(__builtin_fmaf(s0[r], c, nm));
;                     }
;                     u32x4 w;
;                     w.x = cvtpk(s0[0], s0[1]); w.y = cvtpk(s0[2], s0[3]); w.z = cvtpk(s0[4], s0[5]); w.w = cvtpk(s0[6], s0[7]); pw[cc][0] = __builtin_bit_cast(bf16x8, w);
;                     w.x = cvtpk(s0[8], s0[9]); w.y = cvtpk(s0[10], s0[11]); w.z = cvtpk(s0[12], s0[13]); w.w = cvtpk(s0[14], s0[15]); pw[cc][1] = __builtin_bit_cast(bf16x8, w);
;                     f32x16 t = __builtin_amdgcn_mfma_f32_32x32x16_bf16(ones8, pw[cc][0], f32x16{}, 0, 0, 0);
;                     t = __builtin_amdgcn_mfma_f32_32x32x16_bf16(ones8, pw[cc][1], t, 0, 0, 0);
;                     lrun[cc] += t[0];
;                 }
.LBB0_519:
	v_sub_f32_e32 v0, v52, v134
	v_cmp_gt_f32_e32 vcc, s30, v0
	s_cmp_lg_u64 vcc, exec
	s_cselect_b64 s[10:11], -1, 0
	s_cmp_eq_u64 vcc, exec
	s_cbranch_scc1 .LBB0_521
	s_mov_b32 s62, s60
	s_mov_b32 s63, s60
	v_sub_f32_e32 v0, v135, v134
	v_sub_f32_e32 v15, v15, v134
	v_sub_f32_e32 v52, v112, v134
	v_sub_f32_e32 v53, v115, v134
	v_sub_f32_e32 v54, v113, v134
	v_sub_f32_e32 v58, v108, v134
	v_sub_f32_e32 v59, v109, v134
	v_sub_f32_e32 v60, v111, v134
	s_mov_b32 s61, s60
	v_exp_f32_e32 v0, v0
	v_exp_f32_e32 v15, v15
	v_exp_f32_e32 v52, v52
	v_exp_f32_e32 v53, v53
	v_exp_f32_e32 v54, v54
	v_exp_f32_e32 v58, v58
	v_exp_f32_e32 v59, v59
	v_exp_f32_e32 v60, v60
	v_sub_f32_e32 v61, v110, v134
	v_sub_f32_e32 v56, v56, v134
	v_sub_f32_e32 v57, v57, v134
	v_sub_f32_e32 v51, v51, v134
	v_sub_f32_e32 v50, v50, v134
	v_sub_f32_e32 v48, v48, v134
	v_sub_f32_e32 v49, v49, v134
	v_sub_f32_e32 v55, v55, v134
	v_exp_f32_e32 v61, v61
	v_exp_f32_e32 v56, v56
	v_exp_f32_e32 v57, v57
	v_exp_f32_e32 v51, v51
	v_exp_f32_e32 v50, v50
	v_exp_f32_e32 v48, v48
	v_exp_f32_e32 v49, v49
	v_exp_f32_e32 v55, v55
	v_cvt_pk_bf16_f32 v112, v0, v15
	v_cvt_pk_bf16_f32 v113, v52, v53
	v_cvt_pk_bf16_f32 v114, v54, v58
	v_cvt_pk_bf16_f32 v115, v59, v60
	v_cvt_pk_bf16_f32 v108, v61, v56
	v_cvt_pk_bf16_f32 v109, v57, v51
	v_cvt_pk_bf16_f32 v110, v50, v48
	v_cvt_pk_bf16_f32 v111, v49, v55
	v_mfma_f32_32x32x16_bf16 v[48:63], v[220:223], v[112:115], 0
	s_nop 0
	v_mfma_f32_32x32x16_bf16 v[48:63], v[220:223], v[108:111], v[48:63]
	s_nop 11
	v_add_f32_e32 v132, v132, v48
	s_andn2_b64 vcc, exec, s[10:11]
	s_cbranch_vccz .LBB0_522
	s_branch .LBB0_523

; #define LAS __attribute__((address_space(3)))
; __device__ __forceinline__ float fast_exp2(float x) { return __builtin_amdgcn_exp2f(x); }
; template <int MODE, int NQ>
; __device__ __forceinline__ void attn_unit(LAS unsigned char* lds, const Params& P, int layer, int b, int h, int qb) {
;     ...
;         for (int hf = 0; hf < 2; ++hf) {
;             if (it + 2 < NT) { if (hf == 0) AT_GLOADK(AT_TILE(it + 2)); else AT_GLOADV(AT_TILE(it + 2)); }
;             f32x16 sc[NC];
; #pragma unroll
;             for (int cc = 0; cc < NC; ++cc) {
;                 sc[cc] = f32x16{};
; #pragma unroll
;                 for (int d0 = 0; d0 < ND0; ++d0) sc[cc] = __builtin_amdgcn_mfma_f32_32x32x16_bf16(kf[(cc % NMAP) * ND0 + d0], qf[cc][d0], sc[cc], 0, 0, 0);
;             }
;             __builtin_amdgcn_sched_barrier(0);
;             AT_VLOAD(cur, hf);
;             if (hf == 0) AT_KLOAD(cur, 1); else if (it + 1 < NT) AT_KLOAD(nxt, 0);
;             __builtin_amdgcn_sched_barrier(0);
;             bf16x8 pw[NC][2]; float rmrel[NC]; bool alive = false;
; #pragma unroll
;             for (int cc = 0; cc < NC; ++cc) {
;                 f32x16& s0 = sc[cc];
;                 float mn;
;                 if (MODE != 0) {
;                     const LAS f32x4* tp4 = (const LAS f32x4*)(tlane + (kt * 64 + hf * 32) * 4);
;                     float rm = -3e38f;
; #pragma unroll
;                     for (int g = 0; g < 4; ++g) { const f32x4 t4 = tp4[2 * g];
; #pragma unroll
;                         for (int i = 0; i < 4; ++i) { s0[4 * g + i] = s0[4 * g + i] * c + t4[i]; rm = fmaxf(rm, s0[4 * g + i]); } }
;                     rm = xmax(rm);
;                     mn = fmaxf(mrun[cc], rm);
;                     rmrel[cc] = rm;
;                 } else {
;                     float rm = -3e38f;
; #pragma unroll
;                     for (int r = 0; r < 16; ++r) rm = fmaxf(rm, s0[r]);
;                     rm = xmax(rm);
;                     mn = fmaxf(mrun[cc], rm * c);
;                 }
;                 if (__any(mn > mrun[cc] + AT_THR)) {
;                     const float al = fast_exp2(mrun[cc] - mn); lrun[cc] *= al;
; #pragma unroll
;                     for (int r = 0; r < 16; ++r) { o[cc][0][r] *= al; o[cc][1][r] *= al; }
;                     mrun[cc] = mn;
;                 }
.LBB0_593:
	s_waitcnt lgkmcnt(5)
	v_mfma_f32_32x32x16_bf16 v[96:111], v[188:191], v[160:163], 0
	s_mul_i32 s8, s7, 0x5000
	s_add_i32 s8, s8, 0
	v_add_u32_e32 v0, s8, v242
	v_add3_u32 v0, v0, v243, v244
	v_mfma_f32_32x32x16_bf16 v[80:95], v[188:191], v[156:159], 0
	s_waitcnt lgkmcnt(4)
	v_mfma_f32_32x32x16_bf16 v[96:111], v[184:187], v[140:143], v[96:111]
	v_mfma_f32_32x32x16_bf16 v[80:95], v[184:187], v[152:155], v[80:95]
	s_waitcnt lgkmcnt(3)
	v_mfma_f32_32x32x16_bf16 v[96:111], v[180:183], v[132:135], v[96:111]
	v_mfma_f32_32x32x16_bf16 v[80:95], v[180:183], v[148:151], v[80:95]
	s_waitcnt lgkmcnt(2)
	v_mfma_f32_32x32x16_bf16 v[96:111], v[176:179], v[128:131], v[96:111]
	v_mfma_f32_32x32x16_bf16 v[80:95], v[176:179], v[144:147], v[80:95]
	s_waitcnt lgkmcnt(1)
	v_mfma_f32_32x32x16_bf16 v[96:111], v[172:175], v[124:127], v[96:111]
	v_mfma_f32_32x32x16_bf16 v[80:95], v[172:175], v[136:139], v[80:95]
	s_waitcnt lgkmcnt(0)
	v_mfma_f32_32x32x16_bf16 v[96:111], v[168:171], v[120:123], v[96:111]
	v_mfma_f32_32x32x16_bf16 v[80:95], v[168:171], v[116:119], v[80:95]
	v_add_u32_e32 v15, v0, v233
	ds_read_b64_tr_b16 v[196:197], v15 offset:12288
	ds_read_b64_tr_b16 v[198:199], v15 offset:12800
	ds_read_b64_tr_b16 v[192:193], v15 offset:13312
	ds_read_b64_tr_b16 v[194:195], v15 offset:13824
	ds_read_b64_tr_b16 v[188:189], v15 offset:16384
	ds_read_b64_tr_b16 v[190:191], v15 offset:16896
	ds_read_b64_tr_b16 v[184:185], v15 offset:17408
	ds_read_b64_tr_b16 v[186:187], v15 offset:17920
	v_add3_u32 v0, s8, v247, v248
	ds_read_b128 v[180:183], v0 offset:512
	ds_read_b128 v[176:179], v0 offset:2560
	ds_read_b128 v[172:175], v0 offset:4608
	ds_read_b128 v[168:171], v0 offset:6656
	ds_read_b128 v[10:13], v0 offset:8704
	ds_read_b128 v[2:5], v0 offset:10752
	v_max3_f32 v0, v96, s68, v97
	v_max3_f32 v0, v0, v98, v99
	v_max3_f32 v0, v0, v100, v101
	v_max3_f32 v0, v0, v102, v103
	v_max3_f32 v0, v0, v104, v105
	v_max3_f32 v0, v0, v106, v107
	v_max3_f32 v0, v0, v108, v109
	v_max3_f32 v0, v0, v110, v111
	v_mov_b32_e32 v14, v0
	s_nop 1
	v_permlane32_swap_b32_e32 v0, v14
	v_max_f32_e32 v0, v0, v14
	v_mul_f32_e32 v0, 0x3e16c740, v0
	v_max_f32_e32 v0, v113, v0
	v_add_f32_e32 v14, 0x41000000, v113
	v_cmp_gt_f32_e32 vcc, v0, v14
	s_cbranch_vccz .LBB0_595
	v_sub_f32_e32 v14, v113, v0
	v_exp_f32_e32 v14, v14
	s_nop 0
	v_mul_f32_e32 v249, v249, v14
	v_pk_mul_f32 v[78:79], v[78:79], v[14:15] op_sel_hi:[1,0]
	v_pk_mul_f32 v[76:77], v[76:77], v[14:15] op_sel_hi:[1,0]
	v_pk_mul_f32 v[74:75], v[74:75], v[14:15] op_sel_hi:[1,0]
	v_pk_mul_f32 v[72:73], v[72:73], v[14:15] op_sel_hi:[1,0]
	v_pk_mul_f32 v[70:71], v[70:71], v[14:15] op_sel_hi:[1,0]
	v_pk_mul_f32 v[68:69], v[68:69], v[14:15] op_sel_hi:[1,0]
	v_pk_mul_f32 v[66:67], v[66:67], v[14:15] op_sel_hi:[1,0]
	v_pk_mul_f32 v[64:65], v[64:65], v[14:15] op_sel_hi:[1,0]
	v_pk_mul_f32 v[62:63], v[62:63], v[14:15] op_sel_hi:[1,0]
	v_pk_mul_f32 v[60:61], v[60:61], v[14:15] op_sel_hi:[1,0]
	v_pk_mul_f32 v[58:59], v[58:59], v[14:15] op_sel_hi:[1,0]
	v_pk_mul_f32 v[56:57], v[56:57], v[14:15] op_sel_hi:[1,0]
	v_pk_mul_f32 v[54:55], v[54:55], v[14:15] op_sel_hi:[1,0]
	v_pk_mul_f32 v[52:53], v[52:53], v[14:15] op_sel_hi:[1,0]
	v_pk_mul_f32 v[50:51], v[50:51], v[14:15] op_sel_hi:[1,0]
	v_pk_mul_f32 v[48:49], v[48:49], v[14:15] op_sel_hi:[1,0]
	s_branch .LBB0_596

; __device__ __forceinline__ unsigned cvtpk(float lo, float hi) { f32x2 v = {lo, hi}; bf16x2_t b = __builtin_convertvector(v, bf16x2_t); return __builtin_bit_cast(unsigned, b); }
; __device__ __forceinline__ float fast_exp2(float x) { return __builtin_amdgcn_exp2f(x); }
; template <int MODE, int NQ>
; __device__ __forceinline__ void attn_unit(LAS unsigned char* lds, const Params& P, int layer, int b, int h, int qb) {
;     ...
;                     float rm = -3e38f;
; #pragma unroll
;                     for (int r = 0; r < 16; ++r) rm = fmaxf(rm, s0[r]);
;                     rm = xmax(rm);
;                     mn = fmaxf(mrun[cc], rm * c);
;                 }
;                 if (__any(mn > mrun[cc] + AT_THR)) {
;                     const float al = fast_exp2(mrun[cc] - mn); lrun[cc] *= al;
; #pragma unroll
;                     for (int r = 0; r < 16; ++r) { o[cc][0][r] *= al; o[cc][1][r] *= al; }
;                     mrun[cc] = mn;
;                 }
;                 mn = mrun[cc];
;                 if (MODE != 0) rmrel[cc] -= mn;
;                 const bool dead = (MODE != 0) && __all(rmrel[cc] < -136.f);
;                 if (dead) { pw[cc][0] = zero8; pw[cc][1] = zero8; }
;                 else {
;                     alive = true;
;                     if (MODE != 0) {
; #pragma unroll
;                         for (int r = 0; r < 16; ++r) s0[r] = fast_exp2(s0[r] - mn);
;                     } else {
;                         const float nm = -mn;
; #pragma unroll
;                         for (int r = 0; r < 16; ++r) s0[r] = fast_exp2(__builtin_fmaf(s0[r], c, nm));
;                     }
;                     u32x4 w;
;                     w.x = cvtpk(s0[0], s0[1]); w.y = cvtpk(s0[2], s0[3]); w.z = cvtpk(s0[4], s0[5]); w.w = cvtpk(s0[6], s0[7]); pw[cc][0] = __builtin_bit_cast(bf16x8, w);
;                     w.x = cvtpk(s0[8], s0[9]); w.y = cvtpk(s0[10], s0[11]); w.z = cvtpk(s0[12], s0[13]); w.w = cvtpk(s0[14], s0[15]); pw[cc][1] = __builtin_bit_cast(bf16x8, w);
;                     f32x16 t = __builtin_amdgcn_mfma_f32_32x32x16_bf16(ones8, pw[cc][0], f32x16{}, 0, 0, 0);
;                     t = __builtin_amdgcn_mfma_f32_32x32x16_bf16(ones8, pw[cc][1], t, 0, 0, 0);
;                     lrun[cc] += t[0];
;                 }
.LBB0_596:
	s_mov_b32 s62, s60
	s_mov_b32 s63, s60
	v_fma_f32 v14, v96, s97, -v0
	v_fma_f32 v96, v97, s97, -v0
	v_fma_f32 v97, v98, s97, -v0
	v_fma_f32 v98, v99, s97, -v0
	v_fma_f32 v99, v100, s97, -v0
	v_fma_f32 v100, v101, s97, -v0
	v_fma_f32 v101, v102, s97, -v0
	v_fma_f32 v102, v103, s97, -v0
	s_mov_b32 s61, s60
	v_mov_b64_e32 v[222:223], s[62:63]
	v_exp_f32_e32 v14, v14
	v_exp_f32_e32 v96, v96
	v_exp_f32_e32 v97, v97
	v_exp_f32_e32 v98, v98
	v_exp_f32_e32 v99, v99
	v_exp_f32_e32 v100, v100
	v_exp_f32_e32 v101, v101
	v_exp_f32_e32 v102, v102
	v_fma_f32 v103, v104, s97, -v0
	v_fma_f32 v104, v105, s97, -v0
	v_fma_f32 v105, v106, s97, -v0
	v_fma_f32 v106, v107, s97, -v0
	v_fma_f32 v107, v108, s97, -v0
	v_fma_f32 v108, v109, s97, -v0
	v_fma_f32 v109, v110, s97, -v0
	v_fma_f32 v110, v111, s97, -v0
	v_mov_b64_e32 v[220:221], s[60:61]
	v_exp_f32_e32 v103, v103
	v_exp_f32_e32 v104, v104
	v_exp_f32_e32 v105, v105
	v_exp_f32_e32 v106, v106
	v_exp_f32_e32 v107, v107
	v_exp_f32_e32 v108, v108
	v_exp_f32_e32 v109, v109
	v_exp_f32_e32 v110, v110
	v_cvt_pk_bf16_f32 v204, v14, v96
	v_cvt_pk_bf16_f32 v205, v97, v98
	v_cvt_pk_bf16_f32 v206, v99, v100
	v_cvt_pk_bf16_f32 v207, v101, v102
	v_cvt_pk_bf16_f32 v200, v103, v104
	v_cvt_pk_bf16_f32 v201, v105, v106
	v_cvt_pk_bf16_f32 v202, v107, v108
	v_cvt_pk_bf16_f32 v203, v109, v110
	v_mfma_f32_32x32x16_bf16 v[96:111], v[220:223], v[204:207], 0
	v_max3_f32 v14, v80, s68, v81
	v_max3_f32 v14, v14, v82, v83
	v_max3_f32 v14, v14, v84, v85
	v_max3_f32 v14, v14, v86, v87
	v_max3_f32 v14, v14, v88, v89
	v_max3_f32 v14, v14, v90, v91
	v_max3_f32 v14, v14, v92, v93
	v_mfma_f32_32x32x16_bf16 v[96:111], v[220:223], v[200:203], v[96:111]
	v_max3_f32 v14, v14, v94, v95
	s_nop 10
	v_mov_b32_e32 v97, v14
	s_nop 1
	v_permlane32_swap_b32_e32 v14, v97
	v_max_f32_e32 v14, v14, v97
	v_mul_f32_e32 v14, 0x3e16c740, v14
	v_max_f32_e32 v14, v112, v14
	v_add_f32_e32 v97, 0x41000000, v112
	v_cmp_gt_f32_e32 vcc, v14, v97
	s_cbranch_vccz .LBB0_598
	v_sub_f32_e32 v97, v112, v14
	v_exp_f32_e32 v98, v97
	s_nop 0
	v_mul_f32_e32 v245, v245, v98
	v_pk_mul_f32 v[46:47], v[46:47], v[98:99] op_sel_hi:[1,0]
	v_pk_mul_f32 v[44:45], v[44:45], v[98:99] op_sel_hi:[1,0]
	v_pk_mul_f32 v[42:43], v[42:43], v[98:99] op_sel_hi:[1,0]
	v_pk_mul_f32 v[40:41], v[40:41], v[98:99] op_sel_hi:[1,0]
	v_pk_mul_f32 v[38:39], v[38:39], v[98:99] op_sel_hi:[1,0]
	v_pk_mul_f32 v[36:37], v[36:37], v[98:99] op_sel_hi:[1,0]
	v_pk_mul_f32 v[34:35], v[34:35], v[98:99] op_sel_hi:[1,0]
	v_pk_mul_f32 v[32:33], v[32:33], v[98:99] op_sel_hi:[1,0]
	v_pk_mul_f32 v[30:31], v[30:31], v[98:99] op_sel_hi:[1,0]
	v_pk_mul_f32 v[28:29], v[28:29], v[98:99] op_sel_hi:[1,0]
	v_pk_mul_f32 v[26:27], v[26:27], v[98:99] op_sel_hi:[1,0]
	v_pk_mul_f32 v[24:25], v[24:25], v[98:99] op_sel_hi:[1,0]
	v_pk_mul_f32 v[22:23], v[22:23], v[98:99] op_sel_hi:[1,0]
	v_pk_mul_f32 v[20:21], v[20:21], v[98:99] op_sel_hi:[1,0]
	v_pk_mul_f32 v[18:19], v[18:19], v[98:99] op_sel_hi:[1,0]
	v_pk_mul_f32 v[16:17], v[16:17], v[98:99] op_sel_hi:[1,0]
	s_branch .LBB0_599

; #define LAS __attribute__((address_space(3)))
; __device__ __forceinline__ float fast_exp2(float x) { return __builtin_amdgcn_exp2f(x); }
; template <int MODE, int NQ>
; __device__ __forceinline__ void attn_unit(LAS unsigned char* lds, const Params& P, int layer, int b, int h, int qb) {
;     ...
;         for (int hf = 0; hf < 2; ++hf) {
;             if (it + 2 < NT) { if (hf == 0) AT_GLOADK(AT_TILE(it + 2)); else AT_GLOADV(AT_TILE(it + 2)); }
;             f32x16 sc[NC];
; #pragma unroll
;             for (int cc = 0; cc < NC; ++cc) {
;                 sc[cc] = f32x16{};
; #pragma unroll
;                 for (int d0 = 0; d0 < ND0; ++d0) sc[cc] = __builtin_amdgcn_mfma_f32_32x32x16_bf16(kf[(cc % NMAP) * ND0 + d0], qf[cc][d0], sc[cc], 0, 0, 0);
;             }
;             __builtin_amdgcn_sched_barrier(0);
;             AT_VLOAD(cur, hf);
;             if (hf == 0) AT_KLOAD(cur, 1); else if (it + 1 < NT) AT_KLOAD(nxt, 0);
;             __builtin_amdgcn_sched_barrier(0);
;             bf16x8 pw[NC][2]; float rmrel[NC]; bool alive = false;
; #pragma unroll
;             for (int cc = 0; cc < NC; ++cc) {
;                 f32x16& s0 = sc[cc];
;                 float mn;
;                 if (MODE != 0) {
;                     const LAS f32x4* tp4 = (const LAS f32x4*)(tlane + (kt * 64 + hf * 32) * 4);
;                     float rm = -3e38f;
; #pragma unroll
;                     for (int g = 0; g < 4; ++g) { const f32x4 t4 = tp4[2 * g];
; #pragma unroll
;                         for (int i = 0; i < 4; ++i) { s0[4 * g + i] = s0[4 * g + i] * c + t4[i]; rm = fmaxf(rm, s0[4 * g + i]); } }
;                     rm = xmax(rm);
;                     mn = fmaxf(mrun[cc], rm);
;                     rmrel[cc] = rm;
;                 } else {
;                     float rm = -3e38f;
; #pragma unroll
;                     for (int r = 0; r < 16; ++r) rm = fmaxf(rm, s0[r]);
;                     rm = xmax(rm);
;                     mn = fmaxf(mrun[cc], rm * c);
;                 }
;                 if (__any(mn > mrun[cc] + AT_THR)) {
;                     const float al = fast_exp2(mrun[cc] - mn); lrun[cc] *= al;
; #pragma unroll
;                     for (int r = 0; r < 16; ++r) { o[cc][0][r] *= al; o[cc][1][r] *= al; }
;                     mrun[cc] = mn;
;                 }
.LBB0_601:
	v_lshl_add_u64 v[6:7], v[230:231], 0, s[0:1]
	global_load_dwordx4 v[6:9], v[6:7], off
	s_waitcnt lgkmcnt(6)
	v_mfma_f32_32x32x16_bf16 v[100:115], v[180:183], v[160:163], 0
	v_add_f32_e32 v205, v249, v96
	v_mfma_f32_32x32x16_bf16 v[80:95], v[180:183], v[156:159], 0
	s_waitcnt lgkmcnt(5)
	v_mfma_f32_32x32x16_bf16 v[100:115], v[176:179], v[140:143], v[100:115]
	v_mfma_f32_32x32x16_bf16 v[80:95], v[176:179], v[152:155], v[80:95]
	s_waitcnt lgkmcnt(4)
	v_mfma_f32_32x32x16_bf16 v[100:115], v[172:175], v[132:135], v[100:115]
	v_mfma_f32_32x32x16_bf16 v[80:95], v[172:175], v[148:151], v[80:95]
	s_waitcnt lgkmcnt(3)
	v_mfma_f32_32x32x16_bf16 v[100:115], v[168:171], v[128:131], v[100:115]
	v_mfma_f32_32x32x16_bf16 v[80:95], v[168:171], v[144:147], v[80:95]
	s_waitcnt lgkmcnt(2)
	v_mfma_f32_32x32x16_bf16 v[100:115], v[10:13], v[124:127], v[100:115]
	v_mfma_f32_32x32x16_bf16 v[80:95], v[10:13], v[136:139], v[80:95]
	s_waitcnt lgkmcnt(1)
	v_mfma_f32_32x32x16_bf16 v[100:115], v[2:5], v[120:123], v[100:115]
	v_mfma_f32_32x32x16_bf16 v[80:95], v[2:5], v[116:119], v[80:95]
	ds_read_b64_tr_b16 v[196:197], v15 offset:14336
	ds_read_b64_tr_b16 v[198:199], v15 offset:14848
	ds_read_b64_tr_b16 v[192:193], v15 offset:15360
	ds_read_b64_tr_b16 v[194:195], v15 offset:15872
	ds_read_b64_tr_b16 v[10:11], v15 offset:18432
	ds_read_b64_tr_b16 v[12:13], v15 offset:18944
	ds_read_b64_tr_b16 v[2:3], v15 offset:19456
	ds_read_b64_tr_b16 v[4:5], v15 offset:19968
	v_add_u32_e32 v15, s9, v241
	ds_read_b128 v[188:191], v15
	ds_read_b128 v[184:187], v15 offset:2048
	ds_read_b128 v[180:183], v15 offset:4096
	ds_read_b128 v[176:179], v15 offset:6144
	ds_read_b128 v[172:175], v15 offset:8192
	ds_read_b128 v[168:171], v15 offset:10240
	v_max3_f32 v15, v100, s68, v101
	v_max3_f32 v15, v15, v102, v103
	v_max3_f32 v15, v15, v104, v105
	v_max3_f32 v15, v15, v106, v107
	v_max3_f32 v15, v15, v108, v109
	v_max3_f32 v15, v15, v110, v111
	v_max3_f32 v15, v15, v112, v113
	v_max3_f32 v15, v15, v114, v115
	v_mov_b32_e32 v96, v15
	s_nop 1
	v_permlane32_swap_b32_e32 v15, v96
	v_max_f32_e32 v15, v15, v96
	v_mul_f32_e32 v15, 0x3e16c740, v15
	v_max_f32_e32 v15, v0, v15
	v_add_f32_e32 v96, 0x41000000, v0
	v_cmp_gt_f32_e32 vcc, v15, v96
	s_cbranch_vccz .LBB0_603
	v_sub_f32_e32 v0, v0, v15
	v_exp_f32_e32 v0, v0
	v_xor_b32_e32 v96, 0x80000000, v15
	v_mul_f32_e32 v205, v205, v0
	v_pk_mul_f32 v[78:79], v[78:79], v[0:1] op_sel_hi:[1,0]
	v_pk_mul_f32 v[76:77], v[76:77], v[0:1] op_sel_hi:[1,0]
	v_pk_mul_f32 v[74:75], v[74:75], v[0:1] op_sel_hi:[1,0]
	v_pk_mul_f32 v[72:73], v[72:73], v[0:1] op_sel_hi:[1,0]
	v_pk_mul_f32 v[70:71], v[70:71], v[0:1] op_sel_hi:[1,0]
	v_pk_mul_f32 v[68:69], v[68:69], v[0:1] op_sel_hi:[1,0]
	v_pk_mul_f32 v[66:67], v[66:67], v[0:1] op_sel_hi:[1,0]
	v_pk_mul_f32 v[64:65], v[64:65], v[0:1] op_sel_hi:[1,0]
	v_pk_mul_f32 v[62:63], v[62:63], v[0:1] op_sel_hi:[1,0]
	v_pk_mul_f32 v[60:61], v[60:61], v[0:1] op_sel_hi:[1,0]
	v_pk_mul_f32 v[58:59], v[58:59], v[0:1] op_sel_hi:[1,0]
	v_pk_mul_f32 v[56:57], v[56:57], v[0:1] op_sel_hi:[1,0]
	v_pk_mul_f32 v[54:55], v[54:55], v[0:1] op_sel_hi:[1,0]
	v_pk_mul_f32 v[52:53], v[52:53], v[0:1] op_sel_hi:[1,0]
	v_pk_mul_f32 v[50:51], v[50:51], v[0:1] op_sel_hi:[1,0]
	v_pk_mul_f32 v[48:49], v[48:49], v[0:1] op_sel_hi:[1,0]
	v_mov_b32_e32 v0, v15
	s_branch .LBB0_604

; __device__ __forceinline__ unsigned cvtpk(float lo, float hi) { f32x2 v = {lo, hi}; bf16x2_t b = __builtin_convertvector(v, bf16x2_t); return __builtin_bit_cast(unsigned, b); }
; __device__ __forceinline__ float fast_exp2(float x) { return __builtin_amdgcn_exp2f(x); }
; template <int MODE, int NQ>
; __device__ __forceinline__ void attn_unit(LAS unsigned char* lds, const Params& P, int layer, int b, int h, int qb) {
;     ...
;                     float rm = -3e38f;
; #pragma unroll
;                     for (int r = 0; r < 16; ++r) rm = fmaxf(rm, s0[r]);
;                     rm = xmax(rm);
;                     mn = fmaxf(mrun[cc], rm * c);
;                 }
;                 if (__any(mn > mrun[cc] + AT_THR)) {
;                     const float al = fast_exp2(mrun[cc] - mn); lrun[cc] *= al;
; #pragma unroll
;                     for (int r = 0; r < 16; ++r) { o[cc][0][r] *= al; o[cc][1][r] *= al; }
;                     mrun[cc] = mn;
;                 }
;                 mn = mrun[cc];
;                 if (MODE != 0) rmrel[cc] -= mn;
;                 const bool dead = (MODE != 0) && __all(rmrel[cc] < -136.f);
;                 if (dead) { pw[cc][0] = zero8; pw[cc][1] = zero8; }
;                 else {
;                     alive = true;
;                     if (MODE != 0) {
; #pragma unroll
;                         for (int r = 0; r < 16; ++r) s0[r] = fast_exp2(s0[r] - mn);
;                     } else {
;                         const float nm = -mn;
; #pragma unroll
;                         for (int r = 0; r < 16; ++r) s0[r] = fast_exp2(__builtin_fmaf(s0[r], c, nm));
;                     }
;                     u32x4 w;
;                     w.x = cvtpk(s0[0], s0[1]); w.y = cvtpk(s0[2], s0[3]); w.z = cvtpk(s0[4], s0[5]); w.w = cvtpk(s0[6], s0[7]); pw[cc][0] = __builtin_bit_cast(bf16x8, w);
;                     w.x = cvtpk(s0[8], s0[9]); w.y = cvtpk(s0[10], s0[11]); w.z = cvtpk(s0[12], s0[13]); w.w = cvtpk(s0[14], s0[15]); pw[cc][1] = __builtin_bit_cast(bf16x8, w);
;                     f32x16 t = __builtin_amdgcn_mfma_f32_32x32x16_bf16(ones8, pw[cc][0], f32x16{}, 0, 0, 0);
;                     t = __builtin_amdgcn_mfma_f32_32x32x16_bf16(ones8, pw[cc][1], t, 0, 0, 0);
;                     lrun[cc] += t[0];
;                 }
.LBB0_604:
	s_mov_b32 s62, s60
	s_mov_b32 s63, s60
	v_add_f32_e32 v15, v245, v98
	v_fmamk_f32 v97, v100, 0x3e16c740, v96
	v_fmamk_f32 v98, v101, 0x3e16c740, v96
	v_fmamk_f32 v99, v102, 0x3e16c740, v96
	v_fmamk_f32 v100, v103, 0x3e16c740, v96
	v_fmamk_f32 v101, v104, 0x3e16c740, v96
	v_fmamk_f32 v102, v105, 0x3e16c740, v96
	v_fmamk_f32 v103, v106, 0x3e16c740, v96
	v_fmamk_f32 v104, v107, 0x3e16c740, v96
	s_mov_b32 s61, s60
	v_mov_b64_e32 v[222:223], s[62:63]
	v_exp_f32_e32 v97, v97
	v_exp_f32_e32 v98, v98
	v_exp_f32_e32 v99, v99
	v_exp_f32_e32 v100, v100
	v_exp_f32_e32 v101, v101
	v_exp_f32_e32 v102, v102
	v_exp_f32_e32 v103, v103
	v_exp_f32_e32 v104, v104
	v_fmamk_f32 v105, v108, 0x3e16c740, v96
	v_fmamk_f32 v106, v109, 0x3e16c740, v96
	v_fmamk_f32 v107, v110, 0x3e16c740, v96
	v_fmamk_f32 v108, v111, 0x3e16c740, v96
	v_fmamk_f32 v109, v112, 0x3e16c740, v96
	v_fmamk_f32 v110, v113, 0x3e16c740, v96
	v_fmamk_f32 v111, v114, 0x3e16c740, v96
	v_fmac_f32_e32 v96, 0x3e16c740, v115
	v_mov_b64_e32 v[220:221], s[60:61]
	v_exp_f32_e32 v105, v105
	v_exp_f32_e32 v106, v106
	v_exp_f32_e32 v107, v107
	v_exp_f32_e32 v108, v108
	v_exp_f32_e32 v109, v109
	v_exp_f32_e32 v110, v110
	v_exp_f32_e32 v111, v111
	v_exp_f32_e32 v96, v96
	v_cvt_pk_bf16_f32 v112, v97, v98
	v_cvt_pk_bf16_f32 v113, v99, v100
	v_cvt_pk_bf16_f32 v114, v101, v102
	v_cvt_pk_bf16_f32 v115, v103, v104
	v_cvt_pk_bf16_f32 v200, v105, v106
	v_cvt_pk_bf16_f32 v201, v107, v108
	v_cvt_pk_bf16_f32 v202, v109, v110
	v_cvt_pk_bf16_f32 v203, v111, v96
	v_mfma_f32_32x32x16_bf16 v[96:111], v[220:223], v[112:115], 0
	s_nop 0
	v_mfma_f32_32x32x16_bf16 v[96:111], v[220:223], v[200:203], v[96:111]
	s_nop 11
	v_max3_f32 v97, v80, s68, v81
	v_max3_f32 v97, v97, v82, v83
	v_max3_f32 v97, v97, v84, v85
	v_max3_f32 v97, v97, v86, v87
	v_max3_f32 v97, v97, v88, v89
	v_max3_f32 v97, v97, v90, v91
	v_max3_f32 v97, v97, v92, v93
	v_max3_f32 v97, v97, v94, v95
	v_mov_b32_e32 v98, v97
	s_nop 1
	v_permlane32_swap_b32_e32 v97, v98
	v_max_f32_e32 v97, v97, v98
	v_mul_f32_e32 v97, 0x3e16c740, v97
	v_max_f32_e32 v97, v14, v97
	v_add_f32_e32 v98, 0x41000000, v14
	v_cmp_gt_f32_e32 vcc, v97, v98
	s_cbranch_vccz .LBB0_606
	v_sub_f32_e32 v14, v14, v97
	v_exp_f32_e32 v14, v14
	v_xor_b32_e32 v98, 0x80000000, v97
	v_mul_f32_e32 v15, v15, v14
	v_pk_mul_f32 v[46:47], v[46:47], v[14:15] op_sel_hi:[1,0]
	v_pk_mul_f32 v[44:45], v[44:45], v[14:15] op_sel_hi:[1,0]
	v_pk_mul_f32 v[42:43], v[42:43], v[14:15] op_sel_hi:[1,0]
	v_pk_mul_f32 v[40:41], v[40:41], v[14:15] op_sel_hi:[1,0]
	v_pk_mul_f32 v[38:39], v[38:39], v[14:15] op_sel_hi:[1,0]
	v_pk_mul_f32 v[36:37], v[36:37], v[14:15] op_sel_hi:[1,0]
	v_pk_mul_f32 v[34:35], v[34:35], v[14:15] op_sel_hi:[1,0]
	v_pk_mul_f32 v[32:33], v[32:33], v[14:15] op_sel_hi:[1,0]
	v_pk_mul_f32 v[30:31], v[30:31], v[14:15] op_sel_hi:[1,0]
	v_pk_mul_f32 v[28:29], v[28:29], v[14:15] op_sel_hi:[1,0]
	v_pk_mul_f32 v[26:27], v[26:27], v[14:15] op_sel_hi:[1,0]
	v_pk_mul_f32 v[24:25], v[24:25], v[14:15] op_sel_hi:[1,0]
	v_pk_mul_f32 v[22:23], v[22:23], v[14:15] op_sel_hi:[1,0]
	v_pk_mul_f32 v[20:21], v[20:21], v[14:15] op_sel_hi:[1,0]
	v_pk_mul_f32 v[18:19], v[18:19], v[14:15] op_sel_hi:[1,0]
	v_pk_mul_f32 v[16:17], v[16:17], v[14:15] op_sel_hi:[1,0]
	v_mov_b32_e32 v14, v97
	s_branch .LBB0_607

; #define LAS __attribute__((address_space(3)))
; __device__ __forceinline__ float fast_exp2(float x) { return __builtin_amdgcn_exp2f(x); }
; template <int MODE, int NQ>
; __device__ __forceinline__ void attn_unit(LAS unsigned char* lds, const Params& P, int layer, int b, int h, int qb) {
;     ...
;         for (int hf = 0; hf < 2; ++hf) {
;             if (it + 2 < NT) { if (hf == 0) AT_GLOADK(AT_TILE(it + 2)); else AT_GLOADV(AT_TILE(it + 2)); }
;             f32x16 sc[NC];
; #pragma unroll
;             for (int cc = 0; cc < NC; ++cc) {
;                 sc[cc] = f32x16{};
; #pragma unroll
;                 for (int d0 = 0; d0 < ND0; ++d0) sc[cc] = __builtin_amdgcn_mfma_f32_32x32x16_bf16(kf[(cc % NMAP) * ND0 + d0], qf[cc][d0], sc[cc], 0, 0, 0);
;             }
;             __builtin_amdgcn_sched_barrier(0);
;             AT_VLOAD(cur, hf);
;             if (hf == 0) AT_KLOAD(cur, 1); else if (it + 1 < NT) AT_KLOAD(nxt, 0);
;             __builtin_amdgcn_sched_barrier(0);
;             bf16x8 pw[NC][2]; float rmrel[NC]; bool alive = false;
; #pragma unroll
;             for (int cc = 0; cc < NC; ++cc) {
;                 f32x16& s0 = sc[cc];
;                 float mn;
;                 if (MODE != 0) {
;                     const LAS f32x4* tp4 = (const LAS f32x4*)(tlane + (kt * 64 + hf * 32) * 4);
;                     float rm = -3e38f;
; #pragma unroll
;                     for (int g = 0; g < 4; ++g) { const f32x4 t4 = tp4[2 * g];
; #pragma unroll
;                         for (int i = 0; i < 4; ++i) { s0[4 * g + i] = s0[4 * g + i] * c + t4[i]; rm = fmaxf(rm, s0[4 * g + i]); } }
;                     rm = xmax(rm);
;                     mn = fmaxf(mrun[cc], rm);
;                     rmrel[cc] = rm;
;                 } else {
;                     float rm = -3e38f;
; #pragma unroll
;                     for (int r = 0; r < 16; ++r) rm = fmaxf(rm, s0[r]);
;                     rm = xmax(rm);
;                     mn = fmaxf(mrun[cc], rm * c);
;                 }
;                 if (__any(mn > mrun[cc] + AT_THR)) {
;                     const float al = fast_exp2(mrun[cc] - mn); lrun[cc] *= al;
; #pragma unroll
;                     for (int r = 0; r < 16; ++r) { o[cc][0][r] *= al; o[cc][1][r] *= al; }
;                     mrun[cc] = mn;
;                 }
.LBB0_609:
	v_mfma_f32_32x32x16_bf16 v[96:111], v[188:191], v[160:163], 0
	s_add_i32 s0, s9, 0
	v_add_u32_e32 v2, s0, v242
	v_add3_u32 v2, v2, v243, v244
	v_add_u32_e32 v196, v2, v233
	v_mfma_f32_32x32x16_bf16 v[80:95], v[188:191], v[156:159], 0
	v_mfma_f32_32x32x16_bf16 v[96:111], v[184:187], v[140:143], v[96:111]
	v_mfma_f32_32x32x16_bf16 v[80:95], v[184:187], v[152:155], v[80:95]
	v_mfma_f32_32x32x16_bf16 v[96:111], v[180:183], v[132:135], v[96:111]
	v_mfma_f32_32x32x16_bf16 v[80:95], v[180:183], v[148:151], v[80:95]
	v_mfma_f32_32x32x16_bf16 v[96:111], v[176:179], v[128:131], v[96:111]
	v_mfma_f32_32x32x16_bf16 v[80:95], v[176:179], v[144:147], v[80:95]
	v_mfma_f32_32x32x16_bf16 v[96:111], v[172:175], v[124:127], v[96:111]
	v_mfma_f32_32x32x16_bf16 v[80:95], v[172:175], v[136:139], v[80:95]
	v_mfma_f32_32x32x16_bf16 v[96:111], v[168:171], v[120:123], v[96:111]
	v_mfma_f32_32x32x16_bf16 v[80:95], v[168:171], v[116:119], v[80:95]
	ds_read_b64_tr_b16 v[184:185], v196 offset:12288
	ds_read_b64_tr_b16 v[186:187], v196 offset:12800
	ds_read_b64_tr_b16 v[180:181], v196 offset:13312
	ds_read_b64_tr_b16 v[182:183], v196 offset:13824
	ds_read_b64_tr_b16 v[176:177], v196 offset:16384
	ds_read_b64_tr_b16 v[178:179], v196 offset:16896
	ds_read_b64_tr_b16 v[112:113], v196 offset:17408
	ds_read_b64_tr_b16 v[114:115], v196 offset:17920
	v_add3_u32 v2, s0, v247, v248
	ds_read_b128 v[172:175], v2 offset:512
	ds_read_b128 v[168:171], v2 offset:2560
	ds_read_b128 v[164:167], v2 offset:4608
	ds_read_b128 v[10:13], v2 offset:6656
	ds_read_b128 v[6:9], v2 offset:8704
	ds_read_b128 v[2:5], v2 offset:10752
	v_max3_f32 v15, v96, s68, v97
	v_max3_f32 v15, v15, v98, v99
	v_max3_f32 v15, v15, v100, v101
	v_max3_f32 v15, v15, v102, v103
	v_max3_f32 v15, v15, v104, v105
	v_max3_f32 v15, v15, v106, v107
	v_max3_f32 v15, v15, v108, v109
	v_max3_f32 v15, v15, v110, v111
	v_mov_b32_e32 v188, v15
	s_nop 1
	v_permlane32_swap_b32_e32 v15, v188
	v_max_f32_e32 v15, v15, v188
	v_mul_f32_e32 v15, 0x3e16c740, v15
	v_max_f32_e32 v15, v0, v15
	v_add_f32_e32 v188, 0x41000000, v0
	v_cmp_gt_f32_e32 vcc, v15, v188
	s_cbranch_vccz .LBB0_611
	v_sub_f32_e32 v0, v0, v15
	v_exp_f32_e32 v0, v0
	s_nop 0
	v_mul_f32_e32 v249, v249, v0
	v_pk_mul_f32 v[78:79], v[78:79], v[0:1] op_sel_hi:[1,0]
	v_pk_mul_f32 v[76:77], v[76:77], v[0:1] op_sel_hi:[1,0]
	v_pk_mul_f32 v[74:75], v[74:75], v[0:1] op_sel_hi:[1,0]
	v_pk_mul_f32 v[72:73], v[72:73], v[0:1] op_sel_hi:[1,0]
	v_pk_mul_f32 v[70:71], v[70:71], v[0:1] op_sel_hi:[1,0]
	v_pk_mul_f32 v[68:69], v[68:69], v[0:1] op_sel_hi:[1,0]
	v_pk_mul_f32 v[66:67], v[66:67], v[0:1] op_sel_hi:[1,0]
	v_pk_mul_f32 v[64:65], v[64:65], v[0:1] op_sel_hi:[1,0]
	v_pk_mul_f32 v[62:63], v[62:63], v[0:1] op_sel_hi:[1,0]
	v_pk_mul_f32 v[60:61], v[60:61], v[0:1] op_sel_hi:[1,0]
	v_pk_mul_f32 v[58:59], v[58:59], v[0:1] op_sel_hi:[1,0]
	v_pk_mul_f32 v[56:57], v[56:57], v[0:1] op_sel_hi:[1,0]
	v_pk_mul_f32 v[54:55], v[54:55], v[0:1] op_sel_hi:[1,0]
	v_pk_mul_f32 v[52:53], v[52:53], v[0:1] op_sel_hi:[1,0]
	v_pk_mul_f32 v[50:51], v[50:51], v[0:1] op_sel_hi:[1,0]
	v_pk_mul_f32 v[48:49], v[48:49], v[0:1] op_sel_hi:[1,0]
	s_branch .LBB0_612

; __device__ __forceinline__ unsigned cvtpk(float lo, float hi) { f32x2 v = {lo, hi}; bf16x2_t b = __builtin_convertvector(v, bf16x2_t); return __builtin_bit_cast(unsigned, b); }
; __device__ __forceinline__ float fast_exp2(float x) { return __builtin_amdgcn_exp2f(x); }
; template <int MODE, int NQ>
; __device__ __forceinline__ void attn_unit(LAS unsigned char* lds, const Params& P, int layer, int b, int h, int qb) {
;     ...
;                     float rm = -3e38f;
; #pragma unroll
;                     for (int r = 0; r < 16; ++r) rm = fmaxf(rm, s0[r]);
;                     rm = xmax(rm);
;                     mn = fmaxf(mrun[cc], rm * c);
;                 }
;                 if (__any(mn > mrun[cc] + AT_THR)) {
;                     const float al = fast_exp2(mrun[cc] - mn); lrun[cc] *= al;
; #pragma unroll
;                     for (int r = 0; r < 16; ++r) { o[cc][0][r] *= al; o[cc][1][r] *= al; }
;                     mrun[cc] = mn;
;                 }
;                 mn = mrun[cc];
;                 if (MODE != 0) rmrel[cc] -= mn;
;                 const bool dead = (MODE != 0) && __all(rmrel[cc] < -136.f);
;                 if (dead) { pw[cc][0] = zero8; pw[cc][1] = zero8; }
;                 else {
;                     alive = true;
;                     if (MODE != 0) {
; #pragma unroll
;                         for (int r = 0; r < 16; ++r) s0[r] = fast_exp2(s0[r] - mn);
;                     } else {
;                         const float nm = -mn;
; #pragma unroll
;                         for (int r = 0; r < 16; ++r) s0[r] = fast_exp2(__builtin_fmaf(s0[r], c, nm));
;                     }
;                     u32x4 w;
;                     w.x = cvtpk(s0[0], s0[1]); w.y = cvtpk(s0[2], s0[3]); w.z = cvtpk(s0[4], s0[5]); w.w = cvtpk(s0[6], s0[7]); pw[cc][0] = __builtin_bit_cast(bf16x8, w);
;                     w.x = cvtpk(s0[8], s0[9]); w.y = cvtpk(s0[10], s0[11]); w.z = cvtpk(s0[12], s0[13]); w.w = cvtpk(s0[14], s0[15]); pw[cc][1] = __builtin_bit_cast(bf16x8, w);
;                     f32x16 t = __builtin_amdgcn_mfma_f32_32x32x16_bf16(ones8, pw[cc][0], f32x16{}, 0, 0, 0);
;                     t = __builtin_amdgcn_mfma_f32_32x32x16_bf16(ones8, pw[cc][1], t, 0, 0, 0);
;                     lrun[cc] += t[0];
;                 }
.LBB0_612:
	s_mov_b32 s62, s60
	s_mov_b32 s63, s60
	v_fma_f32 v0, v96, s97, -v15
	v_fma_f32 v96, v97, s97, -v15
	v_fma_f32 v97, v98, s97, -v15
	v_fma_f32 v98, v99, s97, -v15
	v_fma_f32 v99, v100, s97, -v15
	v_fma_f32 v100, v101, s97, -v15
	v_fma_f32 v101, v102, s97, -v15
	v_fma_f32 v102, v103, s97, -v15
	s_mov_b32 s61, s60
	v_mov_b64_e32 v[200:201], s[62:63]
	v_exp_f32_e32 v0, v0
	v_exp_f32_e32 v96, v96
	v_exp_f32_e32 v97, v97
	v_exp_f32_e32 v98, v98
	v_exp_f32_e32 v99, v99
	v_exp_f32_e32 v100, v100
	v_exp_f32_e32 v101, v101
	v_exp_f32_e32 v102, v102
	v_fma_f32 v103, v104, s97, -v15
	v_fma_f32 v104, v105, s97, -v15
	v_fma_f32 v105, v106, s97, -v15
	v_fma_f32 v106, v107, s97, -v15
	v_fma_f32 v107, v108, s97, -v15
	v_fma_f32 v108, v109, s97, -v15
	v_fma_f32 v109, v110, s97, -v15
	v_fma_f32 v110, v111, s97, -v15
	v_mov_b64_e32 v[198:199], s[60:61]
	v_exp_f32_e32 v103, v103
	v_exp_f32_e32 v104, v104
	v_exp_f32_e32 v105, v105
	v_exp_f32_e32 v106, v106
	v_exp_f32_e32 v107, v107
	v_exp_f32_e32 v108, v108
	v_exp_f32_e32 v109, v109
	v_exp_f32_e32 v110, v110
	v_cvt_pk_bf16_f32 v192, v0, v96
	v_cvt_pk_bf16_f32 v193, v97, v98
	v_cvt_pk_bf16_f32 v194, v99, v100
	v_cvt_pk_bf16_f32 v195, v101, v102
	v_cvt_pk_bf16_f32 v188, v103, v104
	v_cvt_pk_bf16_f32 v189, v105, v106
	v_cvt_pk_bf16_f32 v190, v107, v108
	v_cvt_pk_bf16_f32 v191, v109, v110
	v_mfma_f32_32x32x16_bf16 v[96:111], v[198:201], v[192:195], 0
	v_max3_f32 v0, v80, s68, v81
	v_max3_f32 v0, v0, v82, v83
	v_max3_f32 v0, v0, v84, v85
	v_max3_f32 v0, v0, v86, v87
	v_max3_f32 v0, v0, v88, v89
	v_max3_f32 v0, v0, v90, v91
	v_max3_f32 v0, v0, v92, v93
	v_mfma_f32_32x32x16_bf16 v[96:111], v[198:201], v[188:191], v[96:111]
	v_max3_f32 v0, v0, v94, v95
	s_nop 10
	v_mov_b32_e32 v97, v0
	s_nop 1
	v_permlane32_swap_b32_e32 v0, v97
	v_max_f32_e32 v0, v0, v97
	v_mul_f32_e32 v0, 0x3e16c740, v0
	v_max_f32_e32 v0, v14, v0
	v_add_f32_e32 v97, 0x41000000, v14
	v_cmp_gt_f32_e32 vcc, v0, v97
	s_cbranch_vccz .LBB0_614
	v_sub_f32_e32 v14, v14, v0
	v_exp_f32_e32 v14, v14
	s_nop 0
	v_mul_f32_e32 v245, v245, v14
	v_pk_mul_f32 v[46:47], v[46:47], v[14:15] op_sel_hi:[1,0]
	v_pk_mul_f32 v[44:45], v[44:45], v[14:15] op_sel_hi:[1,0]
	v_pk_mul_f32 v[42:43], v[42:43], v[14:15] op_sel_hi:[1,0]
	v_pk_mul_f32 v[40:41], v[40:41], v[14:15] op_sel_hi:[1,0]
	v_pk_mul_f32 v[38:39], v[38:39], v[14:15] op_sel_hi:[1,0]
	v_pk_mul_f32 v[36:37], v[36:37], v[14:15] op_sel_hi:[1,0]
	v_pk_mul_f32 v[34:35], v[34:35], v[14:15] op_sel_hi:[1,0]
	v_pk_mul_f32 v[32:33], v[32:33], v[14:15] op_sel_hi:[1,0]
	v_pk_mul_f32 v[30:31], v[30:31], v[14:15] op_sel_hi:[1,0]
	v_pk_mul_f32 v[28:29], v[28:29], v[14:15] op_sel_hi:[1,0]
	v_pk_mul_f32 v[26:27], v[26:27], v[14:15] op_sel_hi:[1,0]
	v_pk_mul_f32 v[24:25], v[24:25], v[14:15] op_sel_hi:[1,0]
	v_pk_mul_f32 v[22:23], v[22:23], v[14:15] op_sel_hi:[1,0]
	v_pk_mul_f32 v[20:21], v[20:21], v[14:15] op_sel_hi:[1,0]
	v_pk_mul_f32 v[18:19], v[18:19], v[14:15] op_sel_hi:[1,0]
	v_pk_mul_f32 v[16:17], v[16:17], v[14:15] op_sel_hi:[1,0]
	s_branch .LBB0_615

; template <int MODE, int NQ>
; __device__ __forceinline__ void attn_unit(LAS unsigned char* lds, const Params& P, int layer, int b, int h, int qb) {
;     ...
;             f32x16 sc[NC];
; #pragma unroll
;             for (int cc = 0; cc < NC; ++cc) {
;                 sc[cc] = f32x16{};
; #pragma unroll
;                 for (int d0 = 0; d0 < ND0; ++d0) sc[cc] = __builtin_amdgcn_mfma_f32_32x32x16_bf16(kf[(cc % NMAP) * ND0 + d0], qf[cc][d0], sc[cc], 0, 0, 0);
;             }
;             __builtin_amdgcn_sched_barrier(0);
;             AT_VLOAD(cur, hf);
;             if (hf == 0) AT_KLOAD(cur, 1); else if (it + 1 < NT) AT_KLOAD(nxt, 0);
;             __builtin_amdgcn_sched_barrier(0);
;             bf16x8 pw[NC][2]; float rmrel[NC]; bool alive = false;
; #pragma unroll
;             for (int cc = 0; cc < NC; ++cc) {
;                 f32x16& s0 = sc[cc];
;                 float mn;
;     ...
;                         for (int r = 0; r < 16; ++r) s0[r] = fast_exp2(s0[r] - mn);
;                     } else {
;                         const float nm = -mn;
; #pragma unroll
;                         for (int r = 0; r < 16; ++r) s0[r] = fast_exp2(__builtin_fmaf(s0[r], c, nm));
;                     }
;                     u32x4 w;
;                     w.x = cvtpk(s0[0], s0[1]); w.y = cvtpk(s0[2], s0[3]); w.z = cvtpk(s0[4], s0[5]); w.w = cvtpk(s0[6], s0[7]); pw[cc][0] = __builtin_bit_cast(bf16x8, w);
;                     w.x = cvtpk(s0[8], s0[9]); w.y = cvtpk(s0[10], s0[11]); w.z = cvtpk(s0[12], s0[13]); w.w = cvtpk(s0[14], s0[15]); pw[cc][1] = __builtin_bit_cast(bf16x8, w);
;                     f32x16 t = __builtin_amdgcn_mfma_f32_32x32x16_bf16(ones8, pw[cc][0], f32x16{}, 0, 0, 0);
;                     t = __builtin_amdgcn_mfma_f32_32x32x16_bf16(ones8, pw[cc][1], t, 0, 0, 0);
;                     lrun[cc] += t[0];
;                 }
;             }
;             if (alive)
; #pragma unroll
;             for (int dv = 0; dv < 2; ++dv)
; #pragma unroll
;                 for (int k2 = 0; k2 < 2; ++k2) {
;                     const s16x4 lo = vlo[dv * 2 + k2], hh = vhi[dv * 2 + k2];
;                     const bf16x8 vf = (bf16x8){lo[0], lo[1], lo[2], lo[3], hh[0], hh[1], hh[2], hh[3]};
; #pragma unroll
;                     for (int cc = 0; cc < NC; ++cc) o[cc][dv] = __builtin_amdgcn_mfma_f32_32x32x16_bf16(vf, pw[cc][k2], o[cc][dv], 0, 0, 0);
;                 }
.LBB0_615:
	v_fma_f32 v14, v80, s97, -v0
	v_fma_f32 v80, v81, s97, -v0
	v_fma_f32 v81, v82, s97, -v0
	v_fma_f32 v82, v83, s97, -v0
	v_fma_f32 v83, v84, s97, -v0
	v_fma_f32 v84, v85, s97, -v0
	v_fma_f32 v85, v86, s97, -v0
	v_fma_f32 v86, v87, s97, -v0
	v_fma_f32 v87, v88, s97, -v0
	v_fma_f32 v88, v89, s97, -v0
	v_fma_f32 v89, v90, s97, -v0
	v_fma_f32 v90, v91, s97, -v0
	v_fma_f32 v91, v92, s97, -v0
	v_fma_f32 v92, v93, s97, -v0
	v_exp_f32_e32 v81, v81
	v_exp_f32_e32 v82, v82
	v_exp_f32_e32 v83, v83
	v_exp_f32_e32 v84, v84
	v_exp_f32_e32 v85, v85
	v_exp_f32_e32 v86, v86
	v_exp_f32_e32 v87, v87
	v_exp_f32_e32 v88, v88
	v_exp_f32_e32 v89, v89
	v_exp_f32_e32 v90, v90
	v_exp_f32_e32 v91, v91
	v_exp_f32_e32 v92, v92
	v_cvt_pk_bf16_f32 v81, v81, v82
	v_cvt_pk_bf16_f32 v82, v83, v84
	v_cvt_pk_bf16_f32 v83, v85, v86
	v_cvt_pk_bf16_f32 v84, v87, v88
	v_cvt_pk_bf16_f32 v85, v89, v90
	v_cvt_pk_bf16_f32 v86, v91, v92
	v_mov_b64_e32 v[90:91], s[62:63]
	v_exp_f32_e32 v14, v14
	v_exp_f32_e32 v80, v80
	v_mov_b64_e32 v[88:89], s[60:61]
	v_add_f32_e32 v197, v249, v96
	s_waitcnt lgkmcnt(8)
	v_mfma_f32_32x32x16_bf16 v[48:63], v[176:179], v[192:195], v[48:63]
	v_cvt_pk_bf16_f32 v80, v14, v80
	v_fma_f32 v93, v94, s97, -v0
	v_fma_f32 v94, v95, s97, -v0
	v_exp_f32_e32 v93, v93
	v_exp_f32_e32 v94, v94
	s_nop 0
	v_cvt_pk_bf16_f32 v87, v93, v94
	v_mfma_f32_32x32x16_bf16 v[96:111], v[88:91], v[80:83], 0
	v_mfma_f32_32x32x16_bf16 v[32:47], v[184:187], v[80:83], v[32:47]
	v_mfma_f32_32x32x16_bf16 v[16:31], v[176:179], v[80:83], v[16:31]
	v_mfma_f32_32x32x16_bf16 v[96:111], v[88:91], v[84:87], v[96:111]
	v_mfma_f32_32x32x16_bf16 v[32:47], v[180:183], v[84:87], v[32:47]
	s_waitcnt lgkmcnt(6)
	v_mfma_f32_32x32x16_bf16 v[48:63], v[112:115], v[188:191], v[48:63]
	v_mfma_f32_32x32x16_bf16 v[16:31], v[112:115], v[84:87], v[16:31]
	s_waitcnt lgkmcnt(5)
	v_mfma_f32_32x32x16_bf16 v[98:113], v[172:175], v[160:163], 0
	v_mfma_f32_32x32x16_bf16 v[80:95], v[172:175], v[156:159], 0
	s_waitcnt lgkmcnt(4)
	v_mfma_f32_32x32x16_bf16 v[98:113], v[168:171], v[140:143], v[98:113]
	v_mfma_f32_32x32x16_bf16 v[80:95], v[168:171], v[152:155], v[80:95]
	s_waitcnt lgkmcnt(3)
	v_mfma_f32_32x32x16_bf16 v[98:113], v[164:167], v[132:135], v[98:113]
	v_mfma_f32_32x32x16_bf16 v[80:95], v[164:167], v[148:151], v[80:95]
	s_waitcnt lgkmcnt(2)
	v_mfma_f32_32x32x16_bf16 v[98:113], v[10:13], v[128:131], v[98:113]
	v_mfma_f32_32x32x16_bf16 v[80:95], v[10:13], v[144:147], v[80:95]
	v_mfma_f32_32x32x16_bf16 v[64:79], v[184:187], v[192:195], v[64:79]
	s_waitcnt lgkmcnt(1)
	v_mfma_f32_32x32x16_bf16 v[98:113], v[6:9], v[124:127], v[98:113]
	v_mfma_f32_32x32x16_bf16 v[80:95], v[6:9], v[136:139], v[80:95]
	v_mfma_f32_32x32x16_bf16 v[64:79], v[180:183], v[188:191], v[64:79]
	s_waitcnt lgkmcnt(0)
	v_mfma_f32_32x32x16_bf16 v[98:113], v[2:5], v[120:123], v[98:113]
	v_mfma_f32_32x32x16_bf16 v[80:95], v[2:5], v[116:119], v[80:95]
	ds_read_b64_tr_b16 v[188:189], v196 offset:14336
	ds_read_b64_tr_b16 v[190:191], v196 offset:14848
	ds_read_b64_tr_b16 v[184:185], v196 offset:15360
	ds_read_b64_tr_b16 v[186:187], v196 offset:15872
	ds_read_b64_tr_b16 v[180:181], v196 offset:18432
	ds_read_b64_tr_b16 v[182:183], v196 offset:18944
	ds_read_b64_tr_b16 v[176:177], v196 offset:19456
	ds_read_b64_tr_b16 v[178:179], v196 offset:19968
	v_add_u32_e32 v2, s8, v241
	ds_read_b128 v[172:175], v2
	ds_read_b128 v[168:171], v2 offset:2048
	ds_read_b128 v[164:167], v2 offset:4096
	ds_read_b128 v[10:13], v2 offset:6144
	ds_read_b128 v[6:9], v2 offset:8192
	ds_read_b128 v[2:5], v2 offset:10240
	v_max3_f32 v14, v98, s68, v99
	v_max3_f32 v14, v14, v100, v101
	v_max3_f32 v14, v14, v102, v103
	v_max3_f32 v14, v14, v104, v105
	v_max3_f32 v14, v14, v106, v107
	v_max3_f32 v14, v14, v108, v109
	v_max3_f32 v14, v14, v110, v111
	v_max3_f32 v14, v14, v112, v113
	v_mov_b32_e32 v97, v14
	s_nop 1
	v_permlane32_swap_b32_e32 v14, v97
	v_max_f32_e32 v14, v14, v97
	v_mul_f32_e32 v14, 0x3e16c740, v14
	v_max_f32_e32 v97, v15, v14
	v_add_f32_e32 v14, 0x41000000, v15
	v_cmp_gt_f32_e32 vcc, v97, v14
	s_cbranch_vccz .LBB0_617
	v_sub_f32_e32 v14, v15, v97
	v_exp_f32_e32 v14, v14
	s_nop 0
	v_mul_f32_e32 v197, v197, v14
	v_pk_mul_f32 v[78:79], v[78:79], v[14:15] op_sel_hi:[1,0]
	v_pk_mul_f32 v[76:77], v[76:77], v[14:15] op_sel_hi:[1,0]
	v_pk_mul_f32 v[74:75], v[74:75], v[14:15] op_sel_hi:[1,0]
	v_pk_mul_f32 v[72:73], v[72:73], v[14:15] op_sel_hi:[1,0]
	v_pk_mul_f32 v[70:71], v[70:71], v[14:15] op_sel_hi:[1,0]
	v_pk_mul_f32 v[68:69], v[68:69], v[14:15] op_sel_hi:[1,0]
	v_pk_mul_f32 v[66:67], v[66:67], v[14:15] op_sel_hi:[1,0]
	v_pk_mul_f32 v[64:65], v[64:65], v[14:15] op_sel_hi:[1,0]
	v_pk_mul_f32 v[62:63], v[62:63], v[14:15] op_sel_hi:[1,0]
	v_pk_mul_f32 v[60:61], v[60:61], v[14:15] op_sel_hi:[1,0]
	v_pk_mul_f32 v[58:59], v[58:59], v[14:15] op_sel_hi:[1,0]
	v_pk_mul_f32 v[56:57], v[56:57], v[14:15] op_sel_hi:[1,0]
	v_pk_mul_f32 v[54:55], v[54:55], v[14:15] op_sel_hi:[1,0]
	v_pk_mul_f32 v[52:53], v[52:53], v[14:15] op_sel_hi:[1,0]
	v_pk_mul_f32 v[50:51], v[50:51], v[14:15] op_sel_hi:[1,0]
	v_pk_mul_f32 v[48:49], v[48:49], v[14:15] op_sel_hi:[1,0]
	v_xor_b32_e32 v14, 0x80000000, v97
	v_mov_b32_e32 v15, v97
	s_branch .LBB0_618

; __device__ __forceinline__ unsigned cvtpk(float lo, float hi) { f32x2 v = {lo, hi}; bf16x2_t b = __builtin_convertvector(v, bf16x2_t); return __builtin_bit_cast(unsigned, b); }
; __device__ __forceinline__ float fast_exp2(float x) { return __builtin_amdgcn_exp2f(x); }
; template <int MODE, int NQ>
; __device__ __forceinline__ void attn_unit(LAS unsigned char* lds, const Params& P, int layer, int b, int h, int qb) {
;     ...
;                     float rm = -3e38f;
; #pragma unroll
;                     for (int r = 0; r < 16; ++r) rm = fmaxf(rm, s0[r]);
;                     rm = xmax(rm);
;                     mn = fmaxf(mrun[cc], rm * c);
;                 }
;                 if (__any(mn > mrun[cc] + AT_THR)) {
;                     const float al = fast_exp2(mrun[cc] - mn); lrun[cc] *= al;
; #pragma unroll
;                     for (int r = 0; r < 16; ++r) { o[cc][0][r] *= al; o[cc][1][r] *= al; }
;                     mrun[cc] = mn;
;                 }
;                 mn = mrun[cc];
;                 if (MODE != 0) rmrel[cc] -= mn;
;                 const bool dead = (MODE != 0) && __all(rmrel[cc] < -136.f);
;                 if (dead) { pw[cc][0] = zero8; pw[cc][1] = zero8; }
;                 else {
;                     alive = true;
;                     if (MODE != 0) {
; #pragma unroll
;                         for (int r = 0; r < 16; ++r) s0[r] = fast_exp2(s0[r] - mn);
;                     } else {
;                         const float nm = -mn;
; #pragma unroll
;                         for (int r = 0; r < 16; ++r) s0[r] = fast_exp2(__builtin_fmaf(s0[r], c, nm));
;                     }
;                     u32x4 w;
;                     w.x = cvtpk(s0[0], s0[1]); w.y = cvtpk(s0[2], s0[3]); w.z = cvtpk(s0[4], s0[5]); w.w = cvtpk(s0[6], s0[7]); pw[cc][0] = __builtin_bit_cast(bf16x8, w);
;                     w.x = cvtpk(s0[8], s0[9]); w.y = cvtpk(s0[10], s0[11]); w.z = cvtpk(s0[12], s0[13]); w.w = cvtpk(s0[14], s0[15]); pw[cc][1] = __builtin_bit_cast(bf16x8, w);
;                     f32x16 t = __builtin_amdgcn_mfma_f32_32x32x16_bf16(ones8, pw[cc][0], f32x16{}, 0, 0, 0);
;                     t = __builtin_amdgcn_mfma_f32_32x32x16_bf16(ones8, pw[cc][1], t, 0, 0, 0);
;                     lrun[cc] += t[0];
;                 }
.LBB0_618:
	s_mov_b32 s62, s60
	s_mov_b32 s63, s60
	v_add_f32_e32 v198, v245, v96
	v_fmamk_f32 v96, v98, 0x3e16c740, v14
	v_fmamk_f32 v97, v99, 0x3e16c740, v14
	v_fmamk_f32 v98, v100, 0x3e16c740, v14
	v_fmamk_f32 v99, v101, 0x3e16c740, v14
	v_fmamk_f32 v100, v102, 0x3e16c740, v14
	v_fmamk_f32 v101, v103, 0x3e16c740, v14
	v_fmamk_f32 v102, v104, 0x3e16c740, v14
	v_fmamk_f32 v103, v105, 0x3e16c740, v14
	s_mov_b32 s61, s60
	v_mov_b64_e32 v[202:203], s[62:63]
	v_exp_f32_e32 v96, v96
	v_exp_f32_e32 v97, v97
	v_exp_f32_e32 v98, v98
	v_exp_f32_e32 v99, v99
	v_exp_f32_e32 v100, v100
	v_exp_f32_e32 v101, v101
	v_exp_f32_e32 v102, v102
	v_exp_f32_e32 v103, v103
	v_fmamk_f32 v104, v106, 0x3e16c740, v14
	v_fmamk_f32 v105, v107, 0x3e16c740, v14
	v_fmamk_f32 v106, v108, 0x3e16c740, v14
	v_fmamk_f32 v107, v109, 0x3e16c740, v14
	v_fmamk_f32 v108, v110, 0x3e16c740, v14
	v_fmamk_f32 v109, v111, 0x3e16c740, v14
	v_fmamk_f32 v110, v112, 0x3e16c740, v14
	v_fmamk_f32 v111, v113, 0x3e16c740, v14
	v_mov_b64_e32 v[200:201], s[60:61]
	v_exp_f32_e32 v104, v104
	v_exp_f32_e32 v105, v105
	v_exp_f32_e32 v106, v106
	v_exp_f32_e32 v107, v107
	v_exp_f32_e32 v108, v108
	v_exp_f32_e32 v109, v109
	v_exp_f32_e32 v110, v110
	v_exp_f32_e32 v111, v111
	v_cvt_pk_bf16_f32 v192, v96, v97
	v_cvt_pk_bf16_f32 v193, v98, v99
	v_cvt_pk_bf16_f32 v194, v100, v101
	v_cvt_pk_bf16_f32 v195, v102, v103
	v_cvt_pk_bf16_f32 v112, v104, v105
	v_cvt_pk_bf16_f32 v113, v106, v107
	v_cvt_pk_bf16_f32 v114, v108, v109
	v_cvt_pk_bf16_f32 v115, v110, v111
	v_mfma_f32_32x32x16_bf16 v[96:111], v[200:203], v[192:195], 0
	s_nop 0
	v_mfma_f32_32x32x16_bf16 v[96:111], v[200:203], v[112:115], v[96:111]
	s_nop 11
	v_max3_f32 v97, v80, s68, v81
	v_max3_f32 v97, v97, v82, v83
	v_max3_f32 v97, v97, v84, v85
	v_max3_f32 v97, v97, v86, v87
	v_max3_f32 v97, v97, v88, v89
	v_max3_f32 v97, v97, v90, v91
	v_max3_f32 v97, v97, v92, v93
	v_max3_f32 v97, v97, v94, v95
	v_mov_b32_e32 v98, v97
	s_nop 1
	v_permlane32_swap_b32_e32 v97, v98
	v_max_f32_e32 v97, v97, v98
	v_mul_f32_e32 v97, 0x3e16c740, v97
	v_max_f32_e32 v97, v0, v97
	v_add_f32_e32 v98, 0x41000000, v0
	v_cmp_gt_f32_e32 vcc, v97, v98
	s_cbranch_vccz .LBB0_620
	v_sub_f32_e32 v0, v0, v97
	v_exp_f32_e32 v0, v0
	v_xor_b32_e32 v196, 0x80000000, v97
	v_mul_f32_e32 v198, v198, v0
	v_pk_mul_f32 v[46:47], v[46:47], v[0:1] op_sel_hi:[1,0]
	v_pk_mul_f32 v[44:45], v[44:45], v[0:1] op_sel_hi:[1,0]
	v_pk_mul_f32 v[42:43], v[42:43], v[0:1] op_sel_hi:[1,0]
	v_pk_mul_f32 v[40:41], v[40:41], v[0:1] op_sel_hi:[1,0]
	v_pk_mul_f32 v[38:39], v[38:39], v[0:1] op_sel_hi:[1,0]
	v_pk_mul_f32 v[36:37], v[36:37], v[0:1] op_sel_hi:[1,0]
	v_pk_mul_f32 v[34:35], v[34:35], v[0:1] op_sel_hi:[1,0]
	v_pk_mul_f32 v[32:33], v[32:33], v[0:1] op_sel_hi:[1,0]
	v_pk_mul_f32 v[30:31], v[30:31], v[0:1] op_sel_hi:[1,0]
	v_pk_mul_f32 v[28:29], v[28:29], v[0:1] op_sel_hi:[1,0]
	v_pk_mul_f32 v[26:27], v[26:27], v[0:1] op_sel_hi:[1,0]
	v_pk_mul_f32 v[24:25], v[24:25], v[0:1] op_sel_hi:[1,0]
	v_pk_mul_f32 v[22:23], v[22:23], v[0:1] op_sel_hi:[1,0]
	v_pk_mul_f32 v[20:21], v[20:21], v[0:1] op_sel_hi:[1,0]
	v_pk_mul_f32 v[18:19], v[18:19], v[0:1] op_sel_hi:[1,0]
	v_pk_mul_f32 v[16:17], v[16:17], v[0:1] op_sel_hi:[1,0]
	v_mov_b32_e32 v0, v97
	s_branch .LBB0_621

; template <int MODE, int NQ>
; __device__ __forceinline__ void attn_unit(LAS unsigned char* lds, const Params& P, int layer, int b, int h, int qb) {
;     ...
;             f32x16 sc[NC];
; #pragma unroll
;             for (int cc = 0; cc < NC; ++cc) {
;                 sc[cc] = f32x16{};
; #pragma unroll
;                 for (int d0 = 0; d0 < ND0; ++d0) sc[cc] = __builtin_amdgcn_mfma_f32_32x32x16_bf16(kf[(cc % NMAP) * ND0 + d0], qf[cc][d0], sc[cc], 0, 0, 0);
;             }
;             __builtin_amdgcn_sched_barrier(0);
;             AT_VLOAD(cur, hf);
;             if (hf == 0) AT_KLOAD(cur, 1); else if (it + 1 < NT) AT_KLOAD(nxt, 0);
;             __builtin_amdgcn_sched_barrier(0);
;             bf16x8 pw[NC][2]; float rmrel[NC]; bool alive = false;
; #pragma unroll
;             for (int cc = 0; cc < NC; ++cc) {
;                 f32x16& s0 = sc[cc];
;                 float mn;
;     ...
;                         for (int r = 0; r < 16; ++r) s0[r] = fast_exp2(s0[r] - mn);
;                     } else {
;                         const float nm = -mn;
; #pragma unroll
;                         for (int r = 0; r < 16; ++r) s0[r] = fast_exp2(__builtin_fmaf(s0[r], c, nm));
;                     }
;                     u32x4 w;
;                     w.x = cvtpk(s0[0], s0[1]); w.y = cvtpk(s0[2], s0[3]); w.z = cvtpk(s0[4], s0[5]); w.w = cvtpk(s0[6], s0[7]); pw[cc][0] = __builtin_bit_cast(bf16x8, w);
;                     w.x = cvtpk(s0[8], s0[9]); w.y = cvtpk(s0[10], s0[11]); w.z = cvtpk(s0[12], s0[13]); w.w = cvtpk(s0[14], s0[15]); pw[cc][1] = __builtin_bit_cast(bf16x8, w);
;                     f32x16 t = __builtin_amdgcn_mfma_f32_32x32x16_bf16(ones8, pw[cc][0], f32x16{}, 0, 0, 0);
;                     t = __builtin_amdgcn_mfma_f32_32x32x16_bf16(ones8, pw[cc][1], t, 0, 0, 0);
;                     lrun[cc] += t[0];
;                 }
;             }
;             if (alive)
; #pragma unroll
;             for (int dv = 0; dv < 2; ++dv)
; #pragma unroll
;                 for (int k2 = 0; k2 < 2; ++k2) {
;                     const s16x4 lo = vlo[dv * 2 + k2], hh = vhi[dv * 2 + k2];
;                     const bf16x8 vf = (bf16x8){lo[0], lo[1], lo[2], lo[3], hh[0], hh[1], hh[2], hh[3]};
; #pragma unroll
;                     for (int cc = 0; cc < NC; ++cc) o[cc][dv] = __builtin_amdgcn_mfma_f32_32x32x16_bf16(vf, pw[cc][k2], o[cc][dv], 0, 0, 0);
;                 }
.LBB0_621:
	v_fmamk_f32 v80, v80, 0x3e16c740, v196
	v_fmamk_f32 v81, v81, 0x3e16c740, v196
	v_fmamk_f32 v82, v82, 0x3e16c740, v196
	v_fmamk_f32 v83, v83, 0x3e16c740, v196
	v_fmamk_f32 v84, v84, 0x3e16c740, v196
	v_fmamk_f32 v85, v85, 0x3e16c740, v196
	v_fmamk_f32 v88, v88, 0x3e16c740, v196
	v_fmamk_f32 v89, v89, 0x3e16c740, v196
	v_fmamk_f32 v90, v90, 0x3e16c740, v196
	v_fmamk_f32 v91, v91, 0x3e16c740, v196
	v_exp_f32_e32 v80, v80
	v_exp_f32_e32 v81, v81
	v_exp_f32_e32 v82, v82
	v_exp_f32_e32 v83, v83
	v_exp_f32_e32 v84, v84
	v_exp_f32_e32 v85, v85
	v_exp_f32_e32 v88, v88
	v_exp_f32_e32 v89, v89
	v_exp_f32_e32 v90, v90
	v_exp_f32_e32 v91, v91
	v_fmamk_f32 v86, v86, 0x3e16c740, v196
	v_fmamk_f32 v87, v87, 0x3e16c740, v196
	v_cvt_pk_bf16_f32 v80, v80, v81
	v_cvt_pk_bf16_f32 v81, v82, v83
	v_cvt_pk_bf16_f32 v82, v84, v85
	v_cvt_pk_bf16_f32 v84, v88, v89
	v_cvt_pk_bf16_f32 v85, v90, v91
	v_mov_b64_e32 v[90:91], s[62:63]
	v_exp_f32_e32 v86, v86
	v_exp_f32_e32 v87, v87
	v_mov_b64_e32 v[88:89], s[60:61]
	v_add_f32_e32 v199, v197, v96
	s_waitcnt lgkmcnt(12)
	v_mfma_f32_32x32x16_bf16 v[64:79], v[188:191], v[192:195], v[64:79]
	v_cvt_pk_bf16_f32 v83, v86, v87
	v_fmamk_f32 v92, v92, 0x3e16c740, v196
	v_fmamk_f32 v93, v93, 0x3e16c740, v196
	v_fmamk_f32 v94, v94, 0x3e16c740, v196
	v_fmamk_f32 v95, v95, 0x3e16c740, v196
	v_exp_f32_e32 v92, v92
	v_exp_f32_e32 v93, v93
	v_mfma_f32_32x32x16_bf16 v[96:111], v[88:91], v[80:83], 0
	v_exp_f32_e32 v94, v94
	v_exp_f32_e32 v95, v95
	v_cvt_pk_bf16_f32 v86, v92, v93
	s_waitcnt lgkmcnt(0)
	s_barrier
	v_cvt_pk_bf16_f32 v87, v94, v95
	v_mfma_f32_32x32x16_bf16 v[32:47], v[188:191], v[80:83], v[32:47]
	v_mfma_f32_32x32x16_bf16 v[48:63], v[180:183], v[192:195], v[48:63]
	v_mfma_f32_32x32x16_bf16 v[16:31], v[180:183], v[80:83], v[16:31]
	v_add_u32_e32 v80, 0, v242
	v_add3_u32 v80, v80, v243, v244
	v_add_u32_e32 v197, v80, v233
	v_mfma_f32_32x32x16_bf16 v[96:111], v[88:91], v[84:87], v[96:111]
	v_mfma_f32_32x32x16_bf16 v[64:79], v[184:187], v[112:115], v[64:79]
	v_mfma_f32_32x32x16_bf16 v[32:47], v[184:187], v[84:87], v[32:47]
	v_mfma_f32_32x32x16_bf16 v[48:63], v[176:179], v[112:115], v[48:63]
	v_mfma_f32_32x32x16_bf16 v[16:31], v[176:179], v[84:87], v[16:31]
	v_mfma_f32_32x32x16_bf16 v[98:113], v[172:175], v[160:163], 0
	v_mfma_f32_32x32x16_bf16 v[80:95], v[172:175], v[156:159], 0
	v_mfma_f32_32x32x16_bf16 v[98:113], v[168:171], v[140:143], v[98:113]
	v_mfma_f32_32x32x16_bf16 v[80:95], v[168:171], v[152:155], v[80:95]
	v_mfma_f32_32x32x16_bf16 v[98:113], v[164:167], v[132:135], v[98:113]
	v_mfma_f32_32x32x16_bf16 v[80:95], v[164:167], v[148:151], v[80:95]
	v_mfma_f32_32x32x16_bf16 v[98:113], v[10:13], v[128:131], v[98:113]
	v_mfma_f32_32x32x16_bf16 v[80:95], v[10:13], v[144:147], v[80:95]
	v_mfma_f32_32x32x16_bf16 v[98:113], v[6:9], v[124:127], v[98:113]
	v_mfma_f32_32x32x16_bf16 v[80:95], v[6:9], v[136:139], v[80:95]
	v_mfma_f32_32x32x16_bf16 v[98:113], v[2:5], v[120:123], v[98:113]
	v_mfma_f32_32x32x16_bf16 v[80:95], v[2:5], v[116:119], v[80:95]
	ds_read_b64_tr_b16 v[188:189], v197 offset:32768
	ds_read_b64_tr_b16 v[190:191], v197 offset:33280
	ds_read_b64_tr_b16 v[184:185], v197 offset:33792
	ds_read_b64_tr_b16 v[186:187], v197 offset:34304
	ds_read_b64_tr_b16 v[180:181], v197 offset:36864
	ds_read_b64_tr_b16 v[182:183], v197 offset:37376
	ds_read_b64_tr_b16 v[176:177], v197 offset:37888
	ds_read_b64_tr_b16 v[178:179], v197 offset:38400
	ds_read_b128 v[172:175], v241 offset:20992
	ds_read_b128 v[168:171], v241 offset:23040
	ds_read_b128 v[164:167], v241 offset:25088
	ds_read_b128 v[10:13], v241 offset:27136
	ds_read_b128 v[6:9], v241 offset:29184
	ds_read_b128 v[2:5], v241 offset:31232
	v_max3_f32 v97, v98, s68, v99
	v_max3_f32 v97, v97, v100, v101
	v_max3_f32 v97, v97, v102, v103
	v_max3_f32 v97, v97, v104, v105
	v_max3_f32 v97, v97, v106, v107
	v_max3_f32 v97, v97, v108, v109
	v_max3_f32 v97, v97, v110, v111
	v_max3_f32 v97, v97, v112, v113
	v_mov_b32_e32 v114, v97
	s_nop 1
	v_permlane32_swap_b32_e32 v97, v114
	v_max_f32_e32 v97, v97, v114
	v_mul_f32_e32 v97, 0x3e16c740, v97
	v_max_f32_e32 v114, v15, v15
	v_max_f32_e32 v200, v114, v97
	v_add_f32_e32 v97, 0x41000000, v15
	v_cmp_gt_f32_e32 vcc, v200, v97
	s_cbranch_vccz .LBB0_623
	v_sub_f32_e32 v14, v15, v200
	v_exp_f32_e32 v14, v14
	s_nop 0
	v_mul_f32_e32 v199, v199, v14
	v_pk_mul_f32 v[78:79], v[78:79], v[14:15] op_sel_hi:[1,0]
	v_pk_mul_f32 v[76:77], v[76:77], v[14:15] op_sel_hi:[1,0]
	v_pk_mul_f32 v[74:75], v[74:75], v[14:15] op_sel_hi:[1,0]
	v_pk_mul_f32 v[72:73], v[72:73], v[14:15] op_sel_hi:[1,0]
	v_pk_mul_f32 v[70:71], v[70:71], v[14:15] op_sel_hi:[1,0]
	v_pk_mul_f32 v[68:69], v[68:69], v[14:15] op_sel_hi:[1,0]
	v_pk_mul_f32 v[66:67], v[66:67], v[14:15] op_sel_hi:[1,0]
	v_pk_mul_f32 v[64:65], v[64:65], v[14:15] op_sel_hi:[1,0]
	v_pk_mul_f32 v[62:63], v[62:63], v[14:15] op_sel_hi:[1,0]
	v_pk_mul_f32 v[60:61], v[60:61], v[14:15] op_sel_hi:[1,0]
	v_pk_mul_f32 v[58:59], v[58:59], v[14:15] op_sel_hi:[1,0]
	v_pk_mul_f32 v[56:57], v[56:57], v[14:15] op_sel_hi:[1,0]
	v_pk_mul_f32 v[54:55], v[54:55], v[14:15] op_sel_hi:[1,0]
	v_pk_mul_f32 v[52:53], v[52:53], v[14:15] op_sel_hi:[1,0]
	v_pk_mul_f32 v[50:51], v[50:51], v[14:15] op_sel_hi:[1,0]
	v_pk_mul_f32 v[48:49], v[48:49], v[14:15] op_sel_hi:[1,0]
	v_xor_b32_e32 v14, 0x80000000, v200
	s_branch .LBB0_624

; __device__ __forceinline__ unsigned cvtpk(float lo, float hi) { f32x2 v = {lo, hi}; bf16x2_t b = __builtin_convertvector(v, bf16x2_t); return __builtin_bit_cast(unsigned, b); }
; __device__ __forceinline__ float fast_exp2(float x) { return __builtin_amdgcn_exp2f(x); }
; template <int MODE, int NQ>
; __device__ __forceinline__ void attn_unit(LAS unsigned char* lds, const Params& P, int layer, int b, int h, int qb) {
;     ...
;                     float rm = -3e38f;
; #pragma unroll
;                     for (int r = 0; r < 16; ++r) rm = fmaxf(rm, s0[r]);
;                     rm = xmax(rm);
;                     mn = fmaxf(mrun[cc], rm * c);
;                 }
;                 if (__any(mn > mrun[cc] + AT_THR)) {
;                     const float al = fast_exp2(mrun[cc] - mn); lrun[cc] *= al;
; #pragma unroll
;                     for (int r = 0; r < 16; ++r) { o[cc][0][r] *= al; o[cc][1][r] *= al; }
;                     mrun[cc] = mn;
;                 }
;                 mn = mrun[cc];
;                 if (MODE != 0) rmrel[cc] -= mn;
;                 const bool dead = (MODE != 0) && __all(rmrel[cc] < -136.f);
;                 if (dead) { pw[cc][0] = zero8; pw[cc][1] = zero8; }
;                 else {
;                     alive = true;
;                     if (MODE != 0) {
; #pragma unroll
;                         for (int r = 0; r < 16; ++r) s0[r] = fast_exp2(s0[r] - mn);
;                     } else {
;                         const float nm = -mn;
; #pragma unroll
;                         for (int r = 0; r < 16; ++r) s0[r] = fast_exp2(__builtin_fmaf(s0[r], c, nm));
;                     }
;                     u32x4 w;
;                     w.x = cvtpk(s0[0], s0[1]); w.y = cvtpk(s0[2], s0[3]); w.z = cvtpk(s0[4], s0[5]); w.w = cvtpk(s0[6], s0[7]); pw[cc][0] = __builtin_bit_cast(bf16x8, w);
;                     w.x = cvtpk(s0[8], s0[9]); w.y = cvtpk(s0[10], s0[11]); w.z = cvtpk(s0[12], s0[13]); w.w = cvtpk(s0[14], s0[15]); pw[cc][1] = __builtin_bit_cast(bf16x8, w);
;                     f32x16 t = __builtin_amdgcn_mfma_f32_32x32x16_bf16(ones8, pw[cc][0], f32x16{}, 0, 0, 0);
;                     t = __builtin_amdgcn_mfma_f32_32x32x16_bf16(ones8, pw[cc][1], t, 0, 0, 0);
;                     lrun[cc] += t[0];
;                 }
.LBB0_624:
	s_mov_b32 s62, s60
	s_mov_b32 s63, s60
	v_add_f32_e32 v198, v198, v96
	v_fmamk_f32 v15, v98, 0x3e16c740, v14
	v_fmamk_f32 v96, v99, 0x3e16c740, v14
	v_fmamk_f32 v97, v100, 0x3e16c740, v14
	v_fmamk_f32 v98, v101, 0x3e16c740, v14
	v_fmamk_f32 v99, v102, 0x3e16c740, v14
	v_fmamk_f32 v100, v103, 0x3e16c740, v14
	v_fmamk_f32 v101, v104, 0x3e16c740, v14
	v_fmamk_f32 v102, v105, 0x3e16c740, v14
	s_mov_b32 s61, s60
	v_mov_b64_e32 v[204:205], s[62:63]
	v_exp_f32_e32 v15, v15
	v_exp_f32_e32 v96, v96
	v_exp_f32_e32 v97, v97
	v_exp_f32_e32 v98, v98
	v_exp_f32_e32 v99, v99
	v_exp_f32_e32 v100, v100
	v_exp_f32_e32 v101, v101
	v_exp_f32_e32 v102, v102
	v_fmamk_f32 v103, v106, 0x3e16c740, v14
	v_fmamk_f32 v104, v107, 0x3e16c740, v14
	v_fmamk_f32 v105, v108, 0x3e16c740, v14
	v_fmamk_f32 v106, v109, 0x3e16c740, v14
	v_fmamk_f32 v107, v110, 0x3e16c740, v14
	v_fmamk_f32 v108, v111, 0x3e16c740, v14
	v_fmamk_f32 v109, v112, 0x3e16c740, v14
	v_fmamk_f32 v110, v113, 0x3e16c740, v14
	v_mov_b64_e32 v[202:203], s[60:61]
	v_exp_f32_e32 v103, v103
	v_exp_f32_e32 v104, v104
	v_exp_f32_e32 v105, v105
	v_exp_f32_e32 v106, v106
	v_exp_f32_e32 v107, v107
	v_exp_f32_e32 v108, v108
	v_exp_f32_e32 v109, v109
	v_exp_f32_e32 v110, v110
	v_cvt_pk_bf16_f32 v192, v15, v96
	v_cvt_pk_bf16_f32 v193, v97, v98
	v_cvt_pk_bf16_f32 v194, v99, v100
	v_cvt_pk_bf16_f32 v195, v101, v102
	v_cvt_pk_bf16_f32 v112, v103, v104
	v_cvt_pk_bf16_f32 v113, v105, v106
	v_cvt_pk_bf16_f32 v114, v107, v108
	v_cvt_pk_bf16_f32 v115, v109, v110
	v_mfma_f32_32x32x16_bf16 v[96:111], v[202:205], v[192:195], 0
	v_max3_f32 v15, v80, s68, v81
	v_max3_f32 v15, v15, v82, v83
	v_max3_f32 v15, v15, v84, v85
	v_max3_f32 v15, v15, v86, v87
	v_max3_f32 v15, v15, v88, v89
	v_max3_f32 v15, v15, v90, v91
	v_max3_f32 v15, v15, v92, v93
	v_mfma_f32_32x32x16_bf16 v[96:111], v[202:205], v[112:115], v[96:111]
	v_max3_f32 v15, v15, v94, v95
	s_nop 10
	v_mov_b32_e32 v97, v15
	s_nop 1
	v_permlane32_swap_b32_e32 v15, v97
	v_max_f32_e32 v15, v15, v97
	v_mul_f32_e32 v15, 0x3e16c740, v15
	v_max_f32_e32 v15, v0, v15
	v_add_f32_e32 v97, 0x41000000, v0
	v_cmp_gt_f32_e32 vcc, v15, v97
	s_cbranch_vccz .LBB0_626
	v_sub_f32_e32 v0, v0, v15
	v_exp_f32_e32 v0, v0
	v_xor_b32_e32 v196, 0x80000000, v15
	v_mul_f32_e32 v198, v198, v0
	v_pk_mul_f32 v[46:47], v[46:47], v[0:1] op_sel_hi:[1,0]
	v_pk_mul_f32 v[44:45], v[44:45], v[0:1] op_sel_hi:[1,0]
	v_pk_mul_f32 v[42:43], v[42:43], v[0:1] op_sel_hi:[1,0]
	v_pk_mul_f32 v[40:41], v[40:41], v[0:1] op_sel_hi:[1,0]
	v_pk_mul_f32 v[38:39], v[38:39], v[0:1] op_sel_hi:[1,0]
	v_pk_mul_f32 v[36:37], v[36:37], v[0:1] op_sel_hi:[1,0]
	v_pk_mul_f32 v[34:35], v[34:35], v[0:1] op_sel_hi:[1,0]
	v_pk_mul_f32 v[32:33], v[32:33], v[0:1] op_sel_hi:[1,0]
	v_pk_mul_f32 v[30:31], v[30:31], v[0:1] op_sel_hi:[1,0]
	v_pk_mul_f32 v[28:29], v[28:29], v[0:1] op_sel_hi:[1,0]
	v_pk_mul_f32 v[26:27], v[26:27], v[0:1] op_sel_hi:[1,0]
	v_pk_mul_f32 v[24:25], v[24:25], v[0:1] op_sel_hi:[1,0]
	v_pk_mul_f32 v[22:23], v[22:23], v[0:1] op_sel_hi:[1,0]
	v_pk_mul_f32 v[20:21], v[20:21], v[0:1] op_sel_hi:[1,0]
	v_pk_mul_f32 v[18:19], v[18:19], v[0:1] op_sel_hi:[1,0]
	v_pk_mul_f32 v[16:17], v[16:17], v[0:1] op_sel_hi:[1,0]
	s_branch .LBB0_627

; template <int MODE, int NQ>
; __device__ __forceinline__ void attn_unit(LAS unsigned char* lds, const Params& P, int layer, int b, int h, int qb) {
;     ...
;             f32x16 sc[NC];
; #pragma unroll
;             for (int cc = 0; cc < NC; ++cc) {
;                 sc[cc] = f32x16{};
; #pragma unroll
;                 for (int d0 = 0; d0 < ND0; ++d0) sc[cc] = __builtin_amdgcn_mfma_f32_32x32x16_bf16(kf[(cc % NMAP) * ND0 + d0], qf[cc][d0], sc[cc], 0, 0, 0);
;             }
;             __builtin_amdgcn_sched_barrier(0);
;             AT_VLOAD(cur, hf);
;             if (hf == 0) AT_KLOAD(cur, 1); else if (it + 1 < NT) AT_KLOAD(nxt, 0);
;             __builtin_amdgcn_sched_barrier(0);
;             bf16x8 pw[NC][2]; float rmrel[NC]; bool alive = false;
; #pragma unroll
;             for (int cc = 0; cc < NC; ++cc) {
;                 f32x16& s0 = sc[cc];
;                 float mn;
;     ...
;                         for (int r = 0; r < 16; ++r) s0[r] = fast_exp2(s0[r] - mn);
;                     } else {
;                         const float nm = -mn;
; #pragma unroll
;                         for (int r = 0; r < 16; ++r) s0[r] = fast_exp2(__builtin_fmaf(s0[r], c, nm));
;                     }
;                     u32x4 w;
;                     w.x = cvtpk(s0[0], s0[1]); w.y = cvtpk(s0[2], s0[3]); w.z = cvtpk(s0[4], s0[5]); w.w = cvtpk(s0[6], s0[7]); pw[cc][0] = __builtin_bit_cast(bf16x8, w);
;                     w.x = cvtpk(s0[8], s0[9]); w.y = cvtpk(s0[10], s0[11]); w.z = cvtpk(s0[12], s0[13]); w.w = cvtpk(s0[14], s0[15]); pw[cc][1] = __builtin_bit_cast(bf16x8, w);
;                     f32x16 t = __builtin_amdgcn_mfma_f32_32x32x16_bf16(ones8, pw[cc][0], f32x16{}, 0, 0, 0);
;                     t = __builtin_amdgcn_mfma_f32_32x32x16_bf16(ones8, pw[cc][1], t, 0, 0, 0);
;                     lrun[cc] += t[0];
;                 }
;             }
;             if (alive)
; #pragma unroll
;             for (int dv = 0; dv < 2; ++dv)
; #pragma unroll
;                 for (int k2 = 0; k2 < 2; ++k2) {
;                     const s16x4 lo = vlo[dv * 2 + k2], hh = vhi[dv * 2 + k2];
;                     const bf16x8 vf = (bf16x8){lo[0], lo[1], lo[2], lo[3], hh[0], hh[1], hh[2], hh[3]};
; #pragma unroll
;                     for (int cc = 0; cc < NC; ++cc) o[cc][dv] = __builtin_amdgcn_mfma_f32_32x32x16_bf16(vf, pw[cc][k2], o[cc][dv], 0, 0, 0);
;                 }
.LBB0_627:
	v_fmamk_f32 v80, v80, 0x3e16c740, v196
	v_fmamk_f32 v81, v81, 0x3e16c740, v196
	v_fmamk_f32 v82, v82, 0x3e16c740, v196
	v_fmamk_f32 v83, v83, 0x3e16c740, v196
	v_fmamk_f32 v84, v84, 0x3e16c740, v196
	v_fmamk_f32 v85, v85, 0x3e16c740, v196
	v_fmamk_f32 v88, v88, 0x3e16c740, v196
	v_fmamk_f32 v89, v89, 0x3e16c740, v196
	v_fmamk_f32 v90, v90, 0x3e16c740, v196
	v_fmamk_f32 v91, v91, 0x3e16c740, v196
	v_exp_f32_e32 v80, v80
	v_exp_f32_e32 v81, v81
	v_exp_f32_e32 v82, v82
	v_exp_f32_e32 v83, v83
	v_exp_f32_e32 v84, v84
	v_exp_f32_e32 v85, v85
	v_exp_f32_e32 v88, v88
	v_exp_f32_e32 v89, v89
	v_exp_f32_e32 v90, v90
	v_exp_f32_e32 v91, v91
	v_fmamk_f32 v86, v86, 0x3e16c740, v196
	v_fmamk_f32 v87, v87, 0x3e16c740, v196
	v_cvt_pk_bf16_f32 v80, v80, v81
	v_cvt_pk_bf16_f32 v81, v82, v83
	v_cvt_pk_bf16_f32 v82, v84, v85
	v_cvt_pk_bf16_f32 v84, v88, v89
	v_cvt_pk_bf16_f32 v85, v90, v91
	v_mov_b64_e32 v[90:91], s[62:63]
	v_exp_f32_e32 v86, v86
	v_exp_f32_e32 v87, v87
	v_mov_b64_e32 v[88:89], s[60:61]
	v_add_f32_e32 v0, v199, v96
	s_waitcnt lgkmcnt(12)
	v_mfma_f32_32x32x16_bf16 v[64:79], v[188:191], v[192:195], v[64:79]
	v_cvt_pk_bf16_f32 v83, v86, v87
	v_fmamk_f32 v92, v92, 0x3e16c740, v196
	v_fmamk_f32 v93, v93, 0x3e16c740, v196
	v_fmamk_f32 v94, v94, 0x3e16c740, v196
	v_fmamk_f32 v95, v95, 0x3e16c740, v196
	v_exp_f32_e32 v92, v92
	v_exp_f32_e32 v93, v93
	v_mfma_f32_32x32x16_bf16 v[96:111], v[88:91], v[80:83], 0
	v_exp_f32_e32 v94, v94
	v_exp_f32_e32 v95, v95
	v_cvt_pk_bf16_f32 v86, v92, v93
	v_cvt_pk_bf16_f32 v87, v94, v95
	v_mfma_f32_32x32x16_bf16 v[32:47], v[188:191], v[80:83], v[32:47]
	s_waitcnt lgkmcnt(8)
	v_mfma_f32_32x32x16_bf16 v[48:63], v[180:183], v[192:195], v[48:63]
	v_mfma_f32_32x32x16_bf16 v[16:31], v[180:183], v[80:83], v[16:31]
	v_mfma_f32_32x32x16_bf16 v[96:111], v[88:91], v[84:87], v[96:111]
	v_mfma_f32_32x32x16_bf16 v[64:79], v[184:187], v[112:115], v[64:79]
	v_mfma_f32_32x32x16_bf16 v[32:47], v[184:187], v[84:87], v[32:47]
	s_waitcnt lgkmcnt(6)
	v_mfma_f32_32x32x16_bf16 v[48:63], v[176:179], v[112:115], v[48:63]
	v_mfma_f32_32x32x16_bf16 v[16:31], v[176:179], v[84:87], v[16:31]
	s_waitcnt lgkmcnt(5)
	v_mfma_f32_32x32x16_bf16 v[98:113], v[172:175], v[160:163], 0
	v_mfma_f32_32x32x16_bf16 v[80:95], v[172:175], v[156:159], 0
	s_waitcnt lgkmcnt(4)
	v_mfma_f32_32x32x16_bf16 v[98:113], v[168:171], v[140:143], v[98:113]
	v_mfma_f32_32x32x16_bf16 v[80:95], v[168:171], v[152:155], v[80:95]
	s_waitcnt lgkmcnt(3)
	v_mfma_f32_32x32x16_bf16 v[98:113], v[164:167], v[132:135], v[98:113]
	v_mfma_f32_32x32x16_bf16 v[80:95], v[164:167], v[148:151], v[80:95]
	s_waitcnt lgkmcnt(2)
	v_mfma_f32_32x32x16_bf16 v[98:113], v[10:13], v[128:131], v[98:113]
	v_mfma_f32_32x32x16_bf16 v[80:95], v[10:13], v[144:147], v[80:95]
	s_waitcnt lgkmcnt(1)
	v_mfma_f32_32x32x16_bf16 v[98:113], v[6:9], v[124:127], v[98:113]
	v_mfma_f32_32x32x16_bf16 v[80:95], v[6:9], v[136:139], v[80:95]
	s_waitcnt lgkmcnt(0)
	v_mfma_f32_32x32x16_bf16 v[98:113], v[2:5], v[120:123], v[98:113]
	v_mfma_f32_32x32x16_bf16 v[80:95], v[2:5], v[116:119], v[80:95]
	ds_read_b64_tr_b16 v[114:115], v197 offset:34816
	ds_read_b64_tr_b16 v[116:117], v197 offset:35328
	ds_read_b64_tr_b16 v[10:11], v197 offset:35840
	ds_read_b64_tr_b16 v[12:13], v197 offset:36352
	ds_read_b64_tr_b16 v[6:7], v197 offset:38912
	ds_read_b64_tr_b16 v[8:9], v197 offset:39424
	ds_read_b64_tr_b16 v[2:3], v197 offset:39936
	ds_read_b64_tr_b16 v[4:5], v197 offset:40448
	s_nop 2
	v_max3_f32 v97, v98, s68, v99
	v_max3_f32 v97, v97, v100, v101
	v_max3_f32 v97, v97, v102, v103
	v_max3_f32 v97, v97, v104, v105
	v_max3_f32 v97, v97, v106, v107
	v_max3_f32 v97, v97, v108, v109
	v_max3_f32 v97, v97, v110, v111
	v_max3_f32 v97, v97, v112, v113
	v_mov_b32_e32 v118, v97
	s_nop 1
	v_permlane32_swap_b32_e32 v97, v118
	v_max_f32_e32 v97, v97, v118
	v_mul_f32_e32 v97, 0x3e16c740, v97
	v_max_f32_e32 v97, v200, v97
	v_add_f32_e32 v118, 0x41000000, v200
	v_cmp_gt_f32_e32 vcc, v97, v118
	s_cbranch_vccz .LBB0_629
	v_sub_f32_e32 v14, v200, v97
	v_exp_f32_e32 v14, v14
	s_nop 0
	v_mul_f32_e32 v0, v0, v14
	v_pk_mul_f32 v[78:79], v[78:79], v[14:15] op_sel_hi:[1,0]
	v_pk_mul_f32 v[76:77], v[76:77], v[14:15] op_sel_hi:[1,0]
	v_pk_mul_f32 v[74:75], v[74:75], v[14:15] op_sel_hi:[1,0]
	v_pk_mul_f32 v[72:73], v[72:73], v[14:15] op_sel_hi:[1,0]
	v_pk_mul_f32 v[70:71], v[70:71], v[14:15] op_sel_hi:[1,0]
	v_pk_mul_f32 v[68:69], v[68:69], v[14:15] op_sel_hi:[1,0]
	v_pk_mul_f32 v[66:67], v[66:67], v[14:15] op_sel_hi:[1,0]
	v_pk_mul_f32 v[64:65], v[64:65], v[14:15] op_sel_hi:[1,0]
	v_pk_mul_f32 v[62:63], v[62:63], v[14:15] op_sel_hi:[1,0]
	v_pk_mul_f32 v[60:61], v[60:61], v[14:15] op_sel_hi:[1,0]
	v_pk_mul_f32 v[58:59], v[58:59], v[14:15] op_sel_hi:[1,0]
	v_pk_mul_f32 v[56:57], v[56:57], v[14:15] op_sel_hi:[1,0]
	v_pk_mul_f32 v[54:55], v[54:55], v[14:15] op_sel_hi:[1,0]
	v_pk_mul_f32 v[52:53], v[52:53], v[14:15] op_sel_hi:[1,0]
	v_pk_mul_f32 v[50:51], v[50:51], v[14:15] op_sel_hi:[1,0]
	v_pk_mul_f32 v[48:49], v[48:49], v[14:15] op_sel_hi:[1,0]
	v_xor_b32_e32 v14, 0x80000000, v97
; __device__ __forceinline__ unsigned cvtpk(float lo, float hi) { f32x2 v = {lo, hi}; bf16x2_t b = __builtin_convertvector(v, bf16x2_t); return __builtin_bit_cast(unsigned, b); }
; __device__ __forceinline__ float fast_exp2(float x) { return __builtin_amdgcn_exp2f(x); }
; template <int MODE, int NQ>
; __device__ __forceinline__ void attn_unit(LAS unsigned char* lds, const Params& P, int layer, int b, int h, int qb) {
;     ...
;                     float rm = -3e38f;
; #pragma unroll
;                     for (int r = 0; r < 16; ++r) rm = fmaxf(rm, s0[r]);
;                     rm = xmax(rm);
;                     mn = fmaxf(mrun[cc], rm * c);
;                 }
;                 if (__any(mn > mrun[cc] + AT_THR)) {
;                     const float al = fast_exp2(mrun[cc] - mn); lrun[cc] *= al;
; #pragma unroll
;                     for (int r = 0; r < 16; ++r) { o[cc][0][r] *= al; o[cc][1][r] *= al; }
;                     mrun[cc] = mn;
;                 }
;                 mn = mrun[cc];
;                 if (MODE != 0) rmrel[cc] -= mn;
;                 const bool dead = (MODE != 0) && __all(rmrel[cc] < -136.f);
;                 if (dead) { pw[cc][0] = zero8; pw[cc][1] = zero8; }
;                 else {
;                     alive = true;
;                     if (MODE != 0) {
; #pragma unroll
;                         for (int r = 0; r < 16; ++r) s0[r] = fast_exp2(s0[r] - mn);
;                     } else {
;                         const float nm = -mn;
; #pragma unroll
;                         for (int r = 0; r < 16; ++r) s0[r] = fast_exp2(__builtin_fmaf(s0[r], c, nm));
;                     }
;                     u32x4 w;
;                     w.x = cvtpk(s0[0], s0[1]); w.y = cvtpk(s0[2], s0[3]); w.z = cvtpk(s0[4], s0[5]); w.w = cvtpk(s0[6], s0[7]); pw[cc][0] = __builtin_bit_cast(bf16x8, w);
;                     w.x = cvtpk(s0[8], s0[9]); w.y = cvtpk(s0[10], s0[11]); w.z = cvtpk(s0[12], s0[13]); w.w = cvtpk(s0[14], s0[15]); pw[cc][1] = __builtin_bit_cast(bf16x8, w);
;                     f32x16 t = __builtin_amdgcn_mfma_f32_32x32x16_bf16(ones8, pw[cc][0], f32x16{}, 0, 0, 0);
;                     t = __builtin_amdgcn_mfma_f32_32x32x16_bf16(ones8, pw[cc][1], t, 0, 0, 0);
;                     lrun[cc] += t[0];
;                 }
.LBB0_629:
	s_mov_b32 s62, s60
	s_mov_b32 s63, s60
	v_add_f32_e32 v126, v198, v96
	v_fmamk_f32 v96, v98, 0x3e16c740, v14
	v_fmamk_f32 v97, v99, 0x3e16c740, v14
	v_fmamk_f32 v98, v100, 0x3e16c740, v14
	v_fmamk_f32 v99, v101, 0x3e16c740, v14
	v_fmamk_f32 v100, v102, 0x3e16c740, v14
	v_fmamk_f32 v101, v103, 0x3e16c740, v14
	v_fmamk_f32 v102, v104, 0x3e16c740, v14
	v_fmamk_f32 v103, v105, 0x3e16c740, v14
	s_mov_b32 s61, s60
	v_mov_b64_e32 v[130:131], s[62:63]
	v_exp_f32_e32 v96, v96
	v_exp_f32_e32 v97, v97
	v_exp_f32_e32 v98, v98
	v_exp_f32_e32 v99, v99
	v_exp_f32_e32 v100, v100
	v_exp_f32_e32 v101, v101
	v_exp_f32_e32 v102, v102
	v_exp_f32_e32 v103, v103
	v_fmamk_f32 v104, v106, 0x3e16c740, v14
	v_fmamk_f32 v105, v107, 0x3e16c740, v14
	v_fmamk_f32 v106, v108, 0x3e16c740, v14
	v_fmamk_f32 v107, v109, 0x3e16c740, v14
	v_fmamk_f32 v108, v110, 0x3e16c740, v14
	v_fmamk_f32 v109, v111, 0x3e16c740, v14
	v_fmamk_f32 v110, v112, 0x3e16c740, v14
	v_fmac_f32_e32 v14, 0x3e16c740, v113
	v_mov_b64_e32 v[128:129], s[60:61]
	v_exp_f32_e32 v104, v104
	v_exp_f32_e32 v105, v105
	v_exp_f32_e32 v106, v106
	v_exp_f32_e32 v107, v107
	v_exp_f32_e32 v108, v108
	v_exp_f32_e32 v109, v109
	v_exp_f32_e32 v110, v110
	v_exp_f32_e32 v14, v14
	v_cvt_pk_bf16_f32 v122, v96, v97
	v_cvt_pk_bf16_f32 v123, v98, v99
	v_cvt_pk_bf16_f32 v124, v100, v101
	v_cvt_pk_bf16_f32 v125, v102, v103
	v_cvt_pk_bf16_f32 v118, v104, v105
	v_cvt_pk_bf16_f32 v119, v106, v107
	v_cvt_pk_bf16_f32 v120, v108, v109
	v_cvt_pk_bf16_f32 v121, v110, v14
	v_mfma_f32_32x32x16_bf16 v[96:111], v[128:131], v[122:125], 0
	v_max3_f32 v14, v80, s68, v81
	v_max3_f32 v14, v14, v82, v83
	v_max3_f32 v14, v14, v84, v85
	v_max3_f32 v14, v14, v86, v87
	v_max3_f32 v14, v14, v88, v89
	v_max3_f32 v14, v14, v90, v91
	v_max3_f32 v14, v14, v92, v93
	v_mfma_f32_32x32x16_bf16 v[96:111], v[128:131], v[118:121], v[96:111]
	v_max3_f32 v14, v14, v94, v95
	s_nop 10
	v_mov_b32_e32 v97, v14
	s_nop 1
	v_permlane32_swap_b32_e32 v14, v97
	v_max_f32_e32 v14, v14, v97
	v_mul_f32_e32 v14, 0x3e16c740, v14
	v_max_f32_e32 v14, v15, v14
	v_add_f32_e32 v97, 0x41000000, v15
	v_cmp_gt_f32_e32 vcc, v14, v97
	s_cbranch_vccz .LBB0_579
	v_sub_f32_e32 v15, v15, v14
	v_exp_f32_e32 v98, v15
	v_xor_b32_e32 v196, 0x80000000, v14
	v_mul_f32_e32 v126, v126, v98
	v_pk_mul_f32 v[46:47], v[46:47], v[98:99] op_sel_hi:[1,0]
	v_pk_mul_f32 v[44:45], v[44:45], v[98:99] op_sel_hi:[1,0]
	v_pk_mul_f32 v[42:43], v[42:43], v[98:99] op_sel_hi:[1,0]
	v_pk_mul_f32 v[40:41], v[40:41], v[98:99] op_sel_hi:[1,0]
	v_pk_mul_f32 v[38:39], v[38:39], v[98:99] op_sel_hi:[1,0]
	v_pk_mul_f32 v[36:37], v[36:37], v[98:99] op_sel_hi:[1,0]
	v_pk_mul_f32 v[34:35], v[34:35], v[98:99] op_sel_hi:[1,0]
	v_pk_mul_f32 v[32:33], v[32:33], v[98:99] op_sel_hi:[1,0]
	v_pk_mul_f32 v[30:31], v[30:31], v[98:99] op_sel_hi:[1,0]
	v_pk_mul_f32 v[28:29], v[28:29], v[98:99] op_sel_hi:[1,0]
	v_pk_mul_f32 v[26:27], v[26:27], v[98:99] op_sel_hi:[1,0]
	v_pk_mul_f32 v[24:25], v[24:25], v[98:99] op_sel_hi:[1,0]
	v_pk_mul_f32 v[22:23], v[22:23], v[98:99] op_sel_hi:[1,0]
	v_pk_mul_f32 v[20:21], v[20:21], v[98:99] op_sel_hi:[1,0]
	v_pk_mul_f32 v[18:19], v[18:19], v[98:99] op_sel_hi:[1,0]
	v_pk_mul_f32 v[16:17], v[16:17], v[98:99] op_sel_hi:[1,0]
	s_branch .LBB0_579

; #define PG8_BAR __builtin_amdgcn_s_barrier()
; template <class Epi>
; __device__ __forceinline__ void gemm_phase(LAS unsigned char* lds, const Gemm g, const Epi& E) {
;     ...
;         if (!has_next) break;
; #pragma unroll
;         for (int a = 0; a < 2; ++a)
; #pragma unroll
;             for (int b = 0; b < 2; ++b)
; #pragma unroll
;                 for (int m = 0; m < 4; ++m)
; #pragma unroll
;                     for (int n = 0; n < 2; ++n) acc[a][b][m][n] = (f32x4){0.f, 0.f, 0.f, 0.f};
;         cur = nxt; cA = nA; cB = nB; ++ui;
;         if (wr == 1) PG8_BAR;
.LBB0_699:
	s_andn2_b64 vcc, exec, s[38:39]
	s_waitcnt lgkmcnt(0)
	s_cbranch_vccnz .LBB0_702
	s_add_u32 s58, s58, 0x80
	s_addc_u32 s59, s59, 0
	s_add_u32 s20, s62, 0x100
	s_addc_u32 s21, s63, 0
	s_mov_b32 s62, 0
	v_mov_b64_e32 v[2:3], 0
	v_mov_b64_e32 v[4:5], 0
	v_mov_b64_e32 v[6:7], 0
	v_mov_b64_e32 v[8:9], 0
	v_mov_b64_e32 v[10:11], 0
	v_mov_b64_e32 v[12:13], 0
	v_mov_b64_e32 v[14:15], 0
	v_mov_b64_e32 v[16:17], 0
	v_mov_b64_e32 v[18:19], 0
	v_mov_b64_e32 v[20:21], 0
	v_mov_b64_e32 v[22:23], 0
	v_mov_b64_e32 v[24:25], 0
	v_mov_b64_e32 v[26:27], 0
	v_mov_b64_e32 v[28:29], 0
	v_mov_b64_e32 v[30:31], 0
	v_mov_b64_e32 v[32:33], 0
	v_mov_b64_e32 v[34:35], 0
	v_mov_b64_e32 v[36:37], 0
	v_mov_b64_e32 v[38:39], 0
	v_mov_b64_e32 v[40:41], 0
	v_mov_b64_e32 v[42:43], 0
	v_mov_b64_e32 v[44:45], 0
	v_mov_b64_e32 v[46:47], 0
	v_mov_b64_e32 v[48:49], 0
	v_mov_b64_e32 v[50:51], 0
	v_mov_b64_e32 v[52:53], 0
	v_mov_b64_e32 v[54:55], 0
	v_mov_b64_e32 v[56:57], 0
	v_mov_b64_e32 v[58:59], 0
	v_mov_b64_e32 v[60:61], 0
	v_mov_b64_e32 v[62:63], 0
	v_mov_b64_e32 v[64:65], 0
	v_mov_b64_e32 v[66:67], 0
	v_mov_b64_e32 v[68:69], 0
	v_mov_b64_e32 v[70:71], 0
	v_mov_b64_e32 v[72:73], 0
	v_mov_b64_e32 v[74:75], 0
	v_mov_b64_e32 v[76:77], 0
	v_mov_b64_e32 v[78:79], 0
	v_mov_b64_e32 v[80:81], 0
	v_mov_b64_e32 v[82:83], 0
	v_mov_b64_e32 v[84:85], 0
	v_mov_b64_e32 v[86:87], 0
	v_mov_b64_e32 v[88:89], 0
	v_mov_b64_e32 v[90:91], 0
	v_mov_b64_e32 v[92:93], 0
	v_mov_b64_e32 v[94:95], 0
	v_mov_b64_e32 v[96:97], 0
	v_mov_b64_e32 v[98:99], 0
	v_mov_b64_e32 v[100:101], 0
	v_mov_b64_e32 v[102:103], 0
	v_mov_b64_e32 v[104:105], 0
	v_mov_b64_e32 v[106:107], 0
	v_mov_b64_e32 v[108:109], 0
	v_mov_b64_e32 v[110:111], 0
	v_mov_b64_e32 v[112:113], 0
	v_mov_b64_e32 v[114:115], 0
	v_mov_b64_e32 v[116:117], 0
	v_mov_b64_e32 v[118:119], 0
	v_mov_b64_e32 v[120:121], 0
	v_mov_b64_e32 v[122:123], 0
	v_mov_b64_e32 v[124:125], 0
	v_mov_b64_e32 v[126:127], 0
	v_mov_b64_e32 v[128:129], 0

; __device__ __forceinline__ unsigned cvtpk(float lo, float hi) { f32x2 v = {lo, hi}; bf16x2_t b = __builtin_convertvector(v, bf16x2_t); return __builtin_bit_cast(unsigned, b); }
;     __device__ __forceinline__ void operator()(AccRef acc, const Unit& u, int wr, int wc, int fr, int fq) const {
;         const int row0 = u.pm * 256 + wr * 64 + fr, col0 = u.pn * 256 + wc * 32 + 8 * fq;
; #pragma unroll
;         for (int ai = 0; ai < 2; ++ai)
; #pragma unroll
;             for (int m = 0; m < 4; ++m) {
;                 const int row = row0 + ai * 128 + m * 16; bf16_t* rowp = XB + (size_t)row * DM + col0; float s = 0.f;
; #pragma unroll
;                 for (int bj = 0; bj < 2; ++bj) {
;                     const u32x4 xo = *(const u32x4*)(rowp + bj * 128);
;                     float v[8];
; #pragma unroll
;                     for (int k = 0; k < 4; ++k) { v[2 * k] = __uint_as_float(xo[k] << 16) + acc[ai][bj][m][k >> 1][(2 * k) & 3]; v[2 * k + 1] = __uint_as_float(xo[k] & 0xffff0000u) + acc[ai][bj][m][k >> 1][(2 * k + 1) & 3]; }
; #pragma unroll
;                     for (int k = 0; k < 8; ++k) s += v[k] * v[k];
;                     u32x4 w; w.x = cvtpk(v[0], v[1]); w.y = cvtpk(v[2], v[3]); w.z = cvtpk(v[4], v[5]); w.w = cvtpk(v[6], v[7]);
;                     st16_wt(rowp + bj * 128, w);
;                 }
;                 s += __shfl_xor(s, 16); s += __shfl_xor(s, 32);
;                 if (fq == 0) red[(ai * 128 + wr * 64 + m * 16 + fr) * 4 + wc] = s;
;                 asm volatile("" ::: "memory");
.LBB0_704:
	v_and_b32_e32 v144, 64, v213
	v_xor_b32_e32 v143, 16, v213
	v_add_u32_e32 v144, 64, v144
	v_cmp_lt_i32_e32 vcc, v143, v144
	s_lshl_b32 s51, s51, 8
	v_add_u32_e32 v142, s51, v146
	v_cndmask_b32_e32 v143, v213, v143, vcc
	v_lshlrev_b32_e32 v154, 2, v143
	v_xor_b32_e32 v143, 32, v213
	v_cmp_lt_i32_e32 vcc, v143, v144
	v_lshl_or_b32 v140, s50, 8, v148
	v_ashrrev_i32_e32 v141, 31, v140
	v_cndmask_b32_e32 v143, v213, v143, vcc
	v_lshlrev_b32_e32 v153, 2, v143
	v_ashrrev_i32_e32 v143, 31, v142
	v_lshlrev_b64 v[144:145], 11, v[142:143]
	v_lshl_add_u64 v[144:145], s[66:67], 0, v[144:145]
	v_lshl_add_u64 v[144:145], v[140:141], 1, v[144:145]
	global_load_dwordx4 v[156:159], v[144:145], off
	s_waitcnt vmcnt(0)
	v_lshlrev_b32_e32 v160, 16, v156
	v_and_b32_e32 v161, 0xffff0000, v156
	v_pk_add_f32 v[160:161], v[126:127], v[160:161]
	v_lshlrev_b32_e32 v126, 16, v157
	v_and_b32_e32 v127, 0xffff0000, v157
	v_pk_add_f32 v[162:163], v[128:129], v[126:127]
	v_lshlrev_b32_e32 v126, 16, v158
	v_and_b32_e32 v127, 0xffff0000, v158
	v_pk_add_f32 v[164:165], v[122:123], v[126:127]
	v_lshlrev_b32_e32 v122, 16, v159
	v_and_b32_e32 v123, 0xffff0000, v159
	v_pk_add_f32 v[166:167], v[124:125], v[122:123]
	v_cvt_pk_bf16_f32 v156, v160, v161
	v_cvt_pk_bf16_f32 v157, v162, v163
	v_cvt_pk_bf16_f32 v158, v164, v165
	v_cvt_pk_bf16_f32 v159, v166, v167
	global_store_dwordx4 v[144:145], v[156:159], off
	global_load_dwordx4 v[156:159], v[144:145], off offset:256
	v_pk_mul_f32 v[128:129], v[160:161], v[160:161]
	v_pk_mul_f32 v[126:127], v[162:163], v[162:163]
	v_add_f32_e32 v128, v128, v129
	v_add_f32_e32 v126, v126, v128
	v_pk_mul_f32 v[124:125], v[164:165], v[164:165]
	v_add_f32_e32 v126, v127, v126
	v_add_f32_e32 v124, v124, v126
	v_pk_mul_f32 v[122:123], v[166:167], v[166:167]
	v_add_f32_e32 v124, v125, v124
	v_add_f32_e32 v122, v122, v124
	v_add_f32_e32 v122, v123, v122
	s_waitcnt vmcnt(0)
	v_lshlrev_b32_e32 v160, 16, v156
	v_and_b32_e32 v161, 0xffff0000, v156
	v_lshlrev_b32_e32 v156, 16, v157
	v_and_b32_e32 v157, 0xffff0000, v157
	v_pk_add_f32 v[120:121], v[120:121], v[156:157]
	v_lshlrev_b32_e32 v156, 16, v158
	v_and_b32_e32 v157, 0xffff0000, v158
	v_pk_add_f32 v[118:119], v[118:119], v[160:161]
	v_pk_add_f32 v[156:157], v[114:115], v[156:157]
	v_lshlrev_b32_e32 v114, 16, v159
	v_and_b32_e32 v115, 0xffff0000, v159
	v_pk_add_f32 v[158:159], v[116:117], v[114:115]
	v_pk_mul_f32 v[114:115], v[118:119], v[118:119]
	v_pk_mul_f32 v[116:117], v[120:121], v[120:121]
	v_add_f32_e32 v114, v114, v122
	v_add_f32_e32 v114, v115, v114
	v_add_f32_e32 v114, v116, v114
	v_pk_mul_f32 v[160:161], v[156:157], v[156:157]
	v_add_f32_e32 v114, v117, v114
	v_add_f32_e32 v114, v160, v114
	v_pk_mul_f32 v[162:163], v[158:159], v[158:159]
	v_add_f32_e32 v114, v161, v114
	v_add_f32_e32 v114, v162, v114
	v_add_f32_e32 v122, v163, v114
	v_cvt_pk_bf16_f32 v114, v118, v119
	v_cvt_pk_bf16_f32 v115, v120, v121
	v_cvt_pk_bf16_f32 v116, v156, v157
	v_cvt_pk_bf16_f32 v117, v158, v159
	global_store_dwordx4 v[144:145], v[114:117], off offset:256
	ds_bpermute_b32 v114, v154, v122
	s_waitcnt lgkmcnt(0)
	v_add_f32_e32 v114, v122, v114
	ds_bpermute_b32 v115, v153, v114
	s_and_saveexec_b64 s[20:21], s[40:41]
	s_cbranch_execz .LBB0_706
	s_waitcnt lgkmcnt(0)
	v_add_f32_e32 v114, v114, v115
	ds_write_b32 v150, v114
.LBB0_706:
	s_or_b64 exec, exec, s[20:21]
	v_or_b32_e32 v114, 16, v142
	s_waitcnt lgkmcnt(0)
	v_ashrrev_i32_e32 v115, 31, v114
	v_lshlrev_b64 v[114:115], 11, v[114:115]
	v_lshl_add_u64 v[114:115], s[66:67], 0, v[114:115]
	v_lshl_add_u64 v[114:115], v[140:141], 1, v[114:115]
	global_load_dwordx4 v[116:119], v[114:115], off
	s_waitcnt vmcnt(0)
	v_lshlrev_b32_e32 v120, 16, v116
	v_and_b32_e32 v121, 0xffff0000, v116
	v_lshlrev_b32_e32 v116, 16, v117
	v_and_b32_e32 v117, 0xffff0000, v117
	v_pk_add_f32 v[112:113], v[112:113], v[116:117]
	v_lshlrev_b32_e32 v116, 16, v118
	v_and_b32_e32 v117, 0xffff0000, v118
	v_pk_add_f32 v[116:117], v[106:107], v[116:117]
	v_lshlrev_b32_e32 v106, 16, v119
	v_and_b32_e32 v107, 0xffff0000, v119
	v_pk_add_f32 v[110:111], v[110:111], v[120:121]
	v_pk_add_f32 v[118:119], v[108:109], v[106:107]
	v_cvt_pk_bf16_f32 v106, v110, v111
	v_cvt_pk_bf16_f32 v107, v112, v113
	v_cvt_pk_bf16_f32 v108, v116, v117
	v_cvt_pk_bf16_f32 v109, v118, v119
	global_store_dwordx4 v[114:115], v[106:109], off
	global_load_dwordx4 v[106:109], v[114:115], off offset:256
	v_pk_mul_f32 v[120:121], v[110:111], v[110:111]
	v_pk_mul_f32 v[122:123], v[112:113], v[112:113]
	v_pk_mul_f32 v[124:125], v[116:117], v[116:117]
	v_add_f32_e32 v116, v120, v121
	v_add_f32_e32 v116, v122, v116
	v_add_f32_e32 v116, v123, v116
	v_add_f32_e32 v116, v124, v116
	v_pk_mul_f32 v[126:127], v[118:119], v[118:119]
	v_add_f32_e32 v116, v125, v116
	v_add_f32_e32 v116, v126, v116
	v_add_f32_e32 v116, v127, v116
	s_waitcnt vmcnt(0)
	v_lshlrev_b32_e32 v110, 16, v106
	v_and_b32_e32 v111, 0xffff0000, v106
	v_lshlrev_b32_e32 v106, 16, v107
	v_and_b32_e32 v107, 0xffff0000, v107
	v_pk_add_f32 v[104:105], v[104:105], v[106:107]
	v_lshlrev_b32_e32 v106, 16, v108
	v_and_b32_e32 v107, 0xffff0000, v108
	v_pk_add_f32 v[102:103], v[102:103], v[110:111]
	v_pk_add_f32 v[106:107], v[98:99], v[106:107]
	v_lshlrev_b32_e32 v98, 16, v109
	v_and_b32_e32 v99, 0xffff0000, v109
	v_pk_add_f32 v[108:109], v[100:101], v[98:99]
	v_pk_mul_f32 v[98:99], v[102:103], v[102:103]
	v_pk_mul_f32 v[100:101], v[104:105], v[104:105]
	v_add_f32_e32 v98, v98, v116
	v_add_f32_e32 v98, v99, v98
	v_add_f32_e32 v98, v100, v98
	v_pk_mul_f32 v[110:111], v[106:107], v[106:107]
	v_add_f32_e32 v98, v101, v98
	v_add_f32_e32 v98, v110, v98
	v_pk_mul_f32 v[112:113], v[108:109], v[108:109]
	v_add_f32_e32 v98, v111, v98
	v_add_f32_e32 v98, v112, v98
	v_add_f32_e32 v110, v113, v98
	v_cvt_pk_bf16_f32 v98, v102, v103
	v_cvt_pk_bf16_f32 v99, v104, v105
	v_cvt_pk_bf16_f32 v100, v106, v107
	v_cvt_pk_bf16_f32 v101, v108, v109
	global_store_dwordx4 v[114:115], v[98:101], off offset:256
	ds_bpermute_b32 v98, v154, v110
	s_waitcnt lgkmcnt(0)
	v_add_f32_e32 v98, v110, v98
	ds_bpermute_b32 v99, v153, v98
	s_and_saveexec_b64 s[20:21], s[40:41]
	s_cbranch_execz .LBB0_708
	s_waitcnt lgkmcnt(0)
	v_add_f32_e32 v98, v98, v99
	ds_write_b32 v150, v98 offset:256
; __device__ __forceinline__ unsigned cvtpk(float lo, float hi) { f32x2 v = {lo, hi}; bf16x2_t b = __builtin_convertvector(v, bf16x2_t); return __builtin_bit_cast(unsigned, b); }
;     __device__ __forceinline__ void operator()(AccRef acc, const Unit& u, int wr, int wc, int fr, int fq) const {
;     ...
;                 const int row = row0 + ai * 128 + m * 16; bf16_t* rowp = XB + (size_t)row * DM + col0; float s = 0.f;
; #pragma unroll
;                 for (int bj = 0; bj < 2; ++bj) {
;                     const u32x4 xo = *(const u32x4*)(rowp + bj * 128);
;                     float v[8];
; #pragma unroll
;                     for (int k = 0; k < 4; ++k) { v[2 * k] = __uint_as_float(xo[k] << 16) + acc[ai][bj][m][k >> 1][(2 * k) & 3]; v[2 * k + 1] = __uint_as_float(xo[k] & 0xffff0000u) + acc[ai][bj][m][k >> 1][(2 * k + 1) & 3]; }
; #pragma unroll
;                     for (int k = 0; k < 8; ++k) s += v[k] * v[k];
;                     u32x4 w; w.x = cvtpk(v[0], v[1]); w.y = cvtpk(v[2], v[3]); w.z = cvtpk(v[4], v[5]); w.w = cvtpk(v[6], v[7]);
;                     st16_wt(rowp + bj * 128, w);
;                 }
;                 s += __shfl_xor(s, 16); s += __shfl_xor(s, 32);
;                 if (fq == 0) red[(ai * 128 + wr * 64 + m * 16 + fr) * 4 + wc] = s;
;                 asm volatile("" ::: "memory");
.LBB0_708:
	s_or_b64 exec, exec, s[20:21]
	v_or_b32_e32 v98, 32, v142
	s_waitcnt lgkmcnt(0)
	v_ashrrev_i32_e32 v99, 31, v98
	v_lshlrev_b64 v[98:99], 11, v[98:99]
	v_lshl_add_u64 v[98:99], s[66:67], 0, v[98:99]
	v_lshl_add_u64 v[98:99], v[140:141], 1, v[98:99]
	global_load_dwordx4 v[100:103], v[98:99], off
	s_waitcnt vmcnt(0)
	v_lshlrev_b32_e32 v104, 16, v100
	v_and_b32_e32 v105, 0xffff0000, v100
	v_lshlrev_b32_e32 v100, 16, v101
	v_and_b32_e32 v101, 0xffff0000, v101
	v_pk_add_f32 v[96:97], v[96:97], v[100:101]
	v_lshlrev_b32_e32 v100, 16, v102
	v_and_b32_e32 v101, 0xffff0000, v102
	v_pk_add_f32 v[100:101], v[90:91], v[100:101]
	v_lshlrev_b32_e32 v90, 16, v103
	v_and_b32_e32 v91, 0xffff0000, v103
	v_pk_add_f32 v[94:95], v[94:95], v[104:105]
	v_pk_add_f32 v[102:103], v[92:93], v[90:91]
	v_cvt_pk_bf16_f32 v90, v94, v95
	v_cvt_pk_bf16_f32 v91, v96, v97
	v_cvt_pk_bf16_f32 v92, v100, v101
	v_cvt_pk_bf16_f32 v93, v102, v103
	global_store_dwordx4 v[98:99], v[90:93], off
	global_load_dwordx4 v[90:93], v[98:99], off offset:256
	v_pk_mul_f32 v[104:105], v[94:95], v[94:95]
	v_pk_mul_f32 v[106:107], v[96:97], v[96:97]
	v_pk_mul_f32 v[108:109], v[100:101], v[100:101]
	v_add_f32_e32 v100, v104, v105
	v_add_f32_e32 v100, v106, v100
	v_add_f32_e32 v100, v107, v100
	v_add_f32_e32 v100, v108, v100
	v_pk_mul_f32 v[110:111], v[102:103], v[102:103]
	v_add_f32_e32 v100, v109, v100
	v_add_f32_e32 v100, v110, v100
	v_add_f32_e32 v100, v111, v100
	s_waitcnt vmcnt(0)
	v_lshlrev_b32_e32 v94, 16, v90
	v_and_b32_e32 v95, 0xffff0000, v90
	v_lshlrev_b32_e32 v90, 16, v91
	v_and_b32_e32 v91, 0xffff0000, v91
	v_pk_add_f32 v[88:89], v[88:89], v[90:91]
	v_lshlrev_b32_e32 v90, 16, v92
	v_and_b32_e32 v91, 0xffff0000, v92
	v_pk_add_f32 v[86:87], v[86:87], v[94:95]
	v_pk_add_f32 v[90:91], v[82:83], v[90:91]
	v_lshlrev_b32_e32 v82, 16, v93
	v_and_b32_e32 v83, 0xffff0000, v93
	v_pk_add_f32 v[92:93], v[84:85], v[82:83]
	v_pk_mul_f32 v[82:83], v[86:87], v[86:87]
	v_pk_mul_f32 v[84:85], v[88:89], v[88:89]
	v_add_f32_e32 v82, v82, v100
	v_add_f32_e32 v82, v83, v82
	v_add_f32_e32 v82, v84, v82
	v_pk_mul_f32 v[94:95], v[90:91], v[90:91]
	v_add_f32_e32 v82, v85, v82
	v_add_f32_e32 v82, v94, v82
	v_pk_mul_f32 v[96:97], v[92:93], v[92:93]
	v_add_f32_e32 v82, v95, v82
	v_add_f32_e32 v82, v96, v82
	v_add_f32_e32 v94, v97, v82
	v_cvt_pk_bf16_f32 v82, v86, v87
	v_cvt_pk_bf16_f32 v83, v88, v89
	v_cvt_pk_bf16_f32 v84, v90, v91
	v_cvt_pk_bf16_f32 v85, v92, v93
	global_store_dwordx4 v[98:99], v[82:85], off offset:256
	ds_bpermute_b32 v82, v154, v94
	s_waitcnt lgkmcnt(0)
	v_add_f32_e32 v82, v94, v82
	ds_bpermute_b32 v83, v153, v82
	s_and_saveexec_b64 s[20:21], s[40:41]
	s_cbranch_execz .LBB0_710
	s_waitcnt lgkmcnt(0)
	v_add_f32_e32 v82, v82, v83
	ds_write_b32 v150, v82 offset:512
.LBB0_710:
	s_or_b64 exec, exec, s[20:21]
	v_or_b32_e32 v82, 48, v142
	s_waitcnt lgkmcnt(0)
	v_ashrrev_i32_e32 v83, 31, v82
	v_lshlrev_b64 v[82:83], 11, v[82:83]
	v_lshl_add_u64 v[82:83], s[66:67], 0, v[82:83]
	v_lshl_add_u64 v[82:83], v[140:141], 1, v[82:83]
	global_load_dwordx4 v[84:87], v[82:83], off
	s_waitcnt vmcnt(0)
	v_lshlrev_b32_e32 v88, 16, v84
	v_and_b32_e32 v89, 0xffff0000, v84
	v_lshlrev_b32_e32 v84, 16, v85
	v_and_b32_e32 v85, 0xffff0000, v85
	v_pk_add_f32 v[80:81], v[80:81], v[84:85]
	v_lshlrev_b32_e32 v84, 16, v86
	v_and_b32_e32 v85, 0xffff0000, v86
	v_pk_add_f32 v[84:85], v[74:75], v[84:85]
	v_lshlrev_b32_e32 v74, 16, v87
	v_and_b32_e32 v75, 0xffff0000, v87
	v_pk_add_f32 v[78:79], v[78:79], v[88:89]
	v_pk_add_f32 v[86:87], v[76:77], v[74:75]
	v_cvt_pk_bf16_f32 v74, v78, v79
	v_cvt_pk_bf16_f32 v75, v80, v81
	v_cvt_pk_bf16_f32 v76, v84, v85
	v_cvt_pk_bf16_f32 v77, v86, v87
	global_store_dwordx4 v[82:83], v[74:77], off
	global_load_dwordx4 v[74:77], v[82:83], off offset:256
	v_pk_mul_f32 v[88:89], v[78:79], v[78:79]
	v_pk_mul_f32 v[90:91], v[80:81], v[80:81]
	v_pk_mul_f32 v[92:93], v[84:85], v[84:85]
	v_add_f32_e32 v84, v88, v89
	v_add_f32_e32 v84, v90, v84
	v_add_f32_e32 v84, v91, v84
	v_add_f32_e32 v84, v92, v84
	v_pk_mul_f32 v[94:95], v[86:87], v[86:87]
	v_add_f32_e32 v84, v93, v84
	v_add_f32_e32 v84, v94, v84
	v_add_f32_e32 v84, v95, v84
	s_waitcnt vmcnt(0)
	v_lshlrev_b32_e32 v78, 16, v74
	v_and_b32_e32 v79, 0xffff0000, v74
	v_lshlrev_b32_e32 v74, 16, v75
	v_and_b32_e32 v75, 0xffff0000, v75
	v_pk_add_f32 v[72:73], v[72:73], v[74:75]
	v_lshlrev_b32_e32 v74, 16, v76
	v_and_b32_e32 v75, 0xffff0000, v76
	v_pk_add_f32 v[70:71], v[70:71], v[78:79]
	v_pk_add_f32 v[74:75], v[66:67], v[74:75]
	v_lshlrev_b32_e32 v66, 16, v77
	v_and_b32_e32 v67, 0xffff0000, v77
	v_pk_add_f32 v[76:77], v[68:69], v[66:67]
	v_pk_mul_f32 v[66:67], v[70:71], v[70:71]
	v_pk_mul_f32 v[68:69], v[72:73], v[72:73]
	v_add_f32_e32 v66, v66, v84
	v_add_f32_e32 v66, v67, v66
	v_add_f32_e32 v66, v68, v66
	v_pk_mul_f32 v[78:79], v[74:75], v[74:75]
	v_add_f32_e32 v66, v69, v66
	v_add_f32_e32 v66, v78, v66
	v_pk_mul_f32 v[80:81], v[76:77], v[76:77]
	v_add_f32_e32 v66, v79, v66
	v_add_f32_e32 v66, v80, v66
	v_add_f32_e32 v78, v81, v66
	v_cvt_pk_bf16_f32 v66, v70, v71
	v_cvt_pk_bf16_f32 v67, v72, v73
	v_cvt_pk_bf16_f32 v68, v74, v75
	v_cvt_pk_bf16_f32 v69, v76, v77
	global_store_dwordx4 v[82:83], v[66:69], off offset:256
	ds_bpermute_b32 v66, v154, v78
	s_waitcnt lgkmcnt(0)
	v_add_f32_e32 v66, v78, v66
	ds_bpermute_b32 v67, v153, v66
	s_and_saveexec_b64 s[20:21], s[40:41]
	s_cbranch_execz .LBB0_712
	s_waitcnt lgkmcnt(0)
	v_add_f32_e32 v66, v66, v67
	ds_write_b32 v150, v66 offset:768
; __device__ __forceinline__ unsigned cvtpk(float lo, float hi) { f32x2 v = {lo, hi}; bf16x2_t b = __builtin_convertvector(v, bf16x2_t); return __builtin_bit_cast(unsigned, b); }
;     __device__ __forceinline__ void operator()(AccRef acc, const Unit& u, int wr, int wc, int fr, int fq) const {
;     ...
;                 const int row = row0 + ai * 128 + m * 16; bf16_t* rowp = XB + (size_t)row * DM + col0; float s = 0.f;
; #pragma unroll
;                 for (int bj = 0; bj < 2; ++bj) {
;                     const u32x4 xo = *(const u32x4*)(rowp + bj * 128);
;                     float v[8];
; #pragma unroll
;                     for (int k = 0; k < 4; ++k) { v[2 * k] = __uint_as_float(xo[k] << 16) + acc[ai][bj][m][k >> 1][(2 * k) & 3]; v[2 * k + 1] = __uint_as_float(xo[k] & 0xffff0000u) + acc[ai][bj][m][k >> 1][(2 * k + 1) & 3]; }
; #pragma unroll
;                     for (int k = 0; k < 8; ++k) s += v[k] * v[k];
;                     u32x4 w; w.x = cvtpk(v[0], v[1]); w.y = cvtpk(v[2], v[3]); w.z = cvtpk(v[4], v[5]); w.w = cvtpk(v[6], v[7]);
;                     st16_wt(rowp + bj * 128, w);
;                 }
;                 s += __shfl_xor(s, 16); s += __shfl_xor(s, 32);
;                 if (fq == 0) red[(ai * 128 + wr * 64 + m * 16 + fr) * 4 + wc] = s;
;                 asm volatile("" ::: "memory");
.LBB0_712:
	s_or_b64 exec, exec, s[20:21]
	s_waitcnt lgkmcnt(0)
	v_lshlrev_b64 v[66:67], 11, v[142:143]
	v_lshl_add_u64 v[66:67], s[66:67], 0, v[66:67]
	v_lshl_add_u64 v[66:67], v[140:141], 1, v[66:67]
	v_add_co_u32_e32 v74, vcc, 0x40000, v66
	s_mov_b64 s[20:21], 0x40000
	s_nop 0
	v_addc_co_u32_e32 v75, vcc, 0, v67, vcc
	global_load_dwordx4 v[70:73], v[74:75], off
	v_lshl_add_u64 v[68:69], v[66:67], 0, s[20:21]
	s_waitcnt vmcnt(0)
	v_lshlrev_b32_e32 v76, 16, v70
	v_and_b32_e32 v77, 0xffff0000, v70
	v_pk_add_f32 v[76:77], v[62:63], v[76:77]
	v_lshlrev_b32_e32 v62, 16, v71
	v_and_b32_e32 v63, 0xffff0000, v71
	v_pk_add_f32 v[78:79], v[64:65], v[62:63]
	v_lshlrev_b32_e32 v62, 16, v72
	v_and_b32_e32 v63, 0xffff0000, v72
	v_pk_add_f32 v[80:81], v[58:59], v[62:63]
	v_lshlrev_b32_e32 v58, 16, v73
	v_and_b32_e32 v59, 0xffff0000, v73
	v_pk_add_f32 v[82:83], v[60:61], v[58:59]
	v_cvt_pk_bf16_f32 v70, v76, v77
	v_cvt_pk_bf16_f32 v71, v78, v79
	v_cvt_pk_bf16_f32 v72, v80, v81
	v_cvt_pk_bf16_f32 v73, v82, v83
	global_store_dwordx4 v[74:75], v[70:73], off
	global_load_dwordx4 v[70:73], v[68:69], off offset:256
	v_pk_mul_f32 v[64:65], v[76:77], v[76:77]
	v_pk_mul_f32 v[62:63], v[78:79], v[78:79]
	v_add_f32_e32 v64, v64, v65
	v_add_f32_e32 v62, v62, v64
	v_pk_mul_f32 v[60:61], v[80:81], v[80:81]
	v_add_f32_e32 v62, v63, v62
	v_add_f32_e32 v60, v60, v62
	v_pk_mul_f32 v[58:59], v[82:83], v[82:83]
	v_add_f32_e32 v60, v61, v60
	v_add_f32_e32 v58, v58, v60
	v_add_f32_e32 v58, v59, v58
	s_waitcnt vmcnt(0)
	v_lshlrev_b32_e32 v74, 16, v70
	v_and_b32_e32 v75, 0xffff0000, v70
	v_lshlrev_b32_e32 v70, 16, v71
	v_and_b32_e32 v71, 0xffff0000, v71
	v_pk_add_f32 v[56:57], v[56:57], v[70:71]
	v_lshlrev_b32_e32 v70, 16, v72
	v_and_b32_e32 v71, 0xffff0000, v72
	v_pk_add_f32 v[54:55], v[54:55], v[74:75]
	v_pk_add_f32 v[70:71], v[50:51], v[70:71]
	v_lshlrev_b32_e32 v50, 16, v73
	v_and_b32_e32 v51, 0xffff0000, v73
	v_pk_add_f32 v[72:73], v[52:53], v[50:51]
	v_pk_mul_f32 v[50:51], v[54:55], v[54:55]
	v_pk_mul_f32 v[52:53], v[56:57], v[56:57]
	v_add_f32_e32 v50, v50, v58
	v_add_f32_e32 v50, v51, v50
	v_add_f32_e32 v50, v52, v50
	v_pk_mul_f32 v[74:75], v[70:71], v[70:71]
	v_add_f32_e32 v50, v53, v50
	v_add_f32_e32 v50, v74, v50
	v_pk_mul_f32 v[76:77], v[72:73], v[72:73]
	v_add_f32_e32 v50, v75, v50
	v_add_f32_e32 v50, v76, v50
	v_add_f32_e32 v58, v77, v50
	v_cvt_pk_bf16_f32 v50, v54, v55
	v_cvt_pk_bf16_f32 v51, v56, v57
	v_cvt_pk_bf16_f32 v52, v70, v71
	v_cvt_pk_bf16_f32 v53, v72, v73
	global_store_dwordx4 v[68:69], v[50:53], off offset:256
	ds_bpermute_b32 v50, v154, v58
	s_waitcnt lgkmcnt(0)
	v_add_f32_e32 v50, v58, v50
	ds_bpermute_b32 v51, v153, v50
	s_and_saveexec_b64 s[20:21], s[40:41]
	s_cbranch_execz .LBB0_714
	s_waitcnt lgkmcnt(0)
	v_add_f32_e32 v50, v50, v51
	ds_write_b32 v150, v50 offset:2048
.LBB0_714:
	s_or_b64 exec, exec, s[20:21]
	v_add_co_u32_e32 v56, vcc, 0x48000, v66
	s_mov_b64 s[20:21], 0x48000
	s_nop 0
	v_addc_co_u32_e32 v57, vcc, 0, v67, vcc
	global_load_dwordx4 v[52:55], v[56:57], off
	s_waitcnt lgkmcnt(0)
	v_lshl_add_u64 v[50:51], v[66:67], 0, s[20:21]
	s_waitcnt vmcnt(0)
	v_lshlrev_b32_e32 v58, 16, v52
	v_and_b32_e32 v59, 0xffff0000, v52
	v_pk_add_f32 v[58:59], v[46:47], v[58:59]
	v_lshlrev_b32_e32 v46, 16, v53
	v_and_b32_e32 v47, 0xffff0000, v53
	v_pk_add_f32 v[60:61], v[48:49], v[46:47]
	v_lshlrev_b32_e32 v46, 16, v54
	v_and_b32_e32 v47, 0xffff0000, v54
	v_pk_add_f32 v[62:63], v[42:43], v[46:47]
	v_lshlrev_b32_e32 v42, 16, v55
	v_and_b32_e32 v43, 0xffff0000, v55
	v_pk_add_f32 v[64:65], v[44:45], v[42:43]
	v_cvt_pk_bf16_f32 v52, v58, v59
	v_cvt_pk_bf16_f32 v53, v60, v61
	v_cvt_pk_bf16_f32 v54, v62, v63
	v_cvt_pk_bf16_f32 v55, v64, v65
	global_store_dwordx4 v[56:57], v[52:55], off
	global_load_dwordx4 v[52:55], v[50:51], off offset:256
	v_pk_mul_f32 v[48:49], v[58:59], v[58:59]
	v_pk_mul_f32 v[46:47], v[60:61], v[60:61]
	v_add_f32_e32 v48, v48, v49
	v_add_f32_e32 v46, v46, v48
	v_pk_mul_f32 v[44:45], v[62:63], v[62:63]
	v_add_f32_e32 v46, v47, v46
	v_add_f32_e32 v44, v44, v46
	v_pk_mul_f32 v[42:43], v[64:65], v[64:65]
	v_add_f32_e32 v44, v45, v44
	v_add_f32_e32 v42, v42, v44
	v_add_f32_e32 v42, v43, v42
	s_waitcnt vmcnt(0)
	v_lshlrev_b32_e32 v56, 16, v52
	v_and_b32_e32 v57, 0xffff0000, v52
	v_lshlrev_b32_e32 v52, 16, v53
	v_and_b32_e32 v53, 0xffff0000, v53
	v_pk_add_f32 v[40:41], v[40:41], v[52:53]
	v_lshlrev_b32_e32 v52, 16, v54
	v_and_b32_e32 v53, 0xffff0000, v54
	v_pk_add_f32 v[38:39], v[38:39], v[56:57]
	v_pk_add_f32 v[52:53], v[34:35], v[52:53]
	v_lshlrev_b32_e32 v34, 16, v55
	v_and_b32_e32 v35, 0xffff0000, v55
	v_pk_add_f32 v[54:55], v[36:37], v[34:35]
	v_pk_mul_f32 v[34:35], v[38:39], v[38:39]
	v_pk_mul_f32 v[36:37], v[40:41], v[40:41]
	v_add_f32_e32 v34, v34, v42
	v_add_f32_e32 v34, v35, v34
	v_add_f32_e32 v34, v36, v34
	v_pk_mul_f32 v[56:57], v[52:53], v[52:53]
	v_add_f32_e32 v34, v37, v34
	v_add_f32_e32 v34, v56, v34
	v_pk_mul_f32 v[58:59], v[54:55], v[54:55]
	v_add_f32_e32 v34, v57, v34
	v_add_f32_e32 v34, v58, v34
	v_add_f32_e32 v42, v59, v34
	v_cvt_pk_bf16_f32 v34, v38, v39
	v_cvt_pk_bf16_f32 v35, v40, v41
	v_cvt_pk_bf16_f32 v36, v52, v53
	v_cvt_pk_bf16_f32 v37, v54, v55
	global_store_dwordx4 v[50:51], v[34:37], off offset:256
	ds_bpermute_b32 v34, v154, v42
	s_waitcnt lgkmcnt(0)
	v_add_f32_e32 v34, v42, v34
	ds_bpermute_b32 v35, v153, v34
	s_and_saveexec_b64 s[20:21], s[40:41]
	s_cbranch_execz .LBB0_716
	s_waitcnt lgkmcnt(0)
	v_add_f32_e32 v34, v34, v35
	ds_write_b32 v150, v34 offset:2304
; __device__ __forceinline__ unsigned cvtpk(float lo, float hi) { f32x2 v = {lo, hi}; bf16x2_t b = __builtin_convertvector(v, bf16x2_t); return __builtin_bit_cast(unsigned, b); }
;     __device__ __forceinline__ void operator()(AccRef acc, const Unit& u, int wr, int wc, int fr, int fq) const {
;     ...
;                 const int row = row0 + ai * 128 + m * 16; bf16_t* rowp = XB + (size_t)row * DM + col0; float s = 0.f;
; #pragma unroll
;                 for (int bj = 0; bj < 2; ++bj) {
;                     const u32x4 xo = *(const u32x4*)(rowp + bj * 128);
;                     float v[8];
; #pragma unroll
;                     for (int k = 0; k < 4; ++k) { v[2 * k] = __uint_as_float(xo[k] << 16) + acc[ai][bj][m][k >> 1][(2 * k) & 3]; v[2 * k + 1] = __uint_as_float(xo[k] & 0xffff0000u) + acc[ai][bj][m][k >> 1][(2 * k + 1) & 3]; }
; #pragma unroll
;                     for (int k = 0; k < 8; ++k) s += v[k] * v[k];
;                     u32x4 w; w.x = cvtpk(v[0], v[1]); w.y = cvtpk(v[2], v[3]); w.z = cvtpk(v[4], v[5]); w.w = cvtpk(v[6], v[7]);
;                     st16_wt(rowp + bj * 128, w);
;                 }
;                 s += __shfl_xor(s, 16); s += __shfl_xor(s, 32);
;                 if (fq == 0) red[(ai * 128 + wr * 64 + m * 16 + fr) * 4 + wc] = s;
;                 asm volatile("" ::: "memory");
.LBB0_716:
	s_or_b64 exec, exec, s[20:21]
	s_waitcnt lgkmcnt(0)
	v_lshlrev_b64 v[34:35], 11, v[142:143]
	v_lshl_add_u64 v[34:35], s[66:67], 0, v[34:35]
	v_lshl_add_u64 v[34:35], v[140:141], 1, v[34:35]
	v_add_co_u32_e32 v42, vcc, 0x50000, v34
	s_mov_b64 s[20:21], 0x50000
	s_nop 0
	v_addc_co_u32_e32 v43, vcc, 0, v35, vcc
	global_load_dwordx4 v[38:41], v[42:43], off
	v_lshl_add_u64 v[36:37], v[34:35], 0, s[20:21]
	s_waitcnt vmcnt(0)
	v_lshlrev_b32_e32 v44, 16, v38
	v_and_b32_e32 v45, 0xffff0000, v38
	v_pk_add_f32 v[44:45], v[30:31], v[44:45]
	v_lshlrev_b32_e32 v30, 16, v39
	v_and_b32_e32 v31, 0xffff0000, v39
	v_pk_add_f32 v[46:47], v[32:33], v[30:31]
	v_lshlrev_b32_e32 v30, 16, v40
	v_and_b32_e32 v31, 0xffff0000, v40
	v_pk_add_f32 v[48:49], v[26:27], v[30:31]
	v_lshlrev_b32_e32 v26, 16, v41
	v_and_b32_e32 v27, 0xffff0000, v41
	v_pk_add_f32 v[50:51], v[28:29], v[26:27]
	v_cvt_pk_bf16_f32 v38, v44, v45
	v_cvt_pk_bf16_f32 v39, v46, v47
	v_cvt_pk_bf16_f32 v40, v48, v49
	v_cvt_pk_bf16_f32 v41, v50, v51
	global_store_dwordx4 v[42:43], v[38:41], off
	global_load_dwordx4 v[38:41], v[36:37], off offset:256
	v_pk_mul_f32 v[32:33], v[44:45], v[44:45]
	v_pk_mul_f32 v[30:31], v[46:47], v[46:47]
	v_add_f32_e32 v32, v32, v33
	v_add_f32_e32 v30, v30, v32
	v_pk_mul_f32 v[28:29], v[48:49], v[48:49]
	v_add_f32_e32 v30, v31, v30
	v_add_f32_e32 v28, v28, v30
	v_pk_mul_f32 v[26:27], v[50:51], v[50:51]
	v_add_f32_e32 v28, v29, v28
	v_add_f32_e32 v26, v26, v28
	v_add_f32_e32 v26, v27, v26
	s_waitcnt vmcnt(0)
	v_lshlrev_b32_e32 v42, 16, v38
	v_and_b32_e32 v43, 0xffff0000, v38
	v_lshlrev_b32_e32 v38, 16, v39
	v_and_b32_e32 v39, 0xffff0000, v39
	v_pk_add_f32 v[24:25], v[24:25], v[38:39]
	v_lshlrev_b32_e32 v38, 16, v40
	v_and_b32_e32 v39, 0xffff0000, v40
	v_pk_add_f32 v[22:23], v[22:23], v[42:43]
	v_pk_add_f32 v[38:39], v[18:19], v[38:39]
	v_lshlrev_b32_e32 v18, 16, v41
	v_and_b32_e32 v19, 0xffff0000, v41
	v_pk_add_f32 v[40:41], v[20:21], v[18:19]
	v_pk_mul_f32 v[18:19], v[22:23], v[22:23]
	v_pk_mul_f32 v[20:21], v[24:25], v[24:25]
	v_add_f32_e32 v18, v18, v26
	v_add_f32_e32 v18, v19, v18
	v_add_f32_e32 v18, v20, v18
	v_pk_mul_f32 v[42:43], v[38:39], v[38:39]
	v_add_f32_e32 v18, v21, v18
	v_add_f32_e32 v18, v42, v18
	v_pk_mul_f32 v[44:45], v[40:41], v[40:41]
	v_add_f32_e32 v18, v43, v18
	v_add_f32_e32 v18, v44, v18
	v_add_f32_e32 v26, v45, v18
	v_cvt_pk_bf16_f32 v18, v22, v23
	v_cvt_pk_bf16_f32 v19, v24, v25
	v_cvt_pk_bf16_f32 v20, v38, v39
	v_cvt_pk_bf16_f32 v21, v40, v41
	global_store_dwordx4 v[36:37], v[18:21], off offset:256
	ds_bpermute_b32 v18, v154, v26
	s_waitcnt lgkmcnt(0)
	v_add_f32_e32 v18, v26, v18
	ds_bpermute_b32 v19, v153, v18
	s_and_saveexec_b64 s[20:21], s[40:41]
	s_cbranch_execz .LBB0_718
	s_waitcnt lgkmcnt(0)
	v_add_f32_e32 v18, v18, v19
	ds_write_b32 v150, v18 offset:2560
.LBB0_718:
	s_or_b64 exec, exec, s[20:21]
	v_add_co_u32_e32 v24, vcc, 0x58000, v34
	s_mov_b64 s[20:21], 0x58000
	s_nop 0
	v_addc_co_u32_e32 v25, vcc, 0, v35, vcc
	global_load_dwordx4 v[20:23], v[24:25], off
	s_waitcnt lgkmcnt(0)
	v_lshl_add_u64 v[18:19], v[34:35], 0, s[20:21]
	s_waitcnt vmcnt(0)
	v_lshlrev_b32_e32 v26, 16, v20
	v_and_b32_e32 v27, 0xffff0000, v20
	v_pk_add_f32 v[26:27], v[14:15], v[26:27]
	v_lshlrev_b32_e32 v14, 16, v21
	v_and_b32_e32 v15, 0xffff0000, v21
	v_pk_add_f32 v[28:29], v[16:17], v[14:15]
	v_lshlrev_b32_e32 v14, 16, v22
	v_and_b32_e32 v15, 0xffff0000, v22
	v_pk_add_f32 v[30:31], v[10:11], v[14:15]
	v_lshlrev_b32_e32 v10, 16, v23
	v_and_b32_e32 v11, 0xffff0000, v23
	v_pk_add_f32 v[32:33], v[12:13], v[10:11]
	v_cvt_pk_bf16_f32 v20, v26, v27
	v_cvt_pk_bf16_f32 v21, v28, v29
	v_cvt_pk_bf16_f32 v22, v30, v31
	v_cvt_pk_bf16_f32 v23, v32, v33
	global_store_dwordx4 v[24:25], v[20:23], off
	global_load_dwordx4 v[20:23], v[18:19], off offset:256
	v_pk_mul_f32 v[16:17], v[26:27], v[26:27]
	v_pk_mul_f32 v[14:15], v[28:29], v[28:29]
	v_add_f32_e32 v16, v16, v17
	v_add_f32_e32 v14, v14, v16
	v_pk_mul_f32 v[12:13], v[30:31], v[30:31]
	v_add_f32_e32 v14, v15, v14
	v_add_f32_e32 v12, v12, v14
	v_pk_mul_f32 v[10:11], v[32:33], v[32:33]
	v_add_f32_e32 v12, v13, v12
	v_add_f32_e32 v10, v10, v12
	v_add_f32_e32 v10, v11, v10
	s_waitcnt vmcnt(0)
	v_lshlrev_b32_e32 v24, 16, v20
	v_and_b32_e32 v25, 0xffff0000, v20
	v_lshlrev_b32_e32 v20, 16, v21
	v_and_b32_e32 v21, 0xffff0000, v21
	v_pk_add_f32 v[8:9], v[8:9], v[20:21]
	v_lshlrev_b32_e32 v20, 16, v22
	v_and_b32_e32 v21, 0xffff0000, v22
	v_pk_add_f32 v[6:7], v[6:7], v[24:25]
	v_pk_add_f32 v[20:21], v[2:3], v[20:21]
	v_lshlrev_b32_e32 v2, 16, v23
	v_and_b32_e32 v3, 0xffff0000, v23
	v_pk_add_f32 v[22:23], v[4:5], v[2:3]
	v_pk_mul_f32 v[2:3], v[6:7], v[6:7]
	v_pk_mul_f32 v[4:5], v[8:9], v[8:9]
	v_add_f32_e32 v2, v2, v10
	v_add_f32_e32 v2, v3, v2
	v_add_f32_e32 v2, v4, v2
	v_pk_mul_f32 v[24:25], v[20:21], v[20:21]
	v_add_f32_e32 v2, v5, v2
	v_add_f32_e32 v2, v24, v2
	v_pk_mul_f32 v[26:27], v[22:23], v[22:23]
	v_add_f32_e32 v2, v25, v2
	v_add_f32_e32 v2, v26, v2
	v_add_f32_e32 v10, v27, v2
	v_cvt_pk_bf16_f32 v2, v6, v7
	v_cvt_pk_bf16_f32 v3, v8, v9
	v_cvt_pk_bf16_f32 v4, v20, v21
	v_cvt_pk_bf16_f32 v5, v22, v23
	global_store_dwordx4 v[18:19], v[2:5], off offset:256
	ds_bpermute_b32 v2, v154, v10
	s_waitcnt lgkmcnt(0)
	v_add_f32_e32 v2, v10, v2
	ds_bpermute_b32 v3, v153, v2
	s_and_saveexec_b64 s[20:21], s[40:41]
	s_cbranch_execz .LBB0_720
	s_waitcnt lgkmcnt(0)
	v_add_f32_e32 v2, v2, v3
	ds_write_b32 v150, v2 offset:2816

; #define PG8_BAR __builtin_amdgcn_s_barrier()
; template <class Epi>
; __device__ __forceinline__ void gemm_phase(LAS unsigned char* lds, const Gemm g, const Epi& E) {
;     ...
; #pragma unroll
;         for (int a = 0; a < 2; ++a)
; #pragma unroll
;             for (int b = 0; b < 2; ++b)
; #pragma unroll
;                 for (int m = 0; m < 4; ++m)
; #pragma unroll
;                     for (int n = 0; n < 2; ++n) acc[a][b][m][n] = (f32x4){0.f, 0.f, 0.f, 0.f};
;         cur = nxt; cA = nA; cB = nB; ++ui;
;         if (wr == 1) PG8_BAR;
.LBB0_790:
	s_andn2_b64 vcc, exec, s[10:11]
	s_cbranch_vccnz .LBB0_793
	s_add_u32 s46, s50, 0x80
	s_addc_u32 s47, s51, 0
	s_add_u32 s24, s48, 0x100
	s_addc_u32 s25, s49, 0
	s_mov_b32 s48, 0
	v_mov_b64_e32 v[2:3], 0
	v_mov_b64_e32 v[4:5], 0
	v_mov_b64_e32 v[6:7], 0
	v_mov_b64_e32 v[8:9], 0
	v_mov_b64_e32 v[10:11], 0
	v_mov_b64_e32 v[12:13], 0
	v_mov_b64_e32 v[14:15], 0
	v_mov_b64_e32 v[16:17], 0
	v_mov_b64_e32 v[18:19], 0
	v_mov_b64_e32 v[20:21], 0
	v_mov_b64_e32 v[22:23], 0
	v_mov_b64_e32 v[24:25], 0
	v_mov_b64_e32 v[26:27], 0
	v_mov_b64_e32 v[28:29], 0
	v_mov_b64_e32 v[30:31], 0
	v_mov_b64_e32 v[32:33], 0
	v_mov_b64_e32 v[34:35], 0
	v_mov_b64_e32 v[36:37], 0
	v_mov_b64_e32 v[38:39], 0
	v_mov_b64_e32 v[40:41], 0
	v_mov_b64_e32 v[42:43], 0
	v_mov_b64_e32 v[44:45], 0
	v_mov_b64_e32 v[46:47], 0
	v_mov_b64_e32 v[48:49], 0
	v_mov_b64_e32 v[50:51], 0
	v_mov_b64_e32 v[52:53], 0
	v_mov_b64_e32 v[54:55], 0
	v_mov_b64_e32 v[56:57], 0
	v_mov_b64_e32 v[58:59], 0
	v_mov_b64_e32 v[60:61], 0
	v_mov_b64_e32 v[62:63], 0
	v_mov_b64_e32 v[64:65], 0
	v_mov_b64_e32 v[66:67], 0
	v_mov_b64_e32 v[68:69], 0
	v_mov_b64_e32 v[70:71], 0
	v_mov_b64_e32 v[72:73], 0
	v_mov_b64_e32 v[74:75], 0
	v_mov_b64_e32 v[76:77], 0
	v_mov_b64_e32 v[78:79], 0
	v_mov_b64_e32 v[80:81], 0
	v_mov_b64_e32 v[82:83], 0
	v_mov_b64_e32 v[84:85], 0
	v_mov_b64_e32 v[86:87], 0
	v_mov_b64_e32 v[88:89], 0
	v_mov_b64_e32 v[90:91], 0
	v_mov_b64_e32 v[92:93], 0
	v_mov_b64_e32 v[94:95], 0
	v_mov_b64_e32 v[96:97], 0
	v_mov_b64_e32 v[98:99], 0
	v_mov_b64_e32 v[100:101], 0
	v_mov_b64_e32 v[102:103], 0
	v_mov_b64_e32 v[104:105], 0
	v_mov_b64_e32 v[106:107], 0
	v_mov_b64_e32 v[108:109], 0
	v_mov_b64_e32 v[110:111], 0
	v_mov_b64_e32 v[112:113], 0
	v_mov_b64_e32 v[114:115], 0
	v_mov_b64_e32 v[116:117], 0
	v_mov_b64_e32 v[118:119], 0
	v_mov_b64_e32 v[120:121], 0
	v_mov_b64_e32 v[122:123], 0
	v_mov_b64_e32 v[124:125], 0
	v_mov_b64_e32 v[126:127], 0
	v_mov_b64_e32 v[128:129], 0

; #define PG8_BAR __builtin_amdgcn_s_barrier()
; template <class Epi>
; __device__ __forceinline__ void gemm_phase(LAS unsigned char* lds, const Gemm g, const Epi& E) {
;     ...
; #pragma unroll
;         for (int a = 0; a < 2; ++a)
; #pragma unroll
;             for (int b = 0; b < 2; ++b)
; #pragma unroll
;                 for (int m = 0; m < 4; ++m)
; #pragma unroll
;                     for (int n = 0; n < 2; ++n) acc[a][b][m][n] = (f32x4){0.f, 0.f, 0.f, 0.f};
;         cur = nxt; cA = nA; cB = nB; ++ui;
;         if (wr == 1) PG8_BAR;
.LBB0_934:
	s_andn2_b64 vcc, exec, s[46:47]
	s_waitcnt lgkmcnt(0)
	s_cbranch_vccnz .LBB0_937
	s_add_u32 s58, s58, 0x80
	s_addc_u32 s59, s59, 0
	s_add_u32 s20, s62, 0x100
	s_addc_u32 s21, s63, 0
	s_mov_b32 s62, 0
	v_mov_b64_e32 v[2:3], 0
	v_mov_b64_e32 v[4:5], 0
	v_mov_b64_e32 v[6:7], 0
	v_mov_b64_e32 v[8:9], 0
	v_mov_b64_e32 v[10:11], 0
	v_mov_b64_e32 v[12:13], 0
	v_mov_b64_e32 v[14:15], 0
	v_mov_b64_e32 v[16:17], 0
	v_mov_b64_e32 v[18:19], 0
	v_mov_b64_e32 v[20:21], 0
	v_mov_b64_e32 v[22:23], 0
	v_mov_b64_e32 v[24:25], 0
	v_mov_b64_e32 v[26:27], 0
	v_mov_b64_e32 v[28:29], 0
	v_mov_b64_e32 v[30:31], 0
	v_mov_b64_e32 v[32:33], 0
	v_mov_b64_e32 v[34:35], 0
	v_mov_b64_e32 v[36:37], 0
	v_mov_b64_e32 v[38:39], 0
	v_mov_b64_e32 v[40:41], 0
	v_mov_b64_e32 v[42:43], 0
	v_mov_b64_e32 v[44:45], 0
	v_mov_b64_e32 v[46:47], 0
	v_mov_b64_e32 v[48:49], 0
	v_mov_b64_e32 v[50:51], 0
	v_mov_b64_e32 v[52:53], 0
	v_mov_b64_e32 v[54:55], 0
	v_mov_b64_e32 v[56:57], 0
	v_mov_b64_e32 v[58:59], 0
	v_mov_b64_e32 v[60:61], 0
	v_mov_b64_e32 v[62:63], 0
	v_mov_b64_e32 v[64:65], 0
	v_mov_b64_e32 v[66:67], 0
	v_mov_b64_e32 v[68:69], 0
	v_mov_b64_e32 v[70:71], 0
	v_mov_b64_e32 v[72:73], 0
	v_mov_b64_e32 v[74:75], 0
	v_mov_b64_e32 v[76:77], 0
	v_mov_b64_e32 v[78:79], 0
	v_mov_b64_e32 v[80:81], 0
	v_mov_b64_e32 v[82:83], 0
	v_mov_b64_e32 v[84:85], 0
	v_mov_b64_e32 v[86:87], 0
	v_mov_b64_e32 v[88:89], 0
	v_mov_b64_e32 v[90:91], 0
	v_mov_b64_e32 v[92:93], 0
	v_mov_b64_e32 v[94:95], 0
	v_mov_b64_e32 v[96:97], 0
	v_mov_b64_e32 v[98:99], 0
	v_mov_b64_e32 v[100:101], 0
	v_mov_b64_e32 v[102:103], 0
	v_mov_b64_e32 v[104:105], 0
	v_mov_b64_e32 v[106:107], 0
	v_mov_b64_e32 v[108:109], 0
	v_mov_b64_e32 v[110:111], 0
	v_mov_b64_e32 v[112:113], 0
	v_mov_b64_e32 v[114:115], 0
	v_mov_b64_e32 v[116:117], 0
	v_mov_b64_e32 v[118:119], 0
	v_mov_b64_e32 v[120:121], 0
	v_mov_b64_e32 v[122:123], 0
	v_mov_b64_e32 v[124:125], 0
	v_mov_b64_e32 v[126:127], 0
	v_mov_b64_e32 v[128:129], 0

; __device__ __forceinline__ unsigned cvtpk(float lo, float hi) { f32x2 v = {lo, hi}; bf16x2_t b = __builtin_convertvector(v, bf16x2_t); return __builtin_bit_cast(unsigned, b); }
;     __device__ __forceinline__ void operator()(AccRef acc, const Unit& u, int wr, int wc, int fr, int fq) const {
;         const int row0 = u.pm * 256 + wr * 64 + fr, col0 = u.pn * 256 + wc * 32 + 8 * fq;
; #pragma unroll
;         for (int ai = 0; ai < 2; ++ai)
; #pragma unroll
;             for (int m = 0; m < 4; ++m) {
;                 const int row = row0 + ai * 128 + m * 16; bf16_t* rowp = XB + (size_t)row * DM + col0; float s = 0.f;
; #pragma unroll
;                 for (int bj = 0; bj < 2; ++bj) {
;                     const u32x4 xo = *(const u32x4*)(rowp + bj * 128);
;                     float v[8];
; #pragma unroll
;                     for (int k = 0; k < 4; ++k) { v[2 * k] = __uint_as_float(xo[k] << 16) + acc[ai][bj][m][k >> 1][(2 * k) & 3]; v[2 * k + 1] = __uint_as_float(xo[k] & 0xffff0000u) + acc[ai][bj][m][k >> 1][(2 * k + 1) & 3]; }
; #pragma unroll
;                     for (int k = 0; k < 8; ++k) s += v[k] * v[k];
;                     u32x4 w; w.x = cvtpk(v[0], v[1]); w.y = cvtpk(v[2], v[3]); w.z = cvtpk(v[4], v[5]); w.w = cvtpk(v[6], v[7]);
;                     st16_wt(rowp + bj * 128, w);
;                 }
;                 s += __shfl_xor(s, 16); s += __shfl_xor(s, 32);
;                 if (fq == 0) red[(ai * 128 + wr * 64 + m * 16 + fr) * 4 + wc] = s;
;                 asm volatile("" ::: "memory");
.LBB0_939:
	v_and_b32_e32 v144, 64, v213
	v_xor_b32_e32 v143, 16, v213
	v_add_u32_e32 v144, 64, v144
	v_cmp_lt_i32_e32 vcc, v143, v144
	s_lshl_b32 s51, s51, 8
	v_add_u32_e32 v142, s51, v146
	v_cndmask_b32_e32 v143, v213, v143, vcc
	v_lshlrev_b32_e32 v154, 2, v143
	v_xor_b32_e32 v143, 32, v213
	v_cmp_lt_i32_e32 vcc, v143, v144
	v_lshl_or_b32 v140, s50, 8, v148
	v_ashrrev_i32_e32 v141, 31, v140
	v_cndmask_b32_e32 v143, v213, v143, vcc
	v_lshlrev_b32_e32 v153, 2, v143
	v_ashrrev_i32_e32 v143, 31, v142
	v_lshlrev_b64 v[144:145], 11, v[142:143]
	v_lshl_add_u64 v[144:145], s[66:67], 0, v[144:145]
	v_lshl_add_u64 v[144:145], v[140:141], 1, v[144:145]
	global_load_dwordx4 v[156:159], v[144:145], off
	s_waitcnt vmcnt(0)
	v_lshlrev_b32_e32 v160, 16, v156
	v_and_b32_e32 v161, 0xffff0000, v156
	v_pk_add_f32 v[160:161], v[126:127], v[160:161]
	v_lshlrev_b32_e32 v126, 16, v157
	v_and_b32_e32 v127, 0xffff0000, v157
	v_pk_add_f32 v[162:163], v[128:129], v[126:127]
	v_lshlrev_b32_e32 v126, 16, v158
	v_and_b32_e32 v127, 0xffff0000, v158
	v_pk_add_f32 v[164:165], v[122:123], v[126:127]
	v_lshlrev_b32_e32 v122, 16, v159
	v_and_b32_e32 v123, 0xffff0000, v159
	v_pk_add_f32 v[166:167], v[124:125], v[122:123]
	v_cvt_pk_bf16_f32 v156, v160, v161
	v_cvt_pk_bf16_f32 v157, v162, v163
	v_cvt_pk_bf16_f32 v158, v164, v165
	v_cvt_pk_bf16_f32 v159, v166, v167
	global_store_dwordx4 v[144:145], v[156:159], off
	global_load_dwordx4 v[156:159], v[144:145], off offset:256
	v_pk_mul_f32 v[128:129], v[160:161], v[160:161]
	v_pk_mul_f32 v[126:127], v[162:163], v[162:163]
	v_add_f32_e32 v128, v128, v129
	v_add_f32_e32 v126, v126, v128
	v_pk_mul_f32 v[124:125], v[164:165], v[164:165]
	v_add_f32_e32 v126, v127, v126
	v_add_f32_e32 v124, v124, v126
	v_pk_mul_f32 v[122:123], v[166:167], v[166:167]
	v_add_f32_e32 v124, v125, v124
	v_add_f32_e32 v122, v122, v124
	v_add_f32_e32 v122, v123, v122
	s_waitcnt vmcnt(0)
	v_lshlrev_b32_e32 v160, 16, v156
	v_and_b32_e32 v161, 0xffff0000, v156
	v_lshlrev_b32_e32 v156, 16, v157
	v_and_b32_e32 v157, 0xffff0000, v157
	v_pk_add_f32 v[120:121], v[120:121], v[156:157]
	v_lshlrev_b32_e32 v156, 16, v158
	v_and_b32_e32 v157, 0xffff0000, v158
	v_pk_add_f32 v[118:119], v[118:119], v[160:161]
	v_pk_add_f32 v[156:157], v[114:115], v[156:157]
	v_lshlrev_b32_e32 v114, 16, v159
	v_and_b32_e32 v115, 0xffff0000, v159
	v_pk_add_f32 v[158:159], v[116:117], v[114:115]
	v_pk_mul_f32 v[114:115], v[118:119], v[118:119]
	v_pk_mul_f32 v[116:117], v[120:121], v[120:121]
	v_add_f32_e32 v114, v114, v122
	v_add_f32_e32 v114, v115, v114
	v_add_f32_e32 v114, v116, v114
	v_pk_mul_f32 v[160:161], v[156:157], v[156:157]
	v_add_f32_e32 v114, v117, v114
	v_add_f32_e32 v114, v160, v114
	v_pk_mul_f32 v[162:163], v[158:159], v[158:159]
	v_add_f32_e32 v114, v161, v114
	v_add_f32_e32 v114, v162, v114
	v_add_f32_e32 v122, v163, v114
	v_cvt_pk_bf16_f32 v114, v118, v119
	v_cvt_pk_bf16_f32 v115, v120, v121
	v_cvt_pk_bf16_f32 v116, v156, v157
	v_cvt_pk_bf16_f32 v117, v158, v159
	global_store_dwordx4 v[144:145], v[114:117], off offset:256
	ds_bpermute_b32 v114, v154, v122
	s_waitcnt lgkmcnt(0)
	v_add_f32_e32 v114, v122, v114
	ds_bpermute_b32 v115, v153, v114
	s_and_saveexec_b64 s[20:21], s[38:39]
	s_cbranch_execz .LBB0_941
	s_waitcnt lgkmcnt(0)
	v_add_f32_e32 v114, v114, v115
	ds_write_b32 v150, v114
.LBB0_941:
	s_or_b64 exec, exec, s[20:21]
	v_or_b32_e32 v114, 16, v142
	s_waitcnt lgkmcnt(0)
	v_ashrrev_i32_e32 v115, 31, v114
	v_lshlrev_b64 v[114:115], 11, v[114:115]
	v_lshl_add_u64 v[114:115], s[66:67], 0, v[114:115]
	v_lshl_add_u64 v[114:115], v[140:141], 1, v[114:115]
	global_load_dwordx4 v[116:119], v[114:115], off
	s_waitcnt vmcnt(0)
	v_lshlrev_b32_e32 v120, 16, v116
	v_and_b32_e32 v121, 0xffff0000, v116
	v_lshlrev_b32_e32 v116, 16, v117
	v_and_b32_e32 v117, 0xffff0000, v117
	v_pk_add_f32 v[112:113], v[112:113], v[116:117]
	v_lshlrev_b32_e32 v116, 16, v118
	v_and_b32_e32 v117, 0xffff0000, v118
	v_pk_add_f32 v[116:117], v[106:107], v[116:117]
	v_lshlrev_b32_e32 v106, 16, v119
	v_and_b32_e32 v107, 0xffff0000, v119
	v_pk_add_f32 v[110:111], v[110:111], v[120:121]
	v_pk_add_f32 v[118:119], v[108:109], v[106:107]
	v_cvt_pk_bf16_f32 v106, v110, v111
	v_cvt_pk_bf16_f32 v107, v112, v113
	v_cvt_pk_bf16_f32 v108, v116, v117
	v_cvt_pk_bf16_f32 v109, v118, v119
	global_store_dwordx4 v[114:115], v[106:109], off
	global_load_dwordx4 v[106:109], v[114:115], off offset:256
	v_pk_mul_f32 v[120:121], v[110:111], v[110:111]
	v_pk_mul_f32 v[122:123], v[112:113], v[112:113]
	v_pk_mul_f32 v[124:125], v[116:117], v[116:117]
	v_add_f32_e32 v116, v120, v121
	v_add_f32_e32 v116, v122, v116
	v_add_f32_e32 v116, v123, v116
	v_add_f32_e32 v116, v124, v116
	v_pk_mul_f32 v[126:127], v[118:119], v[118:119]
	v_add_f32_e32 v116, v125, v116
	v_add_f32_e32 v116, v126, v116
	v_add_f32_e32 v116, v127, v116
	s_waitcnt vmcnt(0)
	v_lshlrev_b32_e32 v110, 16, v106
	v_and_b32_e32 v111, 0xffff0000, v106
	v_lshlrev_b32_e32 v106, 16, v107
	v_and_b32_e32 v107, 0xffff0000, v107
	v_pk_add_f32 v[104:105], v[104:105], v[106:107]
	v_lshlrev_b32_e32 v106, 16, v108
	v_and_b32_e32 v107, 0xffff0000, v108
	v_pk_add_f32 v[102:103], v[102:103], v[110:111]
	v_pk_add_f32 v[106:107], v[98:99], v[106:107]
	v_lshlrev_b32_e32 v98, 16, v109
	v_and_b32_e32 v99, 0xffff0000, v109
	v_pk_add_f32 v[108:109], v[100:101], v[98:99]
	v_pk_mul_f32 v[98:99], v[102:103], v[102:103]
	v_pk_mul_f32 v[100:101], v[104:105], v[104:105]
	v_add_f32_e32 v98, v98, v116
	v_add_f32_e32 v98, v99, v98
	v_add_f32_e32 v98, v100, v98
	v_pk_mul_f32 v[110:111], v[106:107], v[106:107]
	v_add_f32_e32 v98, v101, v98
	v_add_f32_e32 v98, v110, v98
	v_pk_mul_f32 v[112:113], v[108:109], v[108:109]
	v_add_f32_e32 v98, v111, v98
	v_add_f32_e32 v98, v112, v98
	v_add_f32_e32 v110, v113, v98
	v_cvt_pk_bf16_f32 v98, v102, v103
	v_cvt_pk_bf16_f32 v99, v104, v105
	v_cvt_pk_bf16_f32 v100, v106, v107
	v_cvt_pk_bf16_f32 v101, v108, v109
	global_store_dwordx4 v[114:115], v[98:101], off offset:256
	ds_bpermute_b32 v98, v154, v110
	s_waitcnt lgkmcnt(0)
	v_add_f32_e32 v98, v110, v98
	ds_bpermute_b32 v99, v153, v98
	s_and_saveexec_b64 s[20:21], s[38:39]
	s_cbranch_execz .LBB0_943
	s_waitcnt lgkmcnt(0)
	v_add_f32_e32 v98, v98, v99
	ds_write_b32 v150, v98 offset:256
; __device__ __forceinline__ unsigned cvtpk(float lo, float hi) { f32x2 v = {lo, hi}; bf16x2_t b = __builtin_convertvector(v, bf16x2_t); return __builtin_bit_cast(unsigned, b); }
;     __device__ __forceinline__ void operator()(AccRef acc, const Unit& u, int wr, int wc, int fr, int fq) const {
;     ...
;                 const int row = row0 + ai * 128 + m * 16; bf16_t* rowp = XB + (size_t)row * DM + col0; float s = 0.f;
; #pragma unroll
;                 for (int bj = 0; bj < 2; ++bj) {
;                     const u32x4 xo = *(const u32x4*)(rowp + bj * 128);
;                     float v[8];
; #pragma unroll
;                     for (int k = 0; k < 4; ++k) { v[2 * k] = __uint_as_float(xo[k] << 16) + acc[ai][bj][m][k >> 1][(2 * k) & 3]; v[2 * k + 1] = __uint_as_float(xo[k] & 0xffff0000u) + acc[ai][bj][m][k >> 1][(2 * k + 1) & 3]; }
; #pragma unroll
;                     for (int k = 0; k < 8; ++k) s += v[k] * v[k];
;                     u32x4 w; w.x = cvtpk(v[0], v[1]); w.y = cvtpk(v[2], v[3]); w.z = cvtpk(v[4], v[5]); w.w = cvtpk(v[6], v[7]);
;                     st16_wt(rowp + bj * 128, w);
;                 }
;                 s += __shfl_xor(s, 16); s += __shfl_xor(s, 32);
;                 if (fq == 0) red[(ai * 128 + wr * 64 + m * 16 + fr) * 4 + wc] = s;
;                 asm volatile("" ::: "memory");
.LBB0_943:
	s_or_b64 exec, exec, s[20:21]
	v_or_b32_e32 v98, 32, v142
	s_waitcnt lgkmcnt(0)
	v_ashrrev_i32_e32 v99, 31, v98
	v_lshlrev_b64 v[98:99], 11, v[98:99]
	v_lshl_add_u64 v[98:99], s[66:67], 0, v[98:99]
	v_lshl_add_u64 v[98:99], v[140:141], 1, v[98:99]
	global_load_dwordx4 v[100:103], v[98:99], off
	s_waitcnt vmcnt(0)
	v_lshlrev_b32_e32 v104, 16, v100
	v_and_b32_e32 v105, 0xffff0000, v100
	v_lshlrev_b32_e32 v100, 16, v101
	v_and_b32_e32 v101, 0xffff0000, v101
	v_pk_add_f32 v[96:97], v[96:97], v[100:101]
	v_lshlrev_b32_e32 v100, 16, v102
	v_and_b32_e32 v101, 0xffff0000, v102
	v_pk_add_f32 v[100:101], v[90:91], v[100:101]
	v_lshlrev_b32_e32 v90, 16, v103
	v_and_b32_e32 v91, 0xffff0000, v103
	v_pk_add_f32 v[94:95], v[94:95], v[104:105]
	v_pk_add_f32 v[102:103], v[92:93], v[90:91]
	v_cvt_pk_bf16_f32 v90, v94, v95
	v_cvt_pk_bf16_f32 v91, v96, v97
	v_cvt_pk_bf16_f32 v92, v100, v101
	v_cvt_pk_bf16_f32 v93, v102, v103
	global_store_dwordx4 v[98:99], v[90:93], off
	global_load_dwordx4 v[90:93], v[98:99], off offset:256
	v_pk_mul_f32 v[104:105], v[94:95], v[94:95]
	v_pk_mul_f32 v[106:107], v[96:97], v[96:97]
	v_pk_mul_f32 v[108:109], v[100:101], v[100:101]
	v_add_f32_e32 v100, v104, v105
	v_add_f32_e32 v100, v106, v100
	v_add_f32_e32 v100, v107, v100
	v_add_f32_e32 v100, v108, v100
	v_pk_mul_f32 v[110:111], v[102:103], v[102:103]
	v_add_f32_e32 v100, v109, v100
	v_add_f32_e32 v100, v110, v100
	v_add_f32_e32 v100, v111, v100
	s_waitcnt vmcnt(0)
	v_lshlrev_b32_e32 v94, 16, v90
	v_and_b32_e32 v95, 0xffff0000, v90
	v_lshlrev_b32_e32 v90, 16, v91
	v_and_b32_e32 v91, 0xffff0000, v91
	v_pk_add_f32 v[88:89], v[88:89], v[90:91]
	v_lshlrev_b32_e32 v90, 16, v92
	v_and_b32_e32 v91, 0xffff0000, v92
	v_pk_add_f32 v[86:87], v[86:87], v[94:95]
	v_pk_add_f32 v[90:91], v[82:83], v[90:91]
	v_lshlrev_b32_e32 v82, 16, v93
	v_and_b32_e32 v83, 0xffff0000, v93
	v_pk_add_f32 v[92:93], v[84:85], v[82:83]
	v_pk_mul_f32 v[82:83], v[86:87], v[86:87]
	v_pk_mul_f32 v[84:85], v[88:89], v[88:89]
	v_add_f32_e32 v82, v82, v100
	v_add_f32_e32 v82, v83, v82
	v_add_f32_e32 v82, v84, v82
	v_pk_mul_f32 v[94:95], v[90:91], v[90:91]
	v_add_f32_e32 v82, v85, v82
	v_add_f32_e32 v82, v94, v82
	v_pk_mul_f32 v[96:97], v[92:93], v[92:93]
	v_add_f32_e32 v82, v95, v82
	v_add_f32_e32 v82, v96, v82
	v_add_f32_e32 v94, v97, v82
	v_cvt_pk_bf16_f32 v82, v86, v87
	v_cvt_pk_bf16_f32 v83, v88, v89
	v_cvt_pk_bf16_f32 v84, v90, v91
	v_cvt_pk_bf16_f32 v85, v92, v93
	global_store_dwordx4 v[98:99], v[82:85], off offset:256
	ds_bpermute_b32 v82, v154, v94
	s_waitcnt lgkmcnt(0)
	v_add_f32_e32 v82, v94, v82
	ds_bpermute_b32 v83, v153, v82
	s_and_saveexec_b64 s[20:21], s[38:39]
	s_cbranch_execz .LBB0_945
	s_waitcnt lgkmcnt(0)
	v_add_f32_e32 v82, v82, v83
	ds_write_b32 v150, v82 offset:512
.LBB0_945:
	s_or_b64 exec, exec, s[20:21]
	v_or_b32_e32 v82, 48, v142
	s_waitcnt lgkmcnt(0)
	v_ashrrev_i32_e32 v83, 31, v82
	v_lshlrev_b64 v[82:83], 11, v[82:83]
	v_lshl_add_u64 v[82:83], s[66:67], 0, v[82:83]
	v_lshl_add_u64 v[82:83], v[140:141], 1, v[82:83]
	global_load_dwordx4 v[84:87], v[82:83], off
	s_waitcnt vmcnt(0)
	v_lshlrev_b32_e32 v88, 16, v84
	v_and_b32_e32 v89, 0xffff0000, v84
	v_lshlrev_b32_e32 v84, 16, v85
	v_and_b32_e32 v85, 0xffff0000, v85
	v_pk_add_f32 v[80:81], v[80:81], v[84:85]
	v_lshlrev_b32_e32 v84, 16, v86
	v_and_b32_e32 v85, 0xffff0000, v86
	v_pk_add_f32 v[84:85], v[74:75], v[84:85]
	v_lshlrev_b32_e32 v74, 16, v87
	v_and_b32_e32 v75, 0xffff0000, v87
	v_pk_add_f32 v[78:79], v[78:79], v[88:89]
	v_pk_add_f32 v[86:87], v[76:77], v[74:75]
	v_cvt_pk_bf16_f32 v74, v78, v79
	v_cvt_pk_bf16_f32 v75, v80, v81
	v_cvt_pk_bf16_f32 v76, v84, v85
	v_cvt_pk_bf16_f32 v77, v86, v87
	global_store_dwordx4 v[82:83], v[74:77], off
	global_load_dwordx4 v[74:77], v[82:83], off offset:256
	v_pk_mul_f32 v[88:89], v[78:79], v[78:79]
	v_pk_mul_f32 v[90:91], v[80:81], v[80:81]
	v_pk_mul_f32 v[92:93], v[84:85], v[84:85]
	v_add_f32_e32 v84, v88, v89
	v_add_f32_e32 v84, v90, v84
	v_add_f32_e32 v84, v91, v84
	v_add_f32_e32 v84, v92, v84
	v_pk_mul_f32 v[94:95], v[86:87], v[86:87]
	v_add_f32_e32 v84, v93, v84
	v_add_f32_e32 v84, v94, v84
	v_add_f32_e32 v84, v95, v84
	s_waitcnt vmcnt(0)
	v_lshlrev_b32_e32 v78, 16, v74
	v_and_b32_e32 v79, 0xffff0000, v74
	v_lshlrev_b32_e32 v74, 16, v75
	v_and_b32_e32 v75, 0xffff0000, v75
	v_pk_add_f32 v[72:73], v[72:73], v[74:75]
	v_lshlrev_b32_e32 v74, 16, v76
	v_and_b32_e32 v75, 0xffff0000, v76
	v_pk_add_f32 v[70:71], v[70:71], v[78:79]
	v_pk_add_f32 v[74:75], v[66:67], v[74:75]
	v_lshlrev_b32_e32 v66, 16, v77
	v_and_b32_e32 v67, 0xffff0000, v77
	v_pk_add_f32 v[76:77], v[68:69], v[66:67]
	v_pk_mul_f32 v[66:67], v[70:71], v[70:71]
	v_pk_mul_f32 v[68:69], v[72:73], v[72:73]
	v_add_f32_e32 v66, v66, v84
	v_add_f32_e32 v66, v67, v66
	v_add_f32_e32 v66, v68, v66
	v_pk_mul_f32 v[78:79], v[74:75], v[74:75]
	v_add_f32_e32 v66, v69, v66
	v_add_f32_e32 v66, v78, v66
	v_pk_mul_f32 v[80:81], v[76:77], v[76:77]
	v_add_f32_e32 v66, v79, v66
	v_add_f32_e32 v66, v80, v66
	v_add_f32_e32 v78, v81, v66
	v_cvt_pk_bf16_f32 v66, v70, v71
	v_cvt_pk_bf16_f32 v67, v72, v73
	v_cvt_pk_bf16_f32 v68, v74, v75
	v_cvt_pk_bf16_f32 v69, v76, v77
	global_store_dwordx4 v[82:83], v[66:69], off offset:256
	ds_bpermute_b32 v66, v154, v78
	s_waitcnt lgkmcnt(0)
	v_add_f32_e32 v66, v78, v66
	ds_bpermute_b32 v67, v153, v66
	s_and_saveexec_b64 s[20:21], s[38:39]
	s_cbranch_execz .LBB0_947
	s_waitcnt lgkmcnt(0)
	v_add_f32_e32 v66, v66, v67
	ds_write_b32 v150, v66 offset:768
; __device__ __forceinline__ unsigned cvtpk(float lo, float hi) { f32x2 v = {lo, hi}; bf16x2_t b = __builtin_convertvector(v, bf16x2_t); return __builtin_bit_cast(unsigned, b); }
;     __device__ __forceinline__ void operator()(AccRef acc, const Unit& u, int wr, int wc, int fr, int fq) const {
;     ...
;                 const int row = row0 + ai * 128 + m * 16; bf16_t* rowp = XB + (size_t)row * DM + col0; float s = 0.f;
; #pragma unroll
;                 for (int bj = 0; bj < 2; ++bj) {
;                     const u32x4 xo = *(const u32x4*)(rowp + bj * 128);
;                     float v[8];
; #pragma unroll
;                     for (int k = 0; k < 4; ++k) { v[2 * k] = __uint_as_float(xo[k] << 16) + acc[ai][bj][m][k >> 1][(2 * k) & 3]; v[2 * k + 1] = __uint_as_float(xo[k] & 0xffff0000u) + acc[ai][bj][m][k >> 1][(2 * k + 1) & 3]; }
; #pragma unroll
;                     for (int k = 0; k < 8; ++k) s += v[k] * v[k];
;                     u32x4 w; w.x = cvtpk(v[0], v[1]); w.y = cvtpk(v[2], v[3]); w.z = cvtpk(v[4], v[5]); w.w = cvtpk(v[6], v[7]);
;                     st16_wt(rowp + bj * 128, w);
;                 }
;                 s += __shfl_xor(s, 16); s += __shfl_xor(s, 32);
;                 if (fq == 0) red[(ai * 128 + wr * 64 + m * 16 + fr) * 4 + wc] = s;
;                 asm volatile("" ::: "memory");
.LBB0_947:
	s_or_b64 exec, exec, s[20:21]
	s_waitcnt lgkmcnt(0)
	v_lshlrev_b64 v[66:67], 11, v[142:143]
	v_lshl_add_u64 v[66:67], s[66:67], 0, v[66:67]
	v_lshl_add_u64 v[66:67], v[140:141], 1, v[66:67]
	v_add_co_u32_e32 v74, vcc, 0x40000, v66
	s_mov_b64 s[20:21], 0x40000
	s_nop 0
	v_addc_co_u32_e32 v75, vcc, 0, v67, vcc
	global_load_dwordx4 v[70:73], v[74:75], off
	v_lshl_add_u64 v[68:69], v[66:67], 0, s[20:21]
	s_waitcnt vmcnt(0)
	v_lshlrev_b32_e32 v76, 16, v70
	v_and_b32_e32 v77, 0xffff0000, v70
	v_pk_add_f32 v[76:77], v[62:63], v[76:77]
	v_lshlrev_b32_e32 v62, 16, v71
	v_and_b32_e32 v63, 0xffff0000, v71
	v_pk_add_f32 v[78:79], v[64:65], v[62:63]
	v_lshlrev_b32_e32 v62, 16, v72
	v_and_b32_e32 v63, 0xffff0000, v72
	v_pk_add_f32 v[80:81], v[58:59], v[62:63]
	v_lshlrev_b32_e32 v58, 16, v73
	v_and_b32_e32 v59, 0xffff0000, v73
	v_pk_add_f32 v[82:83], v[60:61], v[58:59]
	v_cvt_pk_bf16_f32 v70, v76, v77
	v_cvt_pk_bf16_f32 v71, v78, v79
	v_cvt_pk_bf16_f32 v72, v80, v81
	v_cvt_pk_bf16_f32 v73, v82, v83
	global_store_dwordx4 v[74:75], v[70:73], off
	global_load_dwordx4 v[70:73], v[68:69], off offset:256
	v_pk_mul_f32 v[64:65], v[76:77], v[76:77]
	v_pk_mul_f32 v[62:63], v[78:79], v[78:79]
	v_add_f32_e32 v64, v64, v65
	v_add_f32_e32 v62, v62, v64
	v_pk_mul_f32 v[60:61], v[80:81], v[80:81]
	v_add_f32_e32 v62, v63, v62
	v_add_f32_e32 v60, v60, v62
	v_pk_mul_f32 v[58:59], v[82:83], v[82:83]
	v_add_f32_e32 v60, v61, v60
	v_add_f32_e32 v58, v58, v60
	v_add_f32_e32 v58, v59, v58
	s_waitcnt vmcnt(0)
	v_lshlrev_b32_e32 v74, 16, v70
	v_and_b32_e32 v75, 0xffff0000, v70
	v_lshlrev_b32_e32 v70, 16, v71
	v_and_b32_e32 v71, 0xffff0000, v71
	v_pk_add_f32 v[56:57], v[56:57], v[70:71]
	v_lshlrev_b32_e32 v70, 16, v72
	v_and_b32_e32 v71, 0xffff0000, v72
	v_pk_add_f32 v[54:55], v[54:55], v[74:75]
	v_pk_add_f32 v[70:71], v[50:51], v[70:71]
	v_lshlrev_b32_e32 v50, 16, v73
	v_and_b32_e32 v51, 0xffff0000, v73
	v_pk_add_f32 v[72:73], v[52:53], v[50:51]
	v_pk_mul_f32 v[50:51], v[54:55], v[54:55]
	v_pk_mul_f32 v[52:53], v[56:57], v[56:57]
	v_add_f32_e32 v50, v50, v58
	v_add_f32_e32 v50, v51, v50
	v_add_f32_e32 v50, v52, v50
	v_pk_mul_f32 v[74:75], v[70:71], v[70:71]
	v_add_f32_e32 v50, v53, v50
	v_add_f32_e32 v50, v74, v50
	v_pk_mul_f32 v[76:77], v[72:73], v[72:73]
	v_add_f32_e32 v50, v75, v50
	v_add_f32_e32 v50, v76, v50
	v_add_f32_e32 v58, v77, v50
	v_cvt_pk_bf16_f32 v50, v54, v55
	v_cvt_pk_bf16_f32 v51, v56, v57
	v_cvt_pk_bf16_f32 v52, v70, v71
	v_cvt_pk_bf16_f32 v53, v72, v73
	global_store_dwordx4 v[68:69], v[50:53], off offset:256
	ds_bpermute_b32 v50, v154, v58
	s_waitcnt lgkmcnt(0)
	v_add_f32_e32 v50, v58, v50
	ds_bpermute_b32 v51, v153, v50
	s_and_saveexec_b64 s[20:21], s[38:39]
	s_cbranch_execz .LBB0_949
	s_waitcnt lgkmcnt(0)
	v_add_f32_e32 v50, v50, v51
	ds_write_b32 v150, v50 offset:2048
.LBB0_949:
	s_or_b64 exec, exec, s[20:21]
	v_add_co_u32_e32 v56, vcc, 0x48000, v66
	s_mov_b64 s[20:21], 0x48000
	s_nop 0
	v_addc_co_u32_e32 v57, vcc, 0, v67, vcc
	global_load_dwordx4 v[52:55], v[56:57], off
	s_waitcnt lgkmcnt(0)
	v_lshl_add_u64 v[50:51], v[66:67], 0, s[20:21]
	s_waitcnt vmcnt(0)
	v_lshlrev_b32_e32 v58, 16, v52
	v_and_b32_e32 v59, 0xffff0000, v52
	v_pk_add_f32 v[58:59], v[46:47], v[58:59]
	v_lshlrev_b32_e32 v46, 16, v53
	v_and_b32_e32 v47, 0xffff0000, v53
	v_pk_add_f32 v[60:61], v[48:49], v[46:47]
	v_lshlrev_b32_e32 v46, 16, v54
	v_and_b32_e32 v47, 0xffff0000, v54
	v_pk_add_f32 v[62:63], v[42:43], v[46:47]
	v_lshlrev_b32_e32 v42, 16, v55
	v_and_b32_e32 v43, 0xffff0000, v55
	v_pk_add_f32 v[64:65], v[44:45], v[42:43]
	v_cvt_pk_bf16_f32 v52, v58, v59
	v_cvt_pk_bf16_f32 v53, v60, v61
	v_cvt_pk_bf16_f32 v54, v62, v63
	v_cvt_pk_bf16_f32 v55, v64, v65
	global_store_dwordx4 v[56:57], v[52:55], off
	global_load_dwordx4 v[52:55], v[50:51], off offset:256
	v_pk_mul_f32 v[48:49], v[58:59], v[58:59]
	v_pk_mul_f32 v[46:47], v[60:61], v[60:61]
	v_add_f32_e32 v48, v48, v49
	v_add_f32_e32 v46, v46, v48
	v_pk_mul_f32 v[44:45], v[62:63], v[62:63]
	v_add_f32_e32 v46, v47, v46
	v_add_f32_e32 v44, v44, v46
	v_pk_mul_f32 v[42:43], v[64:65], v[64:65]
	v_add_f32_e32 v44, v45, v44
	v_add_f32_e32 v42, v42, v44
	v_add_f32_e32 v42, v43, v42
	s_waitcnt vmcnt(0)
	v_lshlrev_b32_e32 v56, 16, v52
	v_and_b32_e32 v57, 0xffff0000, v52
	v_lshlrev_b32_e32 v52, 16, v53
	v_and_b32_e32 v53, 0xffff0000, v53
	v_pk_add_f32 v[40:41], v[40:41], v[52:53]
	v_lshlrev_b32_e32 v52, 16, v54
	v_and_b32_e32 v53, 0xffff0000, v54
	v_pk_add_f32 v[38:39], v[38:39], v[56:57]
	v_pk_add_f32 v[52:53], v[34:35], v[52:53]
	v_lshlrev_b32_e32 v34, 16, v55
	v_and_b32_e32 v35, 0xffff0000, v55
	v_pk_add_f32 v[54:55], v[36:37], v[34:35]
	v_pk_mul_f32 v[34:35], v[38:39], v[38:39]
	v_pk_mul_f32 v[36:37], v[40:41], v[40:41]
	v_add_f32_e32 v34, v34, v42
	v_add_f32_e32 v34, v35, v34
	v_add_f32_e32 v34, v36, v34
	v_pk_mul_f32 v[56:57], v[52:53], v[52:53]
	v_add_f32_e32 v34, v37, v34
	v_add_f32_e32 v34, v56, v34
	v_pk_mul_f32 v[58:59], v[54:55], v[54:55]
	v_add_f32_e32 v34, v57, v34
	v_add_f32_e32 v34, v58, v34
	v_add_f32_e32 v42, v59, v34
	v_cvt_pk_bf16_f32 v34, v38, v39
	v_cvt_pk_bf16_f32 v35, v40, v41
	v_cvt_pk_bf16_f32 v36, v52, v53
	v_cvt_pk_bf16_f32 v37, v54, v55
	global_store_dwordx4 v[50:51], v[34:37], off offset:256
	ds_bpermute_b32 v34, v154, v42
	s_waitcnt lgkmcnt(0)
	v_add_f32_e32 v34, v42, v34
	ds_bpermute_b32 v35, v153, v34
	s_and_saveexec_b64 s[20:21], s[38:39]
	s_cbranch_execz .LBB0_951
	s_waitcnt lgkmcnt(0)
	v_add_f32_e32 v34, v34, v35
	ds_write_b32 v150, v34 offset:2304
; __device__ __forceinline__ unsigned cvtpk(float lo, float hi) { f32x2 v = {lo, hi}; bf16x2_t b = __builtin_convertvector(v, bf16x2_t); return __builtin_bit_cast(unsigned, b); }
;     __device__ __forceinline__ void operator()(AccRef acc, const Unit& u, int wr, int wc, int fr, int fq) const {
;     ...
;                 const int row = row0 + ai * 128 + m * 16; bf16_t* rowp = XB + (size_t)row * DM + col0; float s = 0.f;
; #pragma unroll
;                 for (int bj = 0; bj < 2; ++bj) {
;                     const u32x4 xo = *(const u32x4*)(rowp + bj * 128);
;                     float v[8];
; #pragma unroll
;                     for (int k = 0; k < 4; ++k) { v[2 * k] = __uint_as_float(xo[k] << 16) + acc[ai][bj][m][k >> 1][(2 * k) & 3]; v[2 * k + 1] = __uint_as_float(xo[k] & 0xffff0000u) + acc[ai][bj][m][k >> 1][(2 * k + 1) & 3]; }
; #pragma unroll
;                     for (int k = 0; k < 8; ++k) s += v[k] * v[k];
;                     u32x4 w; w.x = cvtpk(v[0], v[1]); w.y = cvtpk(v[2], v[3]); w.z = cvtpk(v[4], v[5]); w.w = cvtpk(v[6], v[7]);
;                     st16_wt(rowp + bj * 128, w);
;                 }
;                 s += __shfl_xor(s, 16); s += __shfl_xor(s, 32);
;                 if (fq == 0) red[(ai * 128 + wr * 64 + m * 16 + fr) * 4 + wc] = s;
;                 asm volatile("" ::: "memory");
.LBB0_951:
	s_or_b64 exec, exec, s[20:21]
	s_waitcnt lgkmcnt(0)
	v_lshlrev_b64 v[34:35], 11, v[142:143]
	v_lshl_add_u64 v[34:35], s[66:67], 0, v[34:35]
	v_lshl_add_u64 v[34:35], v[140:141], 1, v[34:35]
	v_add_co_u32_e32 v42, vcc, 0x50000, v34
	s_mov_b64 s[20:21], 0x50000
	s_nop 0
	v_addc_co_u32_e32 v43, vcc, 0, v35, vcc
	global_load_dwordx4 v[38:41], v[42:43], off
	v_lshl_add_u64 v[36:37], v[34:35], 0, s[20:21]
	s_waitcnt vmcnt(0)
	v_lshlrev_b32_e32 v44, 16, v38
	v_and_b32_e32 v45, 0xffff0000, v38
	v_pk_add_f32 v[44:45], v[30:31], v[44:45]
	v_lshlrev_b32_e32 v30, 16, v39
	v_and_b32_e32 v31, 0xffff0000, v39
	v_pk_add_f32 v[46:47], v[32:33], v[30:31]
	v_lshlrev_b32_e32 v30, 16, v40
	v_and_b32_e32 v31, 0xffff0000, v40
	v_pk_add_f32 v[48:49], v[26:27], v[30:31]
	v_lshlrev_b32_e32 v26, 16, v41
	v_and_b32_e32 v27, 0xffff0000, v41
	v_pk_add_f32 v[50:51], v[28:29], v[26:27]
	v_cvt_pk_bf16_f32 v38, v44, v45
	v_cvt_pk_bf16_f32 v39, v46, v47
	v_cvt_pk_bf16_f32 v40, v48, v49
	v_cvt_pk_bf16_f32 v41, v50, v51
	global_store_dwordx4 v[42:43], v[38:41], off
	global_load_dwordx4 v[38:41], v[36:37], off offset:256
	v_pk_mul_f32 v[32:33], v[44:45], v[44:45]
	v_pk_mul_f32 v[30:31], v[46:47], v[46:47]
	v_add_f32_e32 v32, v32, v33
	v_add_f32_e32 v30, v30, v32
	v_pk_mul_f32 v[28:29], v[48:49], v[48:49]
	v_add_f32_e32 v30, v31, v30
	v_add_f32_e32 v28, v28, v30
	v_pk_mul_f32 v[26:27], v[50:51], v[50:51]
	v_add_f32_e32 v28, v29, v28
	v_add_f32_e32 v26, v26, v28
	v_add_f32_e32 v26, v27, v26
	s_waitcnt vmcnt(0)
	v_lshlrev_b32_e32 v42, 16, v38
	v_and_b32_e32 v43, 0xffff0000, v38
	v_lshlrev_b32_e32 v38, 16, v39
	v_and_b32_e32 v39, 0xffff0000, v39
	v_pk_add_f32 v[24:25], v[24:25], v[38:39]
	v_lshlrev_b32_e32 v38, 16, v40
	v_and_b32_e32 v39, 0xffff0000, v40
	v_pk_add_f32 v[22:23], v[22:23], v[42:43]
	v_pk_add_f32 v[38:39], v[18:19], v[38:39]
	v_lshlrev_b32_e32 v18, 16, v41
	v_and_b32_e32 v19, 0xffff0000, v41
	v_pk_add_f32 v[40:41], v[20:21], v[18:19]
	v_pk_mul_f32 v[18:19], v[22:23], v[22:23]
	v_pk_mul_f32 v[20:21], v[24:25], v[24:25]
	v_add_f32_e32 v18, v18, v26
	v_add_f32_e32 v18, v19, v18
	v_add_f32_e32 v18, v20, v18
	v_pk_mul_f32 v[42:43], v[38:39], v[38:39]
	v_add_f32_e32 v18, v21, v18
	v_add_f32_e32 v18, v42, v18
	v_pk_mul_f32 v[44:45], v[40:41], v[40:41]
	v_add_f32_e32 v18, v43, v18
	v_add_f32_e32 v18, v44, v18
	v_add_f32_e32 v26, v45, v18
	v_cvt_pk_bf16_f32 v18, v22, v23
	v_cvt_pk_bf16_f32 v19, v24, v25
	v_cvt_pk_bf16_f32 v20, v38, v39
	v_cvt_pk_bf16_f32 v21, v40, v41
	global_store_dwordx4 v[36:37], v[18:21], off offset:256
	ds_bpermute_b32 v18, v154, v26
	s_waitcnt lgkmcnt(0)
	v_add_f32_e32 v18, v26, v18
	ds_bpermute_b32 v19, v153, v18
	s_and_saveexec_b64 s[20:21], s[38:39]
	s_cbranch_execz .LBB0_953
	s_waitcnt lgkmcnt(0)
	v_add_f32_e32 v18, v18, v19
	ds_write_b32 v150, v18 offset:2560
.LBB0_953:
	s_or_b64 exec, exec, s[20:21]
	v_add_co_u32_e32 v24, vcc, 0x58000, v34
	s_mov_b64 s[20:21], 0x58000
	s_nop 0
	v_addc_co_u32_e32 v25, vcc, 0, v35, vcc
	global_load_dwordx4 v[20:23], v[24:25], off
	s_waitcnt lgkmcnt(0)
	v_lshl_add_u64 v[18:19], v[34:35], 0, s[20:21]
	s_waitcnt vmcnt(0)
	v_lshlrev_b32_e32 v26, 16, v20
	v_and_b32_e32 v27, 0xffff0000, v20
	v_pk_add_f32 v[26:27], v[14:15], v[26:27]
	v_lshlrev_b32_e32 v14, 16, v21
	v_and_b32_e32 v15, 0xffff0000, v21
	v_pk_add_f32 v[28:29], v[16:17], v[14:15]
	v_lshlrev_b32_e32 v14, 16, v22
	v_and_b32_e32 v15, 0xffff0000, v22
	v_pk_add_f32 v[30:31], v[10:11], v[14:15]
	v_lshlrev_b32_e32 v10, 16, v23
	v_and_b32_e32 v11, 0xffff0000, v23
	v_pk_add_f32 v[32:33], v[12:13], v[10:11]
	v_cvt_pk_bf16_f32 v20, v26, v27
	v_cvt_pk_bf16_f32 v21, v28, v29
	v_cvt_pk_bf16_f32 v22, v30, v31
	v_cvt_pk_bf16_f32 v23, v32, v33
	global_store_dwordx4 v[24:25], v[20:23], off
	global_load_dwordx4 v[20:23], v[18:19], off offset:256
	v_pk_mul_f32 v[16:17], v[26:27], v[26:27]
	v_pk_mul_f32 v[14:15], v[28:29], v[28:29]
	v_add_f32_e32 v16, v16, v17
	v_add_f32_e32 v14, v14, v16
	v_pk_mul_f32 v[12:13], v[30:31], v[30:31]
	v_add_f32_e32 v14, v15, v14
	v_add_f32_e32 v12, v12, v14
	v_pk_mul_f32 v[10:11], v[32:33], v[32:33]
	v_add_f32_e32 v12, v13, v12
	v_add_f32_e32 v10, v10, v12
	v_add_f32_e32 v10, v11, v10
	s_waitcnt vmcnt(0)
	v_lshlrev_b32_e32 v24, 16, v20
	v_and_b32_e32 v25, 0xffff0000, v20
	v_lshlrev_b32_e32 v20, 16, v21
	v_and_b32_e32 v21, 0xffff0000, v21
	v_pk_add_f32 v[8:9], v[8:9], v[20:21]
	v_lshlrev_b32_e32 v20, 16, v22
	v_and_b32_e32 v21, 0xffff0000, v22
	v_pk_add_f32 v[6:7], v[6:7], v[24:25]
	v_pk_add_f32 v[20:21], v[2:3], v[20:21]
	v_lshlrev_b32_e32 v2, 16, v23
	v_and_b32_e32 v3, 0xffff0000, v23
	v_pk_add_f32 v[22:23], v[4:5], v[2:3]
	v_pk_mul_f32 v[2:3], v[6:7], v[6:7]
	v_pk_mul_f32 v[4:5], v[8:9], v[8:9]
	v_add_f32_e32 v2, v2, v10
	v_add_f32_e32 v2, v3, v2
	v_add_f32_e32 v2, v4, v2
	v_pk_mul_f32 v[24:25], v[20:21], v[20:21]
	v_add_f32_e32 v2, v5, v2
	v_add_f32_e32 v2, v24, v2
	v_pk_mul_f32 v[26:27], v[22:23], v[22:23]
	v_add_f32_e32 v2, v25, v2
	v_add_f32_e32 v2, v26, v2
	v_add_f32_e32 v10, v27, v2
	v_cvt_pk_bf16_f32 v2, v6, v7
	v_cvt_pk_bf16_f32 v3, v8, v9
	v_cvt_pk_bf16_f32 v4, v20, v21
	v_cvt_pk_bf16_f32 v5, v22, v23
	global_store_dwordx4 v[18:19], v[2:5], off offset:256
	ds_bpermute_b32 v2, v154, v10
	s_waitcnt lgkmcnt(0)
	v_add_f32_e32 v2, v10, v2
	ds_bpermute_b32 v3, v153, v2
	s_and_saveexec_b64 s[20:21], s[38:39]
	s_cbranch_execz .LBB0_955
	s_waitcnt lgkmcnt(0)
	v_add_f32_e32 v2, v2, v3
	ds_write_b32 v150, v2 offset:2816
